# EpiConv: lane-transposed (ds_bpermute) 8-byte stores per n, issued per group as before (16 instead of 64 cache-line pieces per store)
# speedup vs baseline: 1.0021x; 1.0021x over previous
;     __device__ __forceinline__ void operator()(const f32x4 (&acc)[2][2][4][2], const Unit& u, int wr, int wc, int fr, int fq) const {
;     ...
;         const int ch0 = 128 * u.pn + 32 * wc + 8 * fq;
;         f32x4 w0[2], w1[2], w2[2], bb[2];
; #pragma unroll
;         for (int bj = 0; bj < 2; ++bj) { const int col = bj * 2816 + ch0;
;             w0[bj] = *(const f32x4*)(cw + col); w1[bj] = *(const f32x4*)(cw + 5632 + col); w2[bj] = *(const f32x4*)(cw + 11264 + col); bb[bj] = *(const f32x4*)(cb + col); }
; #pragma unroll
;         for (int ai = 0; ai < 2; ++ai) { const int blk = ai * 2 + wr;
;             if (fr == 0) {
; #pragma unroll
;                 for (int bj = 0; bj < 2; ++bj)
; #pragma unroll
;                     for (int n = 0; n < 2; ++n) *(PG8_LAS f32x4*)(xb + ((((blk * 2 + 0) * 4 + wc) * 4 + fq) * 16 + (bj * 2 + n) * 4)) = acc[ai][bj][0][n]; }
;             if (fr == 15) {
; #pragma unroll
;                 for (int bj = 0; bj < 2; ++bj)
; #pragma unroll
;                     for (int n = 0; n < 2; ++n) *(PG8_LAS f32x4*)(xb + ((((blk * 2 + 1) * 4 + wc) * 4 + fq) * 16 + (bj * 2 + n) * 4)) = acc[ai][bj][3][n]; } }
;         asm volatile("s_waitcnt lgkmcnt(0)" ::: "memory"); __builtin_amdgcn_s_barrier(); asm volatile("" ::: "memory");
;     ...
;                 for (int m = 0; m < 4; ++m) { const int r = 128 * ai + 64 * wr + 16 * m + fr, t = tstart + r;
;                     const bool upok = t >= 1, dnok = (t + 1) < T, store_ok = (r >= vlo) && (r < vhi) && (t < T);
;                     f32x4 res[2];
; #pragma unroll
;                     for (int bj = 0; bj < 2; ++bj) { const f32x4 cur = acc[ai][bj][m][n];
;                         f32x4 su = cur, sd = cur;
;                         if (m > 0) { if (fr == 15) su = acc[ai][bj][m > 0 ? m - 1 : 0][n]; }
;                         if (m < 3) { if (fr == 0) sd = acc[ai][bj][m < 3 ? m + 1 : 3][n]; }
;                         f32x4 up, dn;
;                         up[0] = dpp_ror1(su[0]); up[1] = dpp_ror1(su[1]); up[2] = dpp_ror1(su[2]); up[3] = dpp_ror1(su[3]);
;                         dn[0] = dpp_ror15(sd[0]); dn[1] = dpp_ror15(sd[1]); dn[2] = dpp_ror15(sd[2]); dn[3] = dpp_ror15(sd[3]);
;                         if (m == 0) { f32x4 halo = zero4; if (blk > 0) halo = *(const PG8_LAS f32x4*)(xb + (((((blk - 1) * 2 + 1) * 4 + wc) * 4 + fq) * 16 + (bj * 2 + n) * 4)); if (fr == 0) up = halo; }
.LBB0_705:
	v_lshl_or_b32 v248, s2, 7, v229
	v_lshlrev_b32_e32 v247, 1, v248
	v_lshlrev_b32_e32 v248, 2, v248
	v_add_u32_e32 v249, 0x2c00, v248
	global_load_dwordx4 v[106:109], v248, s[62:63]
	global_load_dwordx4 v[110:113], v248, s[66:67]
	global_load_dwordx4 v[114:117], v248, s[68:69]
	global_load_dwordx4 v[118:121], v248, s[64:65]
	global_load_dwordx4 v[122:125], v249, s[62:63]
	global_load_dwordx4 v[126:129], v249, s[66:67]
	global_load_dwordx4 v[130:133], v249, s[68:69]
	global_load_dwordx4 v[134:137], v249, s[64:65]
	v_readlane_b32 s10, v254, 4
	v_readlane_b32 s11, v254, 5
	s_add_i32 s0, s78, s48
	s_mulk_i32 s0, 0x1600
	s_movk_i32 s29, 0x1600
	s_add_i32 s28, s93, -1
	v_add_u32_e32 v247, s0, v247
	v_mov_b32_e32 v202, 0
	v_mov_b32_e32 v203, 0
	v_and_b32_e32 v250, 7, v226
	v_lshlrev_b32_e32 v250, 3, v250
	v_add_u32_e32 v250, 0x27000, v250
	ds_write_b64 v250, v[202:203]
	s_mov_b64 exec, s[6:7]
	ds_write_b128 v238, v[166:169]
	ds_write_b128 v238, v[70:73] offset:16
	ds_write_b128 v238, v[162:165] offset:32
	ds_write_b128 v238, v[66:69] offset:48
	ds_write_b128 v239, v[102:105]
	ds_write_b128 v239, v[30:33] offset:16
	ds_write_b128 v239, v[98:101] offset:32
	ds_write_b128 v239, v[26:29] offset:48
	s_mov_b64 exec, s[4:5]
	ds_write_b128 v238, v[142:145] offset:1024
	ds_write_b128 v238, v[46:49] offset:1040
	ds_write_b128 v238, v[138:141] offset:1056
	ds_write_b128 v238, v[42:45] offset:1072
	ds_write_b128 v239, v[78:81] offset:1024
	ds_write_b128 v239, v[6:9] offset:1040
	ds_write_b128 v239, v[74:77] offset:1056
	ds_write_b128 v239, v[2:5] offset:1072
	s_mov_b64 exec, -1
	v_and_b32_e32 v250, 0xb80, v238
	v_lshlrev_b32_e32 v250, 3, v250
	v_bfe_u32 v251, v238, 6, 1
	v_lshl_add_u32 v250, v251, 3, v250
	v_lshl_add_u32 v250, v226, 4, v250
	v_add_u32_e32 v243, 0x20000, v250
	v_add_u32_e32 v244, 0xfffffff0, v243
	v_add_u32_e32 v250, 0xfffffc00, v238
	v_mov_b32_e32 v251, 0x27000
	v_cndmask_b32_e64 v245, v251, v250, s[74:75]
	v_add_u32_e32 v250, 0x800, v239
	v_cndmask_b32_e64 v246, v250, v251, s[74:75]
	s_waitcnt lgkmcnt(0)
	s_barrier
	s_cmp_lt_i32 s48, 1
	s_cbranch_scc1 .Lec_edge
	s_add_i32 s0, s48, 0x100
	s_cmp_ge_i32 s0, s93
	s_cbranch_scc1 .Lec_edge
	v_mbcnt_lo_u32_b32 v251, -1, 0
	v_mbcnt_hi_u32_b32 v251, -1, v251
	v_and_b32_e32 v220, 3, v251
	v_lshrrev_b32_e32 v251, 2, v251
	v_lshl_add_u32 v250, v220, 4, v251
	v_lshlrev_b32_e32 v250, 2, v250
	v_sub_u32_e32 v221, v227, v226
	v_add_u32_e32 v251, v221, v251
	v_and_b32_e32 v221, 0x60, v229
	v_lshl_add_u32 v221, v220, 3, v221
	v_lshl_or_b32 v221, s2, 7, v221
	v_lshlrev_b32_e32 v221, 1, v221
	s_add_i32 s0, s78, s48
	s_mulk_i32 s0, 0x1600
	v_add_u32_e32 v221, s0, v221
	v_mad_u32_u24 v247, v251, s29, v221
	v_add_u32_e32 v220, 0, v251
	v_cmp_le_i32_e64 s[12:13], s54, v220
	v_cmp_gt_i32_e32 vcc, s55, v220
	s_and_b64 s[12:13], s[12:13], vcc
	v_add_u32_e32 v220, 16, v251
	v_cmp_le_i32_e64 s[14:15], s54, v220
	v_cmp_gt_i32_e32 vcc, s55, v220
	s_and_b64 s[14:15], s[14:15], vcc
	v_add_u32_e32 v220, 32, v251
	v_cmp_le_i32_e64 s[16:17], s54, v220
	v_cmp_gt_i32_e32 vcc, s55, v220
	s_and_b64 s[16:17], s[16:17], vcc
	v_add_u32_e32 v220, 48, v251
	v_cmp_le_i32_e64 s[18:19], s54, v220
	v_cmp_gt_i32_e32 vcc, s55, v220
	s_and_b64 s[18:19], s[18:19], vcc
	v_add_u32_e32 v220, 128, v251
	v_cmp_le_i32_e64 s[20:21], s54, v220
	v_cmp_gt_i32_e32 vcc, s55, v220
	s_and_b64 s[20:21], s[20:21], vcc
	v_add_u32_e32 v220, 144, v251
	v_cmp_le_i32_e64 s[22:23], s54, v220
	v_cmp_gt_i32_e32 vcc, s55, v220
	s_and_b64 s[22:23], s[22:23], vcc
	v_add_u32_e32 v220, 160, v251
	v_cmp_le_i32_e64 s[24:25], s54, v220
	v_cmp_gt_i32_e32 vcc, s55, v220
	s_and_b64 s[24:25], s[24:25], vcc
	v_add_u32_e32 v220, 176, v251
	v_cmp_le_i32_e64 s[26:27], s54, v220
	v_cmp_gt_i32_e32 vcc, s55, v220
	s_and_b64 s[26:27], s[26:27], vcc
	ds_write_b64 v243, v[166:167]
	ds_write_b64 v243, v[158:159] offset:256
	ds_write_b64 v243, v[150:151] offset:512
	ds_write_b64 v243, v[142:143] offset:768
	ds_read_b64 v[170:171], v244
	ds_read_b64 v[178:179], v243 offset:16
	ds_read_b64 v[198:199], v245
	ds_read_b64 v[172:173], v244 offset:256
	ds_read_b64 v[180:181], v243 offset:272
	ds_read_b64 v[174:175], v244 offset:512
	ds_read_b64 v[194:195], v243 offset:528
	ds_read_b64 v[176:177], v244 offset:768
	ds_read_b64 v[196:197], v243 offset:784
	ds_read_b64 v[200:201], v238 offset:2048
	s_waitcnt vmcnt(0)
	ds_write_b64 v243, v[168:169]
	ds_write_b64 v243, v[160:161] offset:256
	ds_write_b64 v243, v[152:153] offset:512
	ds_write_b64 v243, v[144:145] offset:768
	s_waitcnt lgkmcnt(11)
	v_cndmask_b32_e64 v170, v170, v198, s[6:7]
	v_cndmask_b32_e64 v171, v171, v199, s[6:7]
	v_pk_fma_f32 v[202:203], v[106:107], v[170:171], v[118:119]
	v_pk_fma_f32 v[166:167], v[166:167], v[110:111], v[202:203]
	v_pk_fma_f32 v[166:167], v[114:115], v[178:179], v[166:167]
	ds_read_b64 v[170:171], v244
	ds_read_b64 v[178:179], v243 offset:16
	ds_read_b64 v[198:199], v245 offset:8
	s_waitcnt lgkmcnt(12)
	v_pk_fma_f32 v[202:203], v[106:107], v[172:173], v[118:119]
	v_pk_fma_f32 v[158:159], v[158:159], v[110:111], v[202:203]
	v_pk_fma_f32 v[158:159], v[114:115], v[180:181], v[158:159]
	ds_read_b64 v[172:173], v244 offset:256
	ds_read_b64 v[180:181], v243 offset:272
	s_waitcnt lgkmcnt(12)
	v_pk_fma_f32 v[202:203], v[106:107], v[174:175], v[118:119]
	v_pk_fma_f32 v[150:151], v[150:151], v[110:111], v[202:203]
	v_pk_fma_f32 v[150:151], v[114:115], v[194:195], v[150:151]
	ds_read_b64 v[174:175], v244 offset:512
	ds_read_b64 v[194:195], v243 offset:528
	s_waitcnt lgkmcnt(11)
; #define PG8_LAS __attribute__((address_space(3)))
; __device__ __forceinline__ float dpp_ror1(float v) { return __builtin_bit_cast(float, __builtin_amdgcn_update_dpp(0, __builtin_bit_cast(int, v), 0x121, 0xf, 0xf, false)); }
; __device__ __forceinline__ float dpp_ror15(float v) { return __builtin_bit_cast(float, __builtin_amdgcn_update_dpp(0, __builtin_bit_cast(int, v), 0x12F, 0xf, 0xf, false)); }
;     __device__ __forceinline__ void operator()(const f32x4 (&acc)[2][2][4][2], const Unit& u, int wr, int wc, int fr, int fq) const {
;     ...
;             for (int ai = 0; ai < 2; ++ai) { const int blk = ai * 2 + wr;
; #pragma unroll
;                 for (int m = 0; m < 4; ++m) { const int r = 128 * ai + 64 * wr + 16 * m + fr, t = tstart + r;
;                     const bool upok = t >= 1, dnok = (t + 1) < T, store_ok = (r >= vlo) && (r < vhi) && (t < T);
;                     f32x4 res[2];
; #pragma unroll
;                     for (int bj = 0; bj < 2; ++bj) { const f32x4 cur = acc[ai][bj][m][n];
;                         f32x4 su = cur, sd = cur;
;                         if (m > 0) { if (fr == 15) su = acc[ai][bj][m > 0 ? m - 1 : 0][n]; }
;                         if (m < 3) { if (fr == 0) sd = acc[ai][bj][m < 3 ? m + 1 : 3][n]; }
;                         f32x4 up, dn;
;                         up[0] = dpp_ror1(su[0]); up[1] = dpp_ror1(su[1]); up[2] = dpp_ror1(su[2]); up[3] = dpp_ror1(su[3]);
;                         dn[0] = dpp_ror15(sd[0]); dn[1] = dpp_ror15(sd[1]); dn[2] = dpp_ror15(sd[2]); dn[3] = dpp_ror15(sd[3]);
;                         if (m == 0) { f32x4 halo = zero4; if (blk > 0) halo = *(const PG8_LAS f32x4*)(xb + (((((blk - 1) * 2 + 1) * 4 + wc) * 4 + fq) * 16 + (bj * 2 + n) * 4)); if (fr == 0) up = halo; }
;                         if (m == 3) { f32x4 halo = zero4; if (blk < 3) halo = *(const PG8_LAS f32x4*)(xb + (((((blk + 1) * 2 + 0) * 4 + wc) * 4 + fq) * 16 + (bj * 2 + n) * 4)); if (fr == 15) dn = halo; }
;                         if (edge) { if (!upok) up = zero4; if (!dnok) dn = zero4; }
;                         res[bj] = bb[bj] + w0[bj] * up + w1[bj] * cur + w2[bj] * dn; }
	v_cndmask_b32_e64 v196, v196, v200, s[4:5]
	v_cndmask_b32_e64 v197, v197, v201, s[4:5]
	v_pk_fma_f32 v[202:203], v[106:107], v[176:177], v[118:119]
	v_pk_fma_f32 v[142:143], v[142:143], v[110:111], v[202:203]
	v_pk_fma_f32 v[142:143], v[114:115], v[196:197], v[142:143]
	ds_read_b64 v[176:177], v244 offset:768
	ds_read_b64 v[196:197], v243 offset:784
	ds_read_b64 v[200:201], v238 offset:2056
	ds_write_b64 v243, v[162:163]
	ds_write_b64 v243, v[154:155] offset:256
	ds_write_b64 v243, v[146:147] offset:512
	ds_write_b64 v243, v[138:139] offset:768
	s_waitcnt lgkmcnt(11)
	v_cndmask_b32_e64 v170, v170, v198, s[6:7]
	v_cndmask_b32_e64 v171, v171, v199, s[6:7]
	v_pk_fma_f32 v[202:203], v[108:109], v[170:171], v[120:121]
	v_pk_fma_f32 v[168:169], v[168:169], v[112:113], v[202:203]
	v_pk_fma_f32 v[168:169], v[116:117], v[178:179], v[168:169]
	ds_read_b64 v[170:171], v244
	ds_read_b64 v[178:179], v243 offset:16
	ds_read_b64 v[198:199], v245 offset:32
	s_waitcnt lgkmcnt(12)
	v_pk_fma_f32 v[202:203], v[108:109], v[172:173], v[120:121]
	v_pk_fma_f32 v[160:161], v[160:161], v[112:113], v[202:203]
	v_pk_fma_f32 v[160:161], v[116:117], v[180:181], v[160:161]
	ds_read_b64 v[172:173], v244 offset:256
	ds_read_b64 v[180:181], v243 offset:272
	s_waitcnt lgkmcnt(12)
	v_pk_fma_f32 v[202:203], v[108:109], v[174:175], v[120:121]
	v_pk_fma_f32 v[152:153], v[152:153], v[112:113], v[202:203]
	v_pk_fma_f32 v[152:153], v[116:117], v[194:195], v[152:153]
	ds_read_b64 v[174:175], v244 offset:512
	ds_read_b64 v[194:195], v243 offset:528
	s_waitcnt lgkmcnt(11)
	v_cndmask_b32_e64 v196, v196, v200, s[4:5]
	v_cndmask_b32_e64 v197, v197, v201, s[4:5]
	v_pk_fma_f32 v[202:203], v[108:109], v[176:177], v[120:121]
	v_pk_fma_f32 v[144:145], v[144:145], v[112:113], v[202:203]
	v_pk_fma_f32 v[144:145], v[116:117], v[196:197], v[144:145]
	ds_read_b64 v[176:177], v244 offset:768
	ds_read_b64 v[196:197], v243 offset:784
	ds_read_b64 v[200:201], v238 offset:2080
	ds_write_b64 v243, v[164:165]
	ds_write_b64 v243, v[156:157] offset:256
	ds_write_b64 v243, v[148:149] offset:512
	ds_write_b64 v243, v[140:141] offset:768
	s_waitcnt lgkmcnt(11)
	v_cndmask_b32_e64 v170, v170, v198, s[6:7]
	v_cndmask_b32_e64 v171, v171, v199, s[6:7]
	v_pk_fma_f32 v[202:203], v[122:123], v[170:171], v[134:135]
	v_pk_fma_f32 v[162:163], v[162:163], v[126:127], v[202:203]
	v_pk_fma_f32 v[162:163], v[130:131], v[178:179], v[162:163]
	ds_read_b64 v[170:171], v244
	ds_read_b64 v[178:179], v243 offset:16
	ds_read_b64 v[198:199], v245 offset:40
	s_waitcnt lgkmcnt(12)
	v_pk_fma_f32 v[202:203], v[122:123], v[172:173], v[134:135]
	v_pk_fma_f32 v[154:155], v[154:155], v[126:127], v[202:203]
	v_pk_fma_f32 v[154:155], v[130:131], v[180:181], v[154:155]
	ds_read_b64 v[172:173], v244 offset:256
	ds_read_b64 v[180:181], v243 offset:272
	s_waitcnt lgkmcnt(12)
	v_pk_fma_f32 v[202:203], v[122:123], v[174:175], v[134:135]
	v_pk_fma_f32 v[146:147], v[146:147], v[126:127], v[202:203]
	v_pk_fma_f32 v[146:147], v[130:131], v[194:195], v[146:147]
	ds_read_b64 v[174:175], v244 offset:512
	ds_read_b64 v[194:195], v243 offset:528
	s_waitcnt lgkmcnt(11)
	v_cndmask_b32_e64 v196, v196, v200, s[4:5]
	v_cndmask_b32_e64 v197, v197, v201, s[4:5]
	v_pk_fma_f32 v[202:203], v[122:123], v[176:177], v[134:135]
	v_pk_fma_f32 v[138:139], v[138:139], v[126:127], v[202:203]
	v_pk_fma_f32 v[138:139], v[130:131], v[196:197], v[138:139]
	ds_read_b64 v[176:177], v244 offset:768
	ds_read_b64 v[196:197], v243 offset:784
	ds_read_b64 v[200:201], v238 offset:2088
	ds_write_b64 v243, v[102:103]
	ds_write_b64 v243, v[94:95] offset:256
	ds_write_b64 v243, v[86:87] offset:512
	ds_write_b64 v243, v[78:79] offset:768
	s_waitcnt lgkmcnt(11)
	v_cndmask_b32_e64 v170, v170, v198, s[6:7]
	v_cndmask_b32_e64 v171, v171, v199, s[6:7]
	v_pk_fma_f32 v[202:203], v[124:125], v[170:171], v[136:137]
	v_pk_fma_f32 v[164:165], v[164:165], v[128:129], v[202:203]
	v_pk_fma_f32 v[164:165], v[132:133], v[178:179], v[164:165]
	ds_read_b64 v[170:171], v244
	ds_read_b64 v[178:179], v243 offset:16
	ds_read_b64 v[198:199], v238 offset:3072
	s_waitcnt lgkmcnt(12)
	v_pk_fma_f32 v[202:203], v[124:125], v[172:173], v[136:137]
	v_pk_fma_f32 v[156:157], v[156:157], v[128:129], v[202:203]
	v_pk_fma_f32 v[156:157], v[132:133], v[180:181], v[156:157]
	ds_read_b64 v[172:173], v244 offset:256
	ds_read_b64 v[180:181], v243 offset:272
	s_waitcnt lgkmcnt(12)
	v_pk_fma_f32 v[202:203], v[124:125], v[174:175], v[136:137]
	v_pk_fma_f32 v[148:149], v[148:149], v[128:129], v[202:203]
	v_pk_fma_f32 v[148:149], v[132:133], v[194:195], v[148:149]
	ds_read_b64 v[174:175], v244 offset:512
	ds_read_b64 v[194:195], v243 offset:528
	s_waitcnt lgkmcnt(11)
; #define PG8_LAS __attribute__((address_space(3)))
; __device__ __forceinline__ unsigned cvt_pk_bf16(float lo, float hi) { unsigned r; asm volatile("v_cvt_pk_bf16_f32 %0, %1, %2" : "=v"(r) : "v"(lo), "v"(hi)); return r; }
; __device__ __forceinline__ float dpp_ror1(float v) { return __builtin_bit_cast(float, __builtin_amdgcn_update_dpp(0, __builtin_bit_cast(int, v), 0x121, 0xf, 0xf, false)); }
; __device__ __forceinline__ float dpp_ror15(float v) { return __builtin_bit_cast(float, __builtin_amdgcn_update_dpp(0, __builtin_bit_cast(int, v), 0x12F, 0xf, 0xf, false)); }
;     __device__ __forceinline__ void operator()(const f32x4 (&acc)[2][2][4][2], const Unit& u, int wr, int wc, int fr, int fq) const {
;     ...
;                     for (int bj = 0; bj < 2; ++bj) { const f32x4 cur = acc[ai][bj][m][n];
;                         f32x4 su = cur, sd = cur;
;                         if (m > 0) { if (fr == 15) su = acc[ai][bj][m > 0 ? m - 1 : 0][n]; }
;                         if (m < 3) { if (fr == 0) sd = acc[ai][bj][m < 3 ? m + 1 : 3][n]; }
;                         f32x4 up, dn;
;                         up[0] = dpp_ror1(su[0]); up[1] = dpp_ror1(su[1]); up[2] = dpp_ror1(su[2]); up[3] = dpp_ror1(su[3]);
;                         dn[0] = dpp_ror15(sd[0]); dn[1] = dpp_ror15(sd[1]); dn[2] = dpp_ror15(sd[2]); dn[3] = dpp_ror15(sd[3]);
;                         if (m == 0) { f32x4 halo = zero4; if (blk > 0) halo = *(const PG8_LAS f32x4*)(xb + (((((blk - 1) * 2 + 1) * 4 + wc) * 4 + fq) * 16 + (bj * 2 + n) * 4)); if (fr == 0) up = halo; }
;                         if (m == 3) { f32x4 halo = zero4; if (blk < 3) halo = *(const PG8_LAS f32x4*)(xb + (((((blk + 1) * 2 + 0) * 4 + wc) * 4 + fq) * 16 + (bj * 2 + n) * 4)); if (fr == 15) dn = halo; }
;                         if (edge) { if (!upok) up = zero4; if (!dnok) dn = zero4; }
;                         res[bj] = bb[bj] + w0[bj] * up + w1[bj] * cur + w2[bj] * dn; }
;                     if (store_ok) {
;                         float o[4];
; #pragma unroll
;                         for (int j = 0; j < 4; ++j) { const float gg = res[1][j]; o[j] = gg * __builtin_amdgcn_rcpf(1.f + __expf(-gg)) * res[0][j]; }
;                         u32x2 w; w.x = cvt_pk_bf16(o[0], o[1]); w.y = cvt_pk_bf16(o[2], o[3]);
;                         *(u32x2*)(ACT + (size_t)(seqrow + t) * 2816 + ch0 + 4 * n) = w; } } }
	v_cndmask_b32_e64 v196, v196, v200, s[4:5]
	v_cndmask_b32_e64 v197, v197, v201, s[4:5]
	v_pk_fma_f32 v[202:203], v[124:125], v[176:177], v[136:137]
	v_pk_fma_f32 v[140:141], v[140:141], v[128:129], v[202:203]
	v_pk_fma_f32 v[140:141], v[132:133], v[196:197], v[140:141]
	ds_read_b64 v[176:177], v244 offset:768
	ds_read_b64 v[196:197], v243 offset:784
	ds_read_b64 v[200:201], v246
	v_mul_f32_e32 v208, 0xbfb8aa3b, v162
	v_mul_f32_e32 v209, 0xbfb8aa3b, v163
	v_mul_f32_e32 v210, 0xbfb8aa3b, v164
	v_mul_f32_e32 v211, 0xbfb8aa3b, v165
	v_exp_f32_e32 v208, v208
	v_exp_f32_e32 v209, v209
	v_exp_f32_e32 v210, v210
	v_exp_f32_e32 v211, v211
	v_add_f32_e32 v208, 1.0, v208
	v_add_f32_e32 v209, 1.0, v209
	v_add_f32_e32 v210, 1.0, v210
	v_add_f32_e32 v211, 1.0, v211
	v_rcp_f32_e32 v208, v208
	v_rcp_f32_e32 v209, v209
	v_rcp_f32_e32 v210, v210
	v_rcp_f32_e32 v211, v211
	v_mul_f32_e32 v162, v162, v208
	v_mul_f32_e32 v163, v163, v209
	v_mul_f32_e32 v164, v164, v210
	v_mul_f32_e32 v165, v165, v211
	v_mul_f32_e32 v162, v166, v162
	v_mul_f32_e32 v163, v167, v163
	v_mul_f32_e32 v164, v168, v164
	v_mul_f32_e32 v165, v169, v165
	v_cvt_pk_bf16_f32 v212, v162, v163
	v_cvt_pk_bf16_f32 v213, v164, v165
	ds_bpermute_b32 v212, v250, v212
	ds_bpermute_b32 v213, v250, v213
	v_mul_f32_e32 v208, 0xbfb8aa3b, v154
	v_mul_f32_e32 v209, 0xbfb8aa3b, v155
	v_mul_f32_e32 v210, 0xbfb8aa3b, v156
	v_mul_f32_e32 v211, 0xbfb8aa3b, v157
	v_exp_f32_e32 v208, v208
	v_exp_f32_e32 v209, v209
	v_exp_f32_e32 v210, v210
	v_exp_f32_e32 v211, v211
	v_add_f32_e32 v208, 1.0, v208
	v_add_f32_e32 v209, 1.0, v209
	v_add_f32_e32 v210, 1.0, v210
	v_add_f32_e32 v211, 1.0, v211
	v_rcp_f32_e32 v208, v208
	v_rcp_f32_e32 v209, v209
	v_rcp_f32_e32 v210, v210
	v_rcp_f32_e32 v211, v211
	v_mul_f32_e32 v154, v154, v208
	v_mul_f32_e32 v155, v155, v209
	v_mul_f32_e32 v156, v156, v210
	v_mul_f32_e32 v157, v157, v211
	v_mul_f32_e32 v154, v158, v154
	v_mul_f32_e32 v155, v159, v155
	v_mul_f32_e32 v156, v160, v156
	v_mul_f32_e32 v157, v161, v157
	v_cvt_pk_bf16_f32 v218, v154, v155
	v_cvt_pk_bf16_f32 v219, v156, v157
	ds_bpermute_b32 v218, v250, v218
	ds_bpermute_b32 v219, v250, v219
	s_waitcnt lgkmcnt(2)
	v_add_u32_e32 v221, 0x0, v247
	s_and_saveexec_b64 s[30:31], s[12:13]
	global_store_dwordx2 v221, v[212:213], s[10:11]
	s_mov_b64 exec, s[30:31]
	v_mul_f32_e32 v208, 0xbfb8aa3b, v146
	v_mul_f32_e32 v209, 0xbfb8aa3b, v147
	v_mul_f32_e32 v210, 0xbfb8aa3b, v148
	v_mul_f32_e32 v211, 0xbfb8aa3b, v149
	v_exp_f32_e32 v208, v208
	v_exp_f32_e32 v209, v209
	v_exp_f32_e32 v210, v210
	v_exp_f32_e32 v211, v211
	v_add_f32_e32 v208, 1.0, v208
	v_add_f32_e32 v209, 1.0, v209
	v_add_f32_e32 v210, 1.0, v210
	v_add_f32_e32 v211, 1.0, v211
	v_rcp_f32_e32 v208, v208
	v_rcp_f32_e32 v209, v209
	v_rcp_f32_e32 v210, v210
	v_rcp_f32_e32 v211, v211
	v_mul_f32_e32 v146, v146, v208
	v_mul_f32_e32 v147, v147, v209
	v_mul_f32_e32 v148, v148, v210
	v_mul_f32_e32 v149, v149, v211
	v_mul_f32_e32 v146, v150, v146
	v_mul_f32_e32 v147, v151, v147
	v_mul_f32_e32 v148, v152, v148
	v_mul_f32_e32 v149, v153, v149
	v_cvt_pk_bf16_f32 v212, v146, v147
	v_cvt_pk_bf16_f32 v213, v148, v149
	ds_bpermute_b32 v212, v250, v212
	ds_bpermute_b32 v213, v250, v213
	s_waitcnt lgkmcnt(2)
	v_add_u32_e32 v251, 0x16000, v247
	s_and_saveexec_b64 s[30:31], s[14:15]
	global_store_dwordx2 v251, v[218:219], s[10:11]
	s_mov_b64 exec, s[30:31]
	v_mul_f32_e32 v208, 0xbfb8aa3b, v138
	v_mul_f32_e32 v209, 0xbfb8aa3b, v139
	v_mul_f32_e32 v210, 0xbfb8aa3b, v140
	v_mul_f32_e32 v211, 0xbfb8aa3b, v141
	v_exp_f32_e32 v208, v208
	v_exp_f32_e32 v209, v209
	v_exp_f32_e32 v210, v210
	v_exp_f32_e32 v211, v211
	v_add_f32_e32 v208, 1.0, v208
	v_add_f32_e32 v209, 1.0, v209
	v_add_f32_e32 v210, 1.0, v210
	v_add_f32_e32 v211, 1.0, v211
	v_rcp_f32_e32 v208, v208
	v_rcp_f32_e32 v209, v209
	v_rcp_f32_e32 v210, v210
	v_rcp_f32_e32 v211, v211
	v_mul_f32_e32 v138, v138, v208
	v_mul_f32_e32 v139, v139, v209
	v_mul_f32_e32 v140, v140, v210
	v_mul_f32_e32 v141, v141, v211
	v_mul_f32_e32 v138, v142, v138
	v_mul_f32_e32 v139, v143, v139
	v_mul_f32_e32 v140, v144, v140
	v_mul_f32_e32 v141, v145, v141
	v_cvt_pk_bf16_f32 v218, v138, v139
	v_cvt_pk_bf16_f32 v219, v140, v141
	ds_bpermute_b32 v218, v250, v218
	ds_bpermute_b32 v219, v250, v219
	s_waitcnt lgkmcnt(2)
	v_add_u32_e32 v221, 0x2c000, v247
	s_and_saveexec_b64 s[30:31], s[16:17]
	global_store_dwordx2 v221, v[212:213], s[10:11]
	s_mov_b64 exec, s[30:31]
	s_waitcnt lgkmcnt(0)
	v_add_u32_e32 v251, 0x42000, v247
	s_and_saveexec_b64 s[30:31], s[18:19]
	global_store_dwordx2 v251, v[218:219], s[10:11]
	s_mov_b64 exec, s[30:31]
	global_load_dwordx4 v[138:141], v248, s[62:63] offset:16
	global_load_dwordx4 v[142:145], v248, s[66:67] offset:16
	global_load_dwordx4 v[146:149], v248, s[68:69] offset:16
	global_load_dwordx4 v[150:153], v248, s[64:65] offset:16
	global_load_dwordx4 v[154:157], v249, s[62:63] offset:16
	global_load_dwordx4 v[158:161], v249, s[66:67] offset:16
	global_load_dwordx4 v[162:165], v249, s[68:69] offset:16
	global_load_dwordx4 v[166:169], v249, s[64:65] offset:16
	ds_write_b64 v243, v[104:105]
	ds_write_b64 v243, v[96:97] offset:256
	ds_write_b64 v243, v[88:89] offset:512
	ds_write_b64 v243, v[80:81] offset:768
	v_cndmask_b32_e64 v170, v170, v198, s[6:7]
	v_cndmask_b32_e64 v171, v171, v199, s[6:7]
	v_pk_fma_f32 v[202:203], v[106:107], v[170:171], v[118:119]
	v_pk_fma_f32 v[102:103], v[102:103], v[110:111], v[202:203]
	v_pk_fma_f32 v[102:103], v[114:115], v[178:179], v[102:103]
	ds_read_b64 v[170:171], v244
	ds_read_b64 v[178:179], v243 offset:16
	ds_read_b64 v[198:199], v238 offset:3080
	v_pk_fma_f32 v[202:203], v[106:107], v[172:173], v[118:119]
	v_pk_fma_f32 v[94:95], v[94:95], v[110:111], v[202:203]
	v_pk_fma_f32 v[94:95], v[114:115], v[180:181], v[94:95]
	ds_read_b64 v[172:173], v244 offset:256
	ds_read_b64 v[180:181], v243 offset:272
	v_pk_fma_f32 v[202:203], v[106:107], v[174:175], v[118:119]
	v_pk_fma_f32 v[86:87], v[86:87], v[110:111], v[202:203]
	v_pk_fma_f32 v[86:87], v[114:115], v[194:195], v[86:87]
	ds_read_b64 v[174:175], v244 offset:512
	ds_read_b64 v[194:195], v243 offset:528
	v_cndmask_b32_e64 v196, v196, v200, s[4:5]
	v_cndmask_b32_e64 v197, v197, v201, s[4:5]
	v_pk_fma_f32 v[202:203], v[106:107], v[176:177], v[118:119]
	v_pk_fma_f32 v[78:79], v[78:79], v[110:111], v[202:203]
	v_pk_fma_f32 v[78:79], v[114:115], v[196:197], v[78:79]
	ds_read_b64 v[176:177], v244 offset:768
	ds_read_b64 v[196:197], v243 offset:784
	ds_read_b64 v[200:201], v246 offset:8
	ds_write_b64 v243, v[98:99]
	ds_write_b64 v243, v[90:91] offset:256
	ds_write_b64 v243, v[82:83] offset:512
	ds_write_b64 v243, v[74:75] offset:768
	s_waitcnt lgkmcnt(11)
; #define PG8_LAS __attribute__((address_space(3)))
; __device__ __forceinline__ unsigned cvt_pk_bf16(float lo, float hi) { unsigned r; asm volatile("v_cvt_pk_bf16_f32 %0, %1, %2" : "=v"(r) : "v"(lo), "v"(hi)); return r; }
;     __device__ __forceinline__ void operator()(const f32x4 (&acc)[2][2][4][2], const Unit& u, int wr, int wc, int fr, int fq) const {
;     ...
;                 for (int m = 0; m < 4; ++m) { const int r = 128 * ai + 64 * wr + 16 * m + fr, t = tstart + r;
;                     const bool upok = t >= 1, dnok = (t + 1) < T, store_ok = (r >= vlo) && (r < vhi) && (t < T);
;                     f32x4 res[2];
; #pragma unroll
;                     for (int bj = 0; bj < 2; ++bj) { const f32x4 cur = acc[ai][bj][m][n];
;                         f32x4 su = cur, sd = cur;
;                         if (m > 0) { if (fr == 15) su = acc[ai][bj][m > 0 ? m - 1 : 0][n]; }
;                         if (m < 3) { if (fr == 0) sd = acc[ai][bj][m < 3 ? m + 1 : 3][n]; }
;                         f32x4 up, dn;
;                         up[0] = dpp_ror1(su[0]); up[1] = dpp_ror1(su[1]); up[2] = dpp_ror1(su[2]); up[3] = dpp_ror1(su[3]);
;                         dn[0] = dpp_ror15(sd[0]); dn[1] = dpp_ror15(sd[1]); dn[2] = dpp_ror15(sd[2]); dn[3] = dpp_ror15(sd[3]);
;                         if (m == 0) { f32x4 halo = zero4; if (blk > 0) halo = *(const PG8_LAS f32x4*)(xb + (((((blk - 1) * 2 + 1) * 4 + wc) * 4 + fq) * 16 + (bj * 2 + n) * 4)); if (fr == 0) up = halo; }
;                         if (m == 3) { f32x4 halo = zero4; if (blk < 3) halo = *(const PG8_LAS f32x4*)(xb + (((((blk + 1) * 2 + 0) * 4 + wc) * 4 + fq) * 16 + (bj * 2 + n) * 4)); if (fr == 15) dn = halo; }
;                         if (edge) { if (!upok) up = zero4; if (!dnok) dn = zero4; }
;                         res[bj] = bb[bj] + w0[bj] * up + w1[bj] * cur + w2[bj] * dn; }
;                     if (store_ok) {
;                         float o[4];
; #pragma unroll
;                         for (int j = 0; j < 4; ++j) { const float gg = res[1][j]; o[j] = gg * __builtin_amdgcn_rcpf(1.f + __expf(-gg)) * res[0][j]; }
;                         u32x2 w; w.x = cvt_pk_bf16(o[0], o[1]); w.y = cvt_pk_bf16(o[2], o[3]);
;                         *(u32x2*)(ACT + (size_t)(seqrow + t) * 2816 + ch0 + 4 * n) = w; } } }
	v_cndmask_b32_e64 v170, v170, v198, s[6:7]
	v_cndmask_b32_e64 v171, v171, v199, s[6:7]
	v_pk_fma_f32 v[202:203], v[108:109], v[170:171], v[120:121]
	v_pk_fma_f32 v[104:105], v[104:105], v[112:113], v[202:203]
	v_pk_fma_f32 v[104:105], v[116:117], v[178:179], v[104:105]
	ds_read_b64 v[170:171], v244
	ds_read_b64 v[178:179], v243 offset:16
	ds_read_b64 v[198:199], v238 offset:3104
	s_waitcnt lgkmcnt(12)
	v_pk_fma_f32 v[202:203], v[108:109], v[172:173], v[120:121]
	v_pk_fma_f32 v[96:97], v[96:97], v[112:113], v[202:203]
	v_pk_fma_f32 v[96:97], v[116:117], v[180:181], v[96:97]
	ds_read_b64 v[172:173], v244 offset:256
	ds_read_b64 v[180:181], v243 offset:272
	s_waitcnt lgkmcnt(12)
	v_pk_fma_f32 v[202:203], v[108:109], v[174:175], v[120:121]
	v_pk_fma_f32 v[88:89], v[88:89], v[112:113], v[202:203]
	v_pk_fma_f32 v[88:89], v[116:117], v[194:195], v[88:89]
	ds_read_b64 v[174:175], v244 offset:512
	ds_read_b64 v[194:195], v243 offset:528
	s_waitcnt lgkmcnt(11)
	v_cndmask_b32_e64 v196, v196, v200, s[4:5]
	v_cndmask_b32_e64 v197, v197, v201, s[4:5]
	v_pk_fma_f32 v[202:203], v[108:109], v[176:177], v[120:121]
	v_pk_fma_f32 v[80:81], v[80:81], v[112:113], v[202:203]
	v_pk_fma_f32 v[80:81], v[116:117], v[196:197], v[80:81]
	ds_read_b64 v[176:177], v244 offset:768
	ds_read_b64 v[196:197], v243 offset:784
	ds_read_b64 v[200:201], v246 offset:32
	ds_write_b64 v243, v[100:101]
	ds_write_b64 v243, v[92:93] offset:256
	ds_write_b64 v243, v[84:85] offset:512
	ds_write_b64 v243, v[76:77] offset:768
	s_waitcnt lgkmcnt(11)
	v_cndmask_b32_e64 v170, v170, v198, s[6:7]
	v_cndmask_b32_e64 v171, v171, v199, s[6:7]
	v_pk_fma_f32 v[202:203], v[122:123], v[170:171], v[134:135]
	v_pk_fma_f32 v[98:99], v[98:99], v[126:127], v[202:203]
	v_pk_fma_f32 v[98:99], v[130:131], v[178:179], v[98:99]
	ds_read_b64 v[170:171], v244
	ds_read_b64 v[178:179], v243 offset:16
	ds_read_b64 v[198:199], v238 offset:3112
	s_waitcnt lgkmcnt(12)
	v_pk_fma_f32 v[202:203], v[122:123], v[172:173], v[134:135]
	v_pk_fma_f32 v[90:91], v[90:91], v[126:127], v[202:203]
	v_pk_fma_f32 v[90:91], v[130:131], v[180:181], v[90:91]
	ds_read_b64 v[172:173], v244 offset:256
	ds_read_b64 v[180:181], v243 offset:272
	s_waitcnt lgkmcnt(12)
	v_pk_fma_f32 v[202:203], v[122:123], v[174:175], v[134:135]
	v_pk_fma_f32 v[82:83], v[82:83], v[126:127], v[202:203]
	v_pk_fma_f32 v[82:83], v[130:131], v[194:195], v[82:83]
	ds_read_b64 v[174:175], v244 offset:512
	ds_read_b64 v[194:195], v243 offset:528
	s_waitcnt lgkmcnt(11)
	v_cndmask_b32_e64 v196, v196, v200, s[4:5]
	v_cndmask_b32_e64 v197, v197, v201, s[4:5]
	v_pk_fma_f32 v[202:203], v[122:123], v[176:177], v[134:135]
	v_pk_fma_f32 v[74:75], v[74:75], v[126:127], v[202:203]
	v_pk_fma_f32 v[74:75], v[130:131], v[196:197], v[74:75]
	ds_read_b64 v[176:177], v244 offset:768
	ds_read_b64 v[196:197], v243 offset:784
	ds_read_b64 v[200:201], v246 offset:40
	ds_write_b64 v243, v[70:71]
	ds_write_b64 v243, v[62:63] offset:256
	ds_write_b64 v243, v[54:55] offset:512
	ds_write_b64 v243, v[46:47] offset:768
	s_waitcnt lgkmcnt(11)
	v_cndmask_b32_e64 v170, v170, v198, s[6:7]
	v_cndmask_b32_e64 v171, v171, v199, s[6:7]
	v_pk_fma_f32 v[202:203], v[124:125], v[170:171], v[136:137]
	v_pk_fma_f32 v[100:101], v[100:101], v[128:129], v[202:203]
	v_pk_fma_f32 v[100:101], v[132:133], v[178:179], v[100:101]
	ds_read_b64 v[170:171], v244
	ds_read_b64 v[178:179], v243 offset:16
	ds_read_b64 v[198:199], v245 offset:16
	s_waitcnt lgkmcnt(12)
	v_pk_fma_f32 v[202:203], v[124:125], v[172:173], v[136:137]
	v_pk_fma_f32 v[92:93], v[92:93], v[128:129], v[202:203]
	v_pk_fma_f32 v[92:93], v[132:133], v[180:181], v[92:93]
	ds_read_b64 v[172:173], v244 offset:256
	ds_read_b64 v[180:181], v243 offset:272
	s_waitcnt lgkmcnt(12)
	v_pk_fma_f32 v[202:203], v[124:125], v[174:175], v[136:137]
	v_pk_fma_f32 v[84:85], v[84:85], v[128:129], v[202:203]
	v_pk_fma_f32 v[84:85], v[132:133], v[194:195], v[84:85]
	ds_read_b64 v[174:175], v244 offset:512
	ds_read_b64 v[194:195], v243 offset:528
	s_waitcnt lgkmcnt(11)
	v_cndmask_b32_e64 v196, v196, v200, s[4:5]
	v_cndmask_b32_e64 v197, v197, v201, s[4:5]
	v_pk_fma_f32 v[202:203], v[124:125], v[176:177], v[136:137]
	v_pk_fma_f32 v[76:77], v[76:77], v[128:129], v[202:203]
	v_pk_fma_f32 v[76:77], v[132:133], v[196:197], v[76:77]
	ds_read_b64 v[176:177], v244 offset:768
	ds_read_b64 v[196:197], v243 offset:784
	ds_read_b64 v[200:201], v238 offset:2064
	v_mul_f32_e32 v208, 0xbfb8aa3b, v98
	v_mul_f32_e32 v209, 0xbfb8aa3b, v99
	v_mul_f32_e32 v210, 0xbfb8aa3b, v100
	v_mul_f32_e32 v211, 0xbfb8aa3b, v101
	v_exp_f32_e32 v208, v208
	v_exp_f32_e32 v209, v209
	v_exp_f32_e32 v210, v210
	v_exp_f32_e32 v211, v211
	v_add_f32_e32 v208, 1.0, v208
	v_add_f32_e32 v209, 1.0, v209
	v_add_f32_e32 v210, 1.0, v210
	v_add_f32_e32 v211, 1.0, v211
	v_rcp_f32_e32 v208, v208
	v_rcp_f32_e32 v209, v209
	v_rcp_f32_e32 v210, v210
	v_rcp_f32_e32 v211, v211
	v_mul_f32_e32 v98, v98, v208
	v_mul_f32_e32 v99, v99, v209
	v_mul_f32_e32 v100, v100, v210
	v_mul_f32_e32 v101, v101, v211
	v_mul_f32_e32 v98, v102, v98
	v_mul_f32_e32 v99, v103, v99
	v_mul_f32_e32 v100, v104, v100
	v_mul_f32_e32 v101, v105, v101
	v_cvt_pk_bf16_f32 v212, v98, v99
	v_cvt_pk_bf16_f32 v213, v100, v101
	ds_bpermute_b32 v212, v250, v212
	ds_bpermute_b32 v213, v250, v213
	v_mul_f32_e32 v208, 0xbfb8aa3b, v90
	v_mul_f32_e32 v209, 0xbfb8aa3b, v91
	v_mul_f32_e32 v210, 0xbfb8aa3b, v92
	v_mul_f32_e32 v211, 0xbfb8aa3b, v93
	v_exp_f32_e32 v208, v208
	v_exp_f32_e32 v209, v209
	v_exp_f32_e32 v210, v210
	v_exp_f32_e32 v211, v211
	v_add_f32_e32 v208, 1.0, v208
	v_add_f32_e32 v209, 1.0, v209
	v_add_f32_e32 v210, 1.0, v210
	v_add_f32_e32 v211, 1.0, v211
	v_rcp_f32_e32 v208, v208
	v_rcp_f32_e32 v209, v209
	v_rcp_f32_e32 v210, v210
	v_rcp_f32_e32 v211, v211
	v_mul_f32_e32 v90, v90, v208
	v_mul_f32_e32 v91, v91, v209
	v_mul_f32_e32 v92, v92, v210
	v_mul_f32_e32 v93, v93, v211
	v_mul_f32_e32 v90, v94, v90
	v_mul_f32_e32 v91, v95, v91
	v_mul_f32_e32 v92, v96, v92
	v_mul_f32_e32 v93, v97, v93
	v_cvt_pk_bf16_f32 v218, v90, v91
	v_cvt_pk_bf16_f32 v219, v92, v93
	ds_bpermute_b32 v218, v250, v218
	ds_bpermute_b32 v219, v250, v219
	s_waitcnt lgkmcnt(2)
;     __device__ __forceinline__ void operator()(const f32x4 (&acc)[2][2][4][2], const Unit& u, int wr, int wc, int fr, int fq) const {
;     ...
;         for (int n = 0; n < 2; ++n) {
;             if (n == 1) {
; #pragma unroll
;                 for (int bj = 0; bj < 2; ++bj) { const int col = bj * 2816 + ch0 + 4;
;                     w0[bj] = *(const f32x4*)(cw + col); w1[bj] = *(const f32x4*)(cw + 5632 + col); w2[bj] = *(const f32x4*)(cw + 11264 + col); bb[bj] = *(const f32x4*)(cb + col); } }
; #pragma unroll
;             for (int ai = 0; ai < 2; ++ai) { const int blk = ai * 2 + wr;
; #pragma unroll
;                 for (int m = 0; m < 4; ++m) { const int r = 128 * ai + 64 * wr + 16 * m + fr, t = tstart + r;
;                     const bool upok = t >= 1, dnok = (t + 1) < T, store_ok = (r >= vlo) && (r < vhi) && (t < T);
;                     f32x4 res[2];
; #pragma unroll
;                     for (int bj = 0; bj < 2; ++bj) { const f32x4 cur = acc[ai][bj][m][n];
;                         f32x4 su = cur, sd = cur;
;                         if (m > 0) { if (fr == 15) su = acc[ai][bj][m > 0 ? m - 1 : 0][n]; }
;                         if (m < 3) { if (fr == 0) sd = acc[ai][bj][m < 3 ? m + 1 : 3][n]; }
;                         f32x4 up, dn;
;                         up[0] = dpp_ror1(su[0]); up[1] = dpp_ror1(su[1]); up[2] = dpp_ror1(su[2]); up[3] = dpp_ror1(su[3]);
;                         dn[0] = dpp_ror15(sd[0]); dn[1] = dpp_ror15(sd[1]); dn[2] = dpp_ror15(sd[2]); dn[3] = dpp_ror15(sd[3]);
;                         if (m == 0) { f32x4 halo = zero4; if (blk > 0) halo = *(const PG8_LAS f32x4*)(xb + (((((blk - 1) * 2 + 1) * 4 + wc) * 4 + fq) * 16 + (bj * 2 + n) * 4)); if (fr == 0) up = halo; }
;                         if (m == 3) { f32x4 halo = zero4; if (blk < 3) halo = *(const PG8_LAS f32x4*)(xb + (((((blk + 1) * 2 + 0) * 4 + wc) * 4 + fq) * 16 + (bj * 2 + n) * 4)); if (fr == 15) dn = halo; }
;     ...
;                     if (store_ok) {
;                         float o[4];
; #pragma unroll
;                         for (int j = 0; j < 4; ++j) { const float gg = res[1][j]; o[j] = gg * __builtin_amdgcn_rcpf(1.f + __expf(-gg)) * res[0][j]; }
;                         u32x2 w; w.x = cvt_pk_bf16(o[0], o[1]); w.y = cvt_pk_bf16(o[2], o[3]);
;                         *(u32x2*)(ACT + (size_t)(seqrow + t) * 2816 + ch0 + 4 * n) = w; } } }
	v_add_u32_e32 v221, 0xb0000, v247
	s_and_saveexec_b64 s[30:31], s[20:21]
	global_store_dwordx2 v221, v[212:213], s[10:11]
	s_mov_b64 exec, s[30:31]
	v_mul_f32_e32 v208, 0xbfb8aa3b, v82
	v_mul_f32_e32 v209, 0xbfb8aa3b, v83
	v_mul_f32_e32 v210, 0xbfb8aa3b, v84
	v_mul_f32_e32 v211, 0xbfb8aa3b, v85
	v_exp_f32_e32 v208, v208
	v_exp_f32_e32 v209, v209
	v_exp_f32_e32 v210, v210
	v_exp_f32_e32 v211, v211
	v_add_f32_e32 v208, 1.0, v208
	v_add_f32_e32 v209, 1.0, v209
	v_add_f32_e32 v210, 1.0, v210
	v_add_f32_e32 v211, 1.0, v211
	v_rcp_f32_e32 v208, v208
	v_rcp_f32_e32 v209, v209
	v_rcp_f32_e32 v210, v210
	v_rcp_f32_e32 v211, v211
	v_mul_f32_e32 v82, v82, v208
	v_mul_f32_e32 v83, v83, v209
	v_mul_f32_e32 v84, v84, v210
	v_mul_f32_e32 v85, v85, v211
	v_mul_f32_e32 v82, v86, v82
	v_mul_f32_e32 v83, v87, v83
	v_mul_f32_e32 v84, v88, v84
	v_mul_f32_e32 v85, v89, v85
	v_cvt_pk_bf16_f32 v212, v82, v83
	v_cvt_pk_bf16_f32 v213, v84, v85
	ds_bpermute_b32 v212, v250, v212
	ds_bpermute_b32 v213, v250, v213
	s_waitcnt lgkmcnt(2)
	v_add_u32_e32 v251, 0xc6000, v247
	s_and_saveexec_b64 s[30:31], s[22:23]
	global_store_dwordx2 v251, v[218:219], s[10:11]
	s_mov_b64 exec, s[30:31]
	v_mul_f32_e32 v208, 0xbfb8aa3b, v74
	v_mul_f32_e32 v209, 0xbfb8aa3b, v75
	v_mul_f32_e32 v210, 0xbfb8aa3b, v76
	v_mul_f32_e32 v211, 0xbfb8aa3b, v77
	v_exp_f32_e32 v208, v208
	v_exp_f32_e32 v209, v209
	v_exp_f32_e32 v210, v210
	v_exp_f32_e32 v211, v211
	v_add_f32_e32 v208, 1.0, v208
	v_add_f32_e32 v209, 1.0, v209
	v_add_f32_e32 v210, 1.0, v210
	v_add_f32_e32 v211, 1.0, v211
	v_rcp_f32_e32 v208, v208
	v_rcp_f32_e32 v209, v209
	v_rcp_f32_e32 v210, v210
	v_rcp_f32_e32 v211, v211
	v_mul_f32_e32 v74, v74, v208
	v_mul_f32_e32 v75, v75, v209
	v_mul_f32_e32 v76, v76, v210
	v_mul_f32_e32 v77, v77, v211
	v_mul_f32_e32 v74, v78, v74
	v_mul_f32_e32 v75, v79, v75
	v_mul_f32_e32 v76, v80, v76
	v_mul_f32_e32 v77, v81, v77
	v_cvt_pk_bf16_f32 v218, v74, v75
	v_cvt_pk_bf16_f32 v219, v76, v77
	ds_bpermute_b32 v218, v250, v218
	ds_bpermute_b32 v219, v250, v219
	s_waitcnt lgkmcnt(2)
	v_add_u32_e32 v221, 0xdc000, v247
	s_and_saveexec_b64 s[30:31], s[24:25]
	global_store_dwordx2 v221, v[212:213], s[10:11]
	s_mov_b64 exec, s[30:31]
	s_waitcnt lgkmcnt(0)
	v_add_u32_e32 v251, 0xf2000, v247
	s_and_saveexec_b64 s[30:31], s[26:27]
	global_store_dwordx2 v251, v[218:219], s[10:11]
	s_mov_b64 exec, s[30:31]
	s_waitcnt vmcnt(4)
	ds_write_b64 v243, v[72:73]
	ds_write_b64 v243, v[64:65] offset:256
	ds_write_b64 v243, v[56:57] offset:512
	ds_write_b64 v243, v[48:49] offset:768
	v_cndmask_b32_e64 v170, v170, v198, s[6:7]
	v_cndmask_b32_e64 v171, v171, v199, s[6:7]
	v_pk_fma_f32 v[202:203], v[138:139], v[170:171], v[150:151]
	v_pk_fma_f32 v[70:71], v[70:71], v[142:143], v[202:203]
	v_pk_fma_f32 v[70:71], v[146:147], v[178:179], v[70:71]
	ds_read_b64 v[170:171], v244
	ds_read_b64 v[178:179], v243 offset:16
	ds_read_b64 v[198:199], v245 offset:24
	v_pk_fma_f32 v[202:203], v[138:139], v[172:173], v[150:151]
	v_pk_fma_f32 v[62:63], v[62:63], v[142:143], v[202:203]
	v_pk_fma_f32 v[62:63], v[146:147], v[180:181], v[62:63]
	ds_read_b64 v[172:173], v244 offset:256
	ds_read_b64 v[180:181], v243 offset:272
	v_pk_fma_f32 v[202:203], v[138:139], v[174:175], v[150:151]
	v_pk_fma_f32 v[54:55], v[54:55], v[142:143], v[202:203]
	v_pk_fma_f32 v[54:55], v[146:147], v[194:195], v[54:55]
	ds_read_b64 v[174:175], v244 offset:512
	ds_read_b64 v[194:195], v243 offset:528
	v_cndmask_b32_e64 v196, v196, v200, s[4:5]
	v_cndmask_b32_e64 v197, v197, v201, s[4:5]
	v_pk_fma_f32 v[202:203], v[138:139], v[176:177], v[150:151]
	v_pk_fma_f32 v[46:47], v[46:47], v[142:143], v[202:203]
	v_pk_fma_f32 v[46:47], v[146:147], v[196:197], v[46:47]
	ds_read_b64 v[176:177], v244 offset:768
	ds_read_b64 v[196:197], v243 offset:784
	ds_read_b64 v[200:201], v238 offset:2072
	ds_write_b64 v243, v[66:67]
	ds_write_b64 v243, v[58:59] offset:256
	ds_write_b64 v243, v[50:51] offset:512
	ds_write_b64 v243, v[42:43] offset:768
	s_waitcnt lgkmcnt(11)
	v_cndmask_b32_e64 v170, v170, v198, s[6:7]
	v_cndmask_b32_e64 v171, v171, v199, s[6:7]
	v_pk_fma_f32 v[202:203], v[140:141], v[170:171], v[152:153]
	v_pk_fma_f32 v[72:73], v[72:73], v[144:145], v[202:203]
	v_pk_fma_f32 v[72:73], v[148:149], v[178:179], v[72:73]
	ds_read_b64 v[170:171], v244
	ds_read_b64 v[178:179], v243 offset:16
	ds_read_b64 v[198:199], v245 offset:48
	s_waitcnt lgkmcnt(12)
	v_pk_fma_f32 v[202:203], v[140:141], v[172:173], v[152:153]
	v_pk_fma_f32 v[64:65], v[64:65], v[144:145], v[202:203]
	v_pk_fma_f32 v[64:65], v[148:149], v[180:181], v[64:65]
	ds_read_b64 v[172:173], v244 offset:256
	ds_read_b64 v[180:181], v243 offset:272
	s_waitcnt lgkmcnt(12)
	v_pk_fma_f32 v[202:203], v[140:141], v[174:175], v[152:153]
	v_pk_fma_f32 v[56:57], v[56:57], v[144:145], v[202:203]
	v_pk_fma_f32 v[56:57], v[148:149], v[194:195], v[56:57]
	ds_read_b64 v[174:175], v244 offset:512
	ds_read_b64 v[194:195], v243 offset:528
	s_waitcnt lgkmcnt(11)
	v_cndmask_b32_e64 v196, v196, v200, s[4:5]
	v_cndmask_b32_e64 v197, v197, v201, s[4:5]
	v_pk_fma_f32 v[202:203], v[140:141], v[176:177], v[152:153]
	v_pk_fma_f32 v[48:49], v[48:49], v[144:145], v[202:203]
	v_pk_fma_f32 v[48:49], v[148:149], v[196:197], v[48:49]
	ds_read_b64 v[176:177], v244 offset:768
	ds_read_b64 v[196:197], v243 offset:784
	ds_read_b64 v[200:201], v238 offset:2096
	ds_write_b64 v243, v[68:69]
	ds_write_b64 v243, v[60:61] offset:256
	ds_write_b64 v243, v[52:53] offset:512
	ds_write_b64 v243, v[44:45] offset:768
	s_waitcnt lgkmcnt(11)
; #define PG8_LAS __attribute__((address_space(3)))
;     __device__ __forceinline__ void operator()(const f32x4 (&acc)[2][2][4][2], const Unit& u, int wr, int wc, int fr, int fq) const {
;     ...
;         for (int n = 0; n < 2; ++n) {
;             if (n == 1) {
; #pragma unroll
;                 for (int bj = 0; bj < 2; ++bj) { const int col = bj * 2816 + ch0 + 4;
;                     w0[bj] = *(const f32x4*)(cw + col); w1[bj] = *(const f32x4*)(cw + 5632 + col); w2[bj] = *(const f32x4*)(cw + 11264 + col); bb[bj] = *(const f32x4*)(cb + col); } }
; #pragma unroll
;             for (int ai = 0; ai < 2; ++ai) { const int blk = ai * 2 + wr;
; #pragma unroll
;                 for (int m = 0; m < 4; ++m) { const int r = 128 * ai + 64 * wr + 16 * m + fr, t = tstart + r;
;                     const bool upok = t >= 1, dnok = (t + 1) < T, store_ok = (r >= vlo) && (r < vhi) && (t < T);
;                     f32x4 res[2];
; #pragma unroll
;                     for (int bj = 0; bj < 2; ++bj) { const f32x4 cur = acc[ai][bj][m][n];
;                         f32x4 su = cur, sd = cur;
;                         if (m > 0) { if (fr == 15) su = acc[ai][bj][m > 0 ? m - 1 : 0][n]; }
;                         if (m < 3) { if (fr == 0) sd = acc[ai][bj][m < 3 ? m + 1 : 3][n]; }
;                         f32x4 up, dn;
;                         up[0] = dpp_ror1(su[0]); up[1] = dpp_ror1(su[1]); up[2] = dpp_ror1(su[2]); up[3] = dpp_ror1(su[3]);
;                         dn[0] = dpp_ror15(sd[0]); dn[1] = dpp_ror15(sd[1]); dn[2] = dpp_ror15(sd[2]); dn[3] = dpp_ror15(sd[3]);
;                         if (m == 0) { f32x4 halo = zero4; if (blk > 0) halo = *(const PG8_LAS f32x4*)(xb + (((((blk - 1) * 2 + 1) * 4 + wc) * 4 + fq) * 16 + (bj * 2 + n) * 4)); if (fr == 0) up = halo; }
;                         if (m == 3) { f32x4 halo = zero4; if (blk < 3) halo = *(const PG8_LAS f32x4*)(xb + (((((blk + 1) * 2 + 0) * 4 + wc) * 4 + fq) * 16 + (bj * 2 + n) * 4)); if (fr == 15) dn = halo; }
;                         if (edge) { if (!upok) up = zero4; if (!dnok) dn = zero4; }
;                         res[bj] = bb[bj] + w0[bj] * up + w1[bj] * cur + w2[bj] * dn; }
;                     if (store_ok) {
;                         float o[4];
; #pragma unroll
;                         for (int j = 0; j < 4; ++j) { const float gg = res[1][j]; o[j] = gg * __builtin_amdgcn_rcpf(1.f + __expf(-gg)) * res[0][j]; }
	v_cndmask_b32_e64 v170, v170, v198, s[6:7]
	v_cndmask_b32_e64 v171, v171, v199, s[6:7]
	v_pk_fma_f32 v[202:203], v[154:155], v[170:171], v[166:167]
	v_pk_fma_f32 v[66:67], v[66:67], v[158:159], v[202:203]
	v_pk_fma_f32 v[66:67], v[162:163], v[178:179], v[66:67]
	ds_read_b64 v[170:171], v244
	ds_read_b64 v[178:179], v243 offset:16
	ds_read_b64 v[198:199], v245 offset:56
	s_waitcnt lgkmcnt(12)
	v_pk_fma_f32 v[202:203], v[154:155], v[172:173], v[166:167]
	v_pk_fma_f32 v[58:59], v[58:59], v[158:159], v[202:203]
	v_pk_fma_f32 v[58:59], v[162:163], v[180:181], v[58:59]
	ds_read_b64 v[172:173], v244 offset:256
	ds_read_b64 v[180:181], v243 offset:272
	s_waitcnt lgkmcnt(12)
	v_pk_fma_f32 v[202:203], v[154:155], v[174:175], v[166:167]
	v_pk_fma_f32 v[50:51], v[50:51], v[158:159], v[202:203]
	v_pk_fma_f32 v[50:51], v[162:163], v[194:195], v[50:51]
	ds_read_b64 v[174:175], v244 offset:512
	ds_read_b64 v[194:195], v243 offset:528
	s_waitcnt lgkmcnt(11)
	v_cndmask_b32_e64 v196, v196, v200, s[4:5]
	v_cndmask_b32_e64 v197, v197, v201, s[4:5]
	v_pk_fma_f32 v[202:203], v[154:155], v[176:177], v[166:167]
	v_pk_fma_f32 v[42:43], v[42:43], v[158:159], v[202:203]
	v_pk_fma_f32 v[42:43], v[162:163], v[196:197], v[42:43]
	ds_read_b64 v[176:177], v244 offset:768
	ds_read_b64 v[196:197], v243 offset:784
	ds_read_b64 v[200:201], v238 offset:2104
	ds_write_b64 v243, v[30:31]
	ds_write_b64 v243, v[22:23] offset:256
	ds_write_b64 v243, v[14:15] offset:512
	ds_write_b64 v243, v[6:7] offset:768
	s_waitcnt lgkmcnt(11)
	v_cndmask_b32_e64 v170, v170, v198, s[6:7]
	v_cndmask_b32_e64 v171, v171, v199, s[6:7]
	v_pk_fma_f32 v[202:203], v[156:157], v[170:171], v[168:169]
	v_pk_fma_f32 v[68:69], v[68:69], v[160:161], v[202:203]
	v_pk_fma_f32 v[68:69], v[164:165], v[178:179], v[68:69]
	ds_read_b64 v[170:171], v244
	ds_read_b64 v[178:179], v243 offset:16
	ds_read_b64 v[198:199], v238 offset:3088
	s_waitcnt lgkmcnt(12)
	v_pk_fma_f32 v[202:203], v[156:157], v[172:173], v[168:169]
	v_pk_fma_f32 v[60:61], v[60:61], v[160:161], v[202:203]
	v_pk_fma_f32 v[60:61], v[164:165], v[180:181], v[60:61]
	ds_read_b64 v[172:173], v244 offset:256
	ds_read_b64 v[180:181], v243 offset:272
	s_waitcnt lgkmcnt(12)
	v_pk_fma_f32 v[202:203], v[156:157], v[174:175], v[168:169]
	v_pk_fma_f32 v[52:53], v[52:53], v[160:161], v[202:203]
	v_pk_fma_f32 v[52:53], v[164:165], v[194:195], v[52:53]
	ds_read_b64 v[174:175], v244 offset:512
	ds_read_b64 v[194:195], v243 offset:528
	s_waitcnt lgkmcnt(11)
	v_cndmask_b32_e64 v196, v196, v200, s[4:5]
	v_cndmask_b32_e64 v197, v197, v201, s[4:5]
	v_pk_fma_f32 v[202:203], v[156:157], v[176:177], v[168:169]
	v_pk_fma_f32 v[44:45], v[44:45], v[160:161], v[202:203]
	v_pk_fma_f32 v[44:45], v[164:165], v[196:197], v[44:45]
	ds_read_b64 v[176:177], v244 offset:768
	ds_read_b64 v[196:197], v243 offset:784
	ds_read_b64 v[200:201], v246 offset:16
	v_mul_f32_e32 v208, 0xbfb8aa3b, v66
	v_mul_f32_e32 v209, 0xbfb8aa3b, v67
	v_mul_f32_e32 v210, 0xbfb8aa3b, v68
	v_mul_f32_e32 v211, 0xbfb8aa3b, v69
	v_exp_f32_e32 v208, v208
	v_exp_f32_e32 v209, v209
	v_exp_f32_e32 v210, v210
	v_exp_f32_e32 v211, v211
	v_add_f32_e32 v208, 1.0, v208
	v_add_f32_e32 v209, 1.0, v209
	v_add_f32_e32 v210, 1.0, v210
	v_add_f32_e32 v211, 1.0, v211
	v_rcp_f32_e32 v208, v208
	v_rcp_f32_e32 v209, v209
	v_rcp_f32_e32 v210, v210
	v_rcp_f32_e32 v211, v211
	v_mul_f32_e32 v66, v66, v208
	v_mul_f32_e32 v67, v67, v209
	v_mul_f32_e32 v68, v68, v210
	v_mul_f32_e32 v69, v69, v211
	v_mul_f32_e32 v66, v70, v66
	v_mul_f32_e32 v67, v71, v67
	v_mul_f32_e32 v68, v72, v68
	v_mul_f32_e32 v69, v73, v69
	v_cvt_pk_bf16_f32 v212, v66, v67
	v_cvt_pk_bf16_f32 v213, v68, v69
	ds_bpermute_b32 v212, v250, v212
	ds_bpermute_b32 v213, v250, v213
	v_mul_f32_e32 v208, 0xbfb8aa3b, v58
	v_mul_f32_e32 v209, 0xbfb8aa3b, v59
	v_mul_f32_e32 v210, 0xbfb8aa3b, v60
	v_mul_f32_e32 v211, 0xbfb8aa3b, v61
	v_exp_f32_e32 v208, v208
	v_exp_f32_e32 v209, v209
	v_exp_f32_e32 v210, v210
	v_exp_f32_e32 v211, v211
	v_add_f32_e32 v208, 1.0, v208
	v_add_f32_e32 v209, 1.0, v209
	v_add_f32_e32 v210, 1.0, v210
	v_add_f32_e32 v211, 1.0, v211
	v_rcp_f32_e32 v208, v208
	v_rcp_f32_e32 v209, v209
	v_rcp_f32_e32 v210, v210
	v_rcp_f32_e32 v211, v211
	v_mul_f32_e32 v58, v58, v208
	v_mul_f32_e32 v59, v59, v209
	v_mul_f32_e32 v60, v60, v210
	v_mul_f32_e32 v61, v61, v211
	v_mul_f32_e32 v58, v62, v58
	v_mul_f32_e32 v59, v63, v59
	v_mul_f32_e32 v60, v64, v60
	v_mul_f32_e32 v61, v65, v61
	v_cvt_pk_bf16_f32 v218, v58, v59
	v_cvt_pk_bf16_f32 v219, v60, v61
	ds_bpermute_b32 v218, v250, v218
	ds_bpermute_b32 v219, v250, v219
	s_waitcnt lgkmcnt(2)
	v_add_u32_e32 v221, 0x0, v247
	s_and_saveexec_b64 s[30:31], s[12:13]
	global_store_dwordx2 v221, v[212:213], s[10:11] offset:8
	s_mov_b64 exec, s[30:31]
	v_mul_f32_e32 v208, 0xbfb8aa3b, v50
	v_mul_f32_e32 v209, 0xbfb8aa3b, v51
	v_mul_f32_e32 v210, 0xbfb8aa3b, v52
	v_mul_f32_e32 v211, 0xbfb8aa3b, v53
	v_exp_f32_e32 v208, v208
	v_exp_f32_e32 v209, v209
	v_exp_f32_e32 v210, v210
	v_exp_f32_e32 v211, v211
	v_add_f32_e32 v208, 1.0, v208
	v_add_f32_e32 v209, 1.0, v209
	v_add_f32_e32 v210, 1.0, v210
	v_add_f32_e32 v211, 1.0, v211
	v_rcp_f32_e32 v208, v208
	v_rcp_f32_e32 v209, v209
	v_rcp_f32_e32 v210, v210
	v_rcp_f32_e32 v211, v211
	v_mul_f32_e32 v50, v50, v208
	v_mul_f32_e32 v51, v51, v209
	v_mul_f32_e32 v52, v52, v210
	v_mul_f32_e32 v53, v53, v211
	v_mul_f32_e32 v50, v54, v50
	v_mul_f32_e32 v51, v55, v51
	v_mul_f32_e32 v52, v56, v52
	v_mul_f32_e32 v53, v57, v53
	v_cvt_pk_bf16_f32 v212, v50, v51
	v_cvt_pk_bf16_f32 v213, v52, v53
	ds_bpermute_b32 v212, v250, v212
	ds_bpermute_b32 v213, v250, v213
	s_waitcnt lgkmcnt(2)
;     __device__ __forceinline__ void operator()(const f32x4 (&acc)[2][2][4][2], const Unit& u, int wr, int wc, int fr, int fq) const {
;     ...
;         for (int n = 0; n < 2; ++n) {
;             if (n == 1) {
; #pragma unroll
;                 for (int bj = 0; bj < 2; ++bj) { const int col = bj * 2816 + ch0 + 4;
;                     w0[bj] = *(const f32x4*)(cw + col); w1[bj] = *(const f32x4*)(cw + 5632 + col); w2[bj] = *(const f32x4*)(cw + 11264 + col); bb[bj] = *(const f32x4*)(cb + col); } }
; #pragma unroll
;             for (int ai = 0; ai < 2; ++ai) { const int blk = ai * 2 + wr;
; #pragma unroll
;                 for (int m = 0; m < 4; ++m) { const int r = 128 * ai + 64 * wr + 16 * m + fr, t = tstart + r;
;                     const bool upok = t >= 1, dnok = (t + 1) < T, store_ok = (r >= vlo) && (r < vhi) && (t < T);
;                     f32x4 res[2];
; #pragma unroll
;                     for (int bj = 0; bj < 2; ++bj) { const f32x4 cur = acc[ai][bj][m][n];
;                         f32x4 su = cur, sd = cur;
;                         if (m > 0) { if (fr == 15) su = acc[ai][bj][m > 0 ? m - 1 : 0][n]; }
;                         if (m < 3) { if (fr == 0) sd = acc[ai][bj][m < 3 ? m + 1 : 3][n]; }
;                         f32x4 up, dn;
;                         up[0] = dpp_ror1(su[0]); up[1] = dpp_ror1(su[1]); up[2] = dpp_ror1(su[2]); up[3] = dpp_ror1(su[3]);
;                         dn[0] = dpp_ror15(sd[0]); dn[1] = dpp_ror15(sd[1]); dn[2] = dpp_ror15(sd[2]); dn[3] = dpp_ror15(sd[3]);
;                         if (m == 0) { f32x4 halo = zero4; if (blk > 0) halo = *(const PG8_LAS f32x4*)(xb + (((((blk - 1) * 2 + 1) * 4 + wc) * 4 + fq) * 16 + (bj * 2 + n) * 4)); if (fr == 0) up = halo; }
;                         if (m == 3) { f32x4 halo = zero4; if (blk < 3) halo = *(const PG8_LAS f32x4*)(xb + (((((blk + 1) * 2 + 0) * 4 + wc) * 4 + fq) * 16 + (bj * 2 + n) * 4)); if (fr == 15) dn = halo; }
;     ...
;                     if (store_ok) {
;                         float o[4];
; #pragma unroll
;                         for (int j = 0; j < 4; ++j) { const float gg = res[1][j]; o[j] = gg * __builtin_amdgcn_rcpf(1.f + __expf(-gg)) * res[0][j]; }
;                         u32x2 w; w.x = cvt_pk_bf16(o[0], o[1]); w.y = cvt_pk_bf16(o[2], o[3]);
;                         *(u32x2*)(ACT + (size_t)(seqrow + t) * 2816 + ch0 + 4 * n) = w; } } }
	v_add_u32_e32 v251, 0x16000, v247
	s_and_saveexec_b64 s[30:31], s[14:15]
	global_store_dwordx2 v251, v[218:219], s[10:11] offset:8
	s_mov_b64 exec, s[30:31]
	v_mul_f32_e32 v208, 0xbfb8aa3b, v42
	v_mul_f32_e32 v209, 0xbfb8aa3b, v43
	v_mul_f32_e32 v210, 0xbfb8aa3b, v44
	v_mul_f32_e32 v211, 0xbfb8aa3b, v45
	v_exp_f32_e32 v208, v208
	v_exp_f32_e32 v209, v209
	v_exp_f32_e32 v210, v210
	v_exp_f32_e32 v211, v211
	v_add_f32_e32 v208, 1.0, v208
	v_add_f32_e32 v209, 1.0, v209
	v_add_f32_e32 v210, 1.0, v210
	v_add_f32_e32 v211, 1.0, v211
	v_rcp_f32_e32 v208, v208
	v_rcp_f32_e32 v209, v209
	v_rcp_f32_e32 v210, v210
	v_rcp_f32_e32 v211, v211
	v_mul_f32_e32 v42, v42, v208
	v_mul_f32_e32 v43, v43, v209
	v_mul_f32_e32 v44, v44, v210
	v_mul_f32_e32 v45, v45, v211
	v_mul_f32_e32 v42, v46, v42
	v_mul_f32_e32 v43, v47, v43
	v_mul_f32_e32 v44, v48, v44
	v_mul_f32_e32 v45, v49, v45
	v_cvt_pk_bf16_f32 v218, v42, v43
	v_cvt_pk_bf16_f32 v219, v44, v45
	ds_bpermute_b32 v218, v250, v218
	ds_bpermute_b32 v219, v250, v219
	s_waitcnt lgkmcnt(2)
	v_add_u32_e32 v221, 0x2c000, v247
	s_and_saveexec_b64 s[30:31], s[16:17]
	global_store_dwordx2 v221, v[212:213], s[10:11] offset:8
	s_mov_b64 exec, s[30:31]
	s_waitcnt lgkmcnt(0)
	v_add_u32_e32 v251, 0x42000, v247
	s_and_saveexec_b64 s[30:31], s[18:19]
	global_store_dwordx2 v251, v[218:219], s[10:11] offset:8
	s_mov_b64 exec, s[30:31]
	ds_write_b64 v243, v[32:33]
	ds_write_b64 v243, v[24:25] offset:256
	ds_write_b64 v243, v[16:17] offset:512
	ds_write_b64 v243, v[8:9] offset:768
	v_cndmask_b32_e64 v170, v170, v198, s[6:7]
	v_cndmask_b32_e64 v171, v171, v199, s[6:7]
	v_pk_fma_f32 v[202:203], v[138:139], v[170:171], v[150:151]
	v_pk_fma_f32 v[30:31], v[30:31], v[142:143], v[202:203]
	v_pk_fma_f32 v[30:31], v[146:147], v[178:179], v[30:31]
	ds_read_b64 v[170:171], v244
	ds_read_b64 v[178:179], v243 offset:16
	ds_read_b64 v[198:199], v238 offset:3096
	v_pk_fma_f32 v[202:203], v[138:139], v[172:173], v[150:151]
	v_pk_fma_f32 v[22:23], v[22:23], v[142:143], v[202:203]
	v_pk_fma_f32 v[22:23], v[146:147], v[180:181], v[22:23]
	ds_read_b64 v[172:173], v244 offset:256
	ds_read_b64 v[180:181], v243 offset:272
	v_pk_fma_f32 v[202:203], v[138:139], v[174:175], v[150:151]
	v_pk_fma_f32 v[14:15], v[14:15], v[142:143], v[202:203]
	v_pk_fma_f32 v[14:15], v[146:147], v[194:195], v[14:15]
	ds_read_b64 v[174:175], v244 offset:512
	ds_read_b64 v[194:195], v243 offset:528
	v_cndmask_b32_e64 v196, v196, v200, s[4:5]
	v_cndmask_b32_e64 v197, v197, v201, s[4:5]
	v_pk_fma_f32 v[202:203], v[138:139], v[176:177], v[150:151]
	v_pk_fma_f32 v[6:7], v[6:7], v[142:143], v[202:203]
	v_pk_fma_f32 v[6:7], v[146:147], v[196:197], v[6:7]
	ds_read_b64 v[176:177], v244 offset:768
	ds_read_b64 v[196:197], v243 offset:784
	ds_read_b64 v[200:201], v246 offset:24
	ds_write_b64 v243, v[26:27]
	ds_write_b64 v243, v[18:19] offset:256
	ds_write_b64 v243, v[10:11] offset:512
	ds_write_b64 v243, v[2:3] offset:768
	s_waitcnt lgkmcnt(11)
	v_cndmask_b32_e64 v170, v170, v198, s[6:7]
	v_cndmask_b32_e64 v171, v171, v199, s[6:7]
	v_pk_fma_f32 v[202:203], v[140:141], v[170:171], v[152:153]
	v_pk_fma_f32 v[32:33], v[32:33], v[144:145], v[202:203]
	v_pk_fma_f32 v[32:33], v[148:149], v[178:179], v[32:33]
	ds_read_b64 v[170:171], v244
	ds_read_b64 v[178:179], v243 offset:16
	ds_read_b64 v[198:199], v238 offset:3120
	s_waitcnt lgkmcnt(12)
	v_pk_fma_f32 v[202:203], v[140:141], v[172:173], v[152:153]
	v_pk_fma_f32 v[24:25], v[24:25], v[144:145], v[202:203]
	v_pk_fma_f32 v[24:25], v[148:149], v[180:181], v[24:25]
	ds_read_b64 v[172:173], v244 offset:256
	ds_read_b64 v[180:181], v243 offset:272
	s_waitcnt lgkmcnt(12)
	v_pk_fma_f32 v[202:203], v[140:141], v[174:175], v[152:153]
	v_pk_fma_f32 v[16:17], v[16:17], v[144:145], v[202:203]
	v_pk_fma_f32 v[16:17], v[148:149], v[194:195], v[16:17]
	ds_read_b64 v[174:175], v244 offset:512
	ds_read_b64 v[194:195], v243 offset:528
	s_waitcnt lgkmcnt(11)
	v_cndmask_b32_e64 v196, v196, v200, s[4:5]
	v_cndmask_b32_e64 v197, v197, v201, s[4:5]
	v_pk_fma_f32 v[202:203], v[140:141], v[176:177], v[152:153]
	v_pk_fma_f32 v[8:9], v[8:9], v[144:145], v[202:203]
	v_pk_fma_f32 v[8:9], v[148:149], v[196:197], v[8:9]
	ds_read_b64 v[176:177], v244 offset:768
	ds_read_b64 v[196:197], v243 offset:784
	ds_read_b64 v[200:201], v246 offset:48
	ds_write_b64 v243, v[28:29]
	ds_write_b64 v243, v[20:21] offset:256
	ds_write_b64 v243, v[12:13] offset:512
	ds_write_b64 v243, v[4:5] offset:768
	s_waitcnt lgkmcnt(11)
	v_cndmask_b32_e64 v170, v170, v198, s[6:7]
	v_cndmask_b32_e64 v171, v171, v199, s[6:7]
	v_pk_fma_f32 v[202:203], v[154:155], v[170:171], v[166:167]
	v_pk_fma_f32 v[26:27], v[26:27], v[158:159], v[202:203]
	v_pk_fma_f32 v[26:27], v[162:163], v[178:179], v[26:27]
	ds_read_b64 v[170:171], v244
	ds_read_b64 v[178:179], v243 offset:16
	ds_read_b64 v[198:199], v238 offset:3128
	s_waitcnt lgkmcnt(12)
	v_pk_fma_f32 v[202:203], v[154:155], v[172:173], v[166:167]
	v_pk_fma_f32 v[18:19], v[18:19], v[158:159], v[202:203]
	v_pk_fma_f32 v[18:19], v[162:163], v[180:181], v[18:19]
	ds_read_b64 v[172:173], v244 offset:256
	ds_read_b64 v[180:181], v243 offset:272
	s_waitcnt lgkmcnt(12)
	v_pk_fma_f32 v[202:203], v[154:155], v[174:175], v[166:167]
	v_pk_fma_f32 v[10:11], v[10:11], v[158:159], v[202:203]
	v_pk_fma_f32 v[10:11], v[162:163], v[194:195], v[10:11]
	ds_read_b64 v[174:175], v244 offset:512
	ds_read_b64 v[194:195], v243 offset:528
	s_waitcnt lgkmcnt(11)
	v_cndmask_b32_e64 v196, v196, v200, s[4:5]
	v_cndmask_b32_e64 v197, v197, v201, s[4:5]
	v_pk_fma_f32 v[202:203], v[154:155], v[176:177], v[166:167]
	v_pk_fma_f32 v[2:3], v[2:3], v[158:159], v[202:203]
	v_pk_fma_f32 v[2:3], v[162:163], v[196:197], v[2:3]
	ds_read_b64 v[176:177], v244 offset:768
	ds_read_b64 v[196:197], v243 offset:784
	ds_read_b64 v[200:201], v246 offset:56
	s_waitcnt lgkmcnt(7)
; #define PG8_LAS __attribute__((address_space(3)))
; __device__ __forceinline__ unsigned cvt_pk_bf16(float lo, float hi) { unsigned r; asm volatile("v_cvt_pk_bf16_f32 %0, %1, %2" : "=v"(r) : "v"(lo), "v"(hi)); return r; }
;     __device__ __forceinline__ void operator()(const f32x4 (&acc)[2][2][4][2], const Unit& u, int wr, int wc, int fr, int fq) const {
;     ...
;                 for (int m = 0; m < 4; ++m) { const int r = 128 * ai + 64 * wr + 16 * m + fr, t = tstart + r;
;                     const bool upok = t >= 1, dnok = (t + 1) < T, store_ok = (r >= vlo) && (r < vhi) && (t < T);
;                     f32x4 res[2];
; #pragma unroll
;                     for (int bj = 0; bj < 2; ++bj) { const f32x4 cur = acc[ai][bj][m][n];
;                         f32x4 su = cur, sd = cur;
;                         if (m > 0) { if (fr == 15) su = acc[ai][bj][m > 0 ? m - 1 : 0][n]; }
;                         if (m < 3) { if (fr == 0) sd = acc[ai][bj][m < 3 ? m + 1 : 3][n]; }
;                         f32x4 up, dn;
;                         up[0] = dpp_ror1(su[0]); up[1] = dpp_ror1(su[1]); up[2] = dpp_ror1(su[2]); up[3] = dpp_ror1(su[3]);
;                         dn[0] = dpp_ror15(sd[0]); dn[1] = dpp_ror15(sd[1]); dn[2] = dpp_ror15(sd[2]); dn[3] = dpp_ror15(sd[3]);
;                         if (m == 0) { f32x4 halo = zero4; if (blk > 0) halo = *(const PG8_LAS f32x4*)(xb + (((((blk - 1) * 2 + 1) * 4 + wc) * 4 + fq) * 16 + (bj * 2 + n) * 4)); if (fr == 0) up = halo; }
;                         if (m == 3) { f32x4 halo = zero4; if (blk < 3) halo = *(const PG8_LAS f32x4*)(xb + (((((blk + 1) * 2 + 0) * 4 + wc) * 4 + fq) * 16 + (bj * 2 + n) * 4)); if (fr == 15) dn = halo; }
;                         if (edge) { if (!upok) up = zero4; if (!dnok) dn = zero4; }
;                         res[bj] = bb[bj] + w0[bj] * up + w1[bj] * cur + w2[bj] * dn; }
;                     if (store_ok) {
;                         float o[4];
; #pragma unroll
;                         for (int j = 0; j < 4; ++j) { const float gg = res[1][j]; o[j] = gg * __builtin_amdgcn_rcpf(1.f + __expf(-gg)) * res[0][j]; }
;                         u32x2 w; w.x = cvt_pk_bf16(o[0], o[1]); w.y = cvt_pk_bf16(o[2], o[3]);
;                         *(u32x2*)(ACT + (size_t)(seqrow + t) * 2816 + ch0 + 4 * n) = w; } } }
	v_cndmask_b32_e64 v170, v170, v198, s[6:7]
	v_cndmask_b32_e64 v171, v171, v199, s[6:7]
	v_pk_fma_f32 v[202:203], v[156:157], v[170:171], v[168:169]
	v_pk_fma_f32 v[28:29], v[28:29], v[160:161], v[202:203]
	v_pk_fma_f32 v[28:29], v[164:165], v[178:179], v[28:29]
	s_waitcnt lgkmcnt(5)
	v_pk_fma_f32 v[202:203], v[156:157], v[172:173], v[168:169]
	v_pk_fma_f32 v[20:21], v[20:21], v[160:161], v[202:203]
	v_pk_fma_f32 v[20:21], v[164:165], v[180:181], v[20:21]
	s_waitcnt lgkmcnt(3)
	v_pk_fma_f32 v[202:203], v[156:157], v[174:175], v[168:169]
	v_pk_fma_f32 v[12:13], v[12:13], v[160:161], v[202:203]
	v_pk_fma_f32 v[12:13], v[164:165], v[194:195], v[12:13]
	s_waitcnt lgkmcnt(0)
	v_cndmask_b32_e64 v196, v196, v200, s[4:5]
	v_cndmask_b32_e64 v197, v197, v201, s[4:5]
	v_pk_fma_f32 v[202:203], v[156:157], v[176:177], v[168:169]
	v_pk_fma_f32 v[4:5], v[4:5], v[160:161], v[202:203]
	v_pk_fma_f32 v[4:5], v[164:165], v[196:197], v[4:5]
	v_mul_f32_e32 v208, 0xbfb8aa3b, v26
	v_mul_f32_e32 v209, 0xbfb8aa3b, v27
	v_mul_f32_e32 v210, 0xbfb8aa3b, v28
	v_mul_f32_e32 v211, 0xbfb8aa3b, v29
	v_exp_f32_e32 v208, v208
	v_exp_f32_e32 v209, v209
	v_exp_f32_e32 v210, v210
	v_exp_f32_e32 v211, v211
	v_add_f32_e32 v208, 1.0, v208
	v_add_f32_e32 v209, 1.0, v209
	v_add_f32_e32 v210, 1.0, v210
	v_add_f32_e32 v211, 1.0, v211
	v_rcp_f32_e32 v208, v208
	v_rcp_f32_e32 v209, v209
	v_rcp_f32_e32 v210, v210
	v_rcp_f32_e32 v211, v211
	v_mul_f32_e32 v26, v26, v208
	v_mul_f32_e32 v27, v27, v209
	v_mul_f32_e32 v28, v28, v210
	v_mul_f32_e32 v29, v29, v211
	v_mul_f32_e32 v26, v30, v26
	v_mul_f32_e32 v27, v31, v27
	v_mul_f32_e32 v28, v32, v28
	v_mul_f32_e32 v29, v33, v29
	v_cvt_pk_bf16_f32 v212, v26, v27
	v_cvt_pk_bf16_f32 v213, v28, v29
	ds_bpermute_b32 v212, v250, v212
	ds_bpermute_b32 v213, v250, v213
	v_mul_f32_e32 v208, 0xbfb8aa3b, v18
	v_mul_f32_e32 v209, 0xbfb8aa3b, v19
	v_mul_f32_e32 v210, 0xbfb8aa3b, v20
	v_mul_f32_e32 v211, 0xbfb8aa3b, v21
	v_exp_f32_e32 v208, v208
	v_exp_f32_e32 v209, v209
	v_exp_f32_e32 v210, v210
	v_exp_f32_e32 v211, v211
	v_add_f32_e32 v208, 1.0, v208
	v_add_f32_e32 v209, 1.0, v209
	v_add_f32_e32 v210, 1.0, v210
	v_add_f32_e32 v211, 1.0, v211
	v_rcp_f32_e32 v208, v208
	v_rcp_f32_e32 v209, v209
	v_rcp_f32_e32 v210, v210
	v_rcp_f32_e32 v211, v211
	v_mul_f32_e32 v18, v18, v208
	v_mul_f32_e32 v19, v19, v209
	v_mul_f32_e32 v20, v20, v210
	v_mul_f32_e32 v21, v21, v211
	v_mul_f32_e32 v18, v22, v18
	v_mul_f32_e32 v19, v23, v19
	v_mul_f32_e32 v20, v24, v20
	v_mul_f32_e32 v21, v25, v21
	v_cvt_pk_bf16_f32 v218, v18, v19
	v_cvt_pk_bf16_f32 v219, v20, v21
	ds_bpermute_b32 v218, v250, v218
	ds_bpermute_b32 v219, v250, v219
	s_waitcnt lgkmcnt(2)
	v_add_u32_e32 v221, 0xb0000, v247
	s_and_saveexec_b64 s[30:31], s[20:21]
	global_store_dwordx2 v221, v[212:213], s[10:11] offset:8
	s_mov_b64 exec, s[30:31]
	v_mul_f32_e32 v208, 0xbfb8aa3b, v10
	v_mul_f32_e32 v209, 0xbfb8aa3b, v11
	v_mul_f32_e32 v210, 0xbfb8aa3b, v12
	v_mul_f32_e32 v211, 0xbfb8aa3b, v13
	v_exp_f32_e32 v208, v208
	v_exp_f32_e32 v209, v209
	v_exp_f32_e32 v210, v210
	v_exp_f32_e32 v211, v211
	v_add_f32_e32 v208, 1.0, v208
	v_add_f32_e32 v209, 1.0, v209
	v_add_f32_e32 v210, 1.0, v210
	v_add_f32_e32 v211, 1.0, v211
	v_rcp_f32_e32 v208, v208
	v_rcp_f32_e32 v209, v209
	v_rcp_f32_e32 v210, v210
	v_rcp_f32_e32 v211, v211
	v_mul_f32_e32 v10, v10, v208
	v_mul_f32_e32 v11, v11, v209
	v_mul_f32_e32 v12, v12, v210
	v_mul_f32_e32 v13, v13, v211
	v_mul_f32_e32 v10, v14, v10
	v_mul_f32_e32 v11, v15, v11
	v_mul_f32_e32 v12, v16, v12
	v_mul_f32_e32 v13, v17, v13
	v_cvt_pk_bf16_f32 v212, v10, v11
	v_cvt_pk_bf16_f32 v213, v12, v13
	ds_bpermute_b32 v212, v250, v212
	ds_bpermute_b32 v213, v250, v213
	s_waitcnt lgkmcnt(2)
	v_add_u32_e32 v251, 0xc6000, v247
	s_and_saveexec_b64 s[30:31], s[22:23]
	global_store_dwordx2 v251, v[218:219], s[10:11] offset:8
	s_mov_b64 exec, s[30:31]
	v_mul_f32_e32 v208, 0xbfb8aa3b, v2
	v_mul_f32_e32 v209, 0xbfb8aa3b, v3
	v_mul_f32_e32 v210, 0xbfb8aa3b, v4
	v_mul_f32_e32 v211, 0xbfb8aa3b, v5
	v_exp_f32_e32 v208, v208
	v_exp_f32_e32 v209, v209
	v_exp_f32_e32 v210, v210
	v_exp_f32_e32 v211, v211
	v_add_f32_e32 v208, 1.0, v208
	v_add_f32_e32 v209, 1.0, v209
	v_add_f32_e32 v210, 1.0, v210
	v_add_f32_e32 v211, 1.0, v211
	v_rcp_f32_e32 v208, v208
	v_rcp_f32_e32 v209, v209
	v_rcp_f32_e32 v210, v210
	v_rcp_f32_e32 v211, v211
	v_mul_f32_e32 v2, v2, v208
	v_mul_f32_e32 v3, v3, v209
	v_mul_f32_e32 v4, v4, v210
	v_mul_f32_e32 v5, v5, v211
	v_mul_f32_e32 v2, v6, v2
	v_mul_f32_e32 v3, v7, v3
	v_mul_f32_e32 v4, v8, v4
	v_mul_f32_e32 v5, v9, v5
	v_cvt_pk_bf16_f32 v218, v2, v3
	v_cvt_pk_bf16_f32 v219, v4, v5
	ds_bpermute_b32 v218, v250, v218
	ds_bpermute_b32 v219, v250, v219
	s_waitcnt lgkmcnt(2)
	v_add_u32_e32 v221, 0xdc000, v247
	s_and_saveexec_b64 s[30:31], s[24:25]
	global_store_dwordx2 v221, v[212:213], s[10:11] offset:8
	s_mov_b64 exec, s[30:31]
	s_waitcnt lgkmcnt(0)
	v_add_u32_e32 v251, 0xf2000, v247
	s_and_saveexec_b64 s[30:31], s[26:27]
	global_store_dwordx2 v251, v[218:219], s[10:11] offset:8
	s_mov_b64 exec, s[30:31]
	s_branch .Lec_done
; #define PG8_LAS __attribute__((address_space(3)))
; __device__ __forceinline__ float dpp_ror1(float v) { return __builtin_bit_cast(float, __builtin_amdgcn_update_dpp(0, __builtin_bit_cast(int, v), 0x121, 0xf, 0xf, false)); }
; __device__ __forceinline__ float dpp_ror15(float v) { return __builtin_bit_cast(float, __builtin_amdgcn_update_dpp(0, __builtin_bit_cast(int, v), 0x12F, 0xf, 0xf, false)); }
;     __device__ __forceinline__ void operator()(const f32x4 (&acc)[2][2][4][2], const Unit& u, int wr, int wc, int fr, int fq) const {
;     ...
;         if (u.pm < 132) { const int b = u.pm / 33, i = u.pm - b * 33; seqrow = b * 8192; tstart = 254 * i - 1; T = 8192; vlo = 1; vhi = 255; }
;         else { seqrow = 32768 + (u.pm - 132) * 256; tstart = 0; T = 256; vlo = 0; vhi = 256; }
;         const bool edge = (tstart <= 0) || (tstart + 256 >= T);
;     ...
;                 for (int m = 0; m < 4; ++m) { const int r = 128 * ai + 64 * wr + 16 * m + fr, t = tstart + r;
;                     const bool upok = t >= 1, dnok = (t + 1) < T, store_ok = (r >= vlo) && (r < vhi) && (t < T);
;                     f32x4 res[2];
; #pragma unroll
;                     for (int bj = 0; bj < 2; ++bj) { const f32x4 cur = acc[ai][bj][m][n];
;                         f32x4 su = cur, sd = cur;
;                         if (m > 0) { if (fr == 15) su = acc[ai][bj][m > 0 ? m - 1 : 0][n]; }
;                         if (m < 3) { if (fr == 0) sd = acc[ai][bj][m < 3 ? m + 1 : 3][n]; }
;                         f32x4 up, dn;
;                         up[0] = dpp_ror1(su[0]); up[1] = dpp_ror1(su[1]); up[2] = dpp_ror1(su[2]); up[3] = dpp_ror1(su[3]);
;                         dn[0] = dpp_ror15(sd[0]); dn[1] = dpp_ror15(sd[1]); dn[2] = dpp_ror15(sd[2]); dn[3] = dpp_ror15(sd[3]);
;                         if (m == 0) { f32x4 halo = zero4; if (blk > 0) halo = *(const PG8_LAS f32x4*)(xb + (((((blk - 1) * 2 + 1) * 4 + wc) * 4 + fq) * 16 + (bj * 2 + n) * 4)); if (fr == 0) up = halo; }
;                         if (m == 3) { f32x4 halo = zero4; if (blk < 3) halo = *(const PG8_LAS f32x4*)(xb + (((((blk + 1) * 2 + 0) * 4 + wc) * 4 + fq) * 16 + (bj * 2 + n) * 4)); if (fr == 15) dn = halo; }
;                         if (edge) { if (!upok) up = zero4; if (!dnok) dn = zero4; }
.Lec_edge:
	v_mbcnt_lo_u32_b32 v251, -1, 0
	v_mbcnt_hi_u32_b32 v251, -1, v251
	v_and_b32_e32 v220, 3, v251
	v_lshrrev_b32_e32 v251, 2, v251
	v_lshl_add_u32 v250, v220, 4, v251
	v_lshlrev_b32_e32 v250, 2, v250
	v_sub_u32_e32 v221, v227, v226
	v_add_u32_e32 v251, v221, v251
	v_and_b32_e32 v221, 0x60, v229
	v_lshl_add_u32 v221, v220, 3, v221
	v_lshl_or_b32 v221, s2, 7, v221
	v_lshlrev_b32_e32 v221, 1, v221
	s_add_i32 s0, s78, s48
	s_mulk_i32 s0, 0x1600
	v_add_u32_e32 v221, s0, v221
	v_mad_u32_u24 v247, v251, s29, v221
	v_add_u32_e32 v220, 0, v251
	v_cmp_le_i32_e64 s[12:13], s54, v220
	v_cmp_gt_i32_e32 vcc, s55, v220
	s_and_b64 s[12:13], s[12:13], vcc
	v_add_u32_e32 v220, s48, v220
	v_cmp_gt_i32_e32 vcc, s93, v220
	s_and_b64 s[12:13], s[12:13], vcc
	v_add_u32_e32 v220, 16, v251
	v_cmp_le_i32_e64 s[14:15], s54, v220
	v_cmp_gt_i32_e32 vcc, s55, v220
	s_and_b64 s[14:15], s[14:15], vcc
	v_add_u32_e32 v220, s48, v220
	v_cmp_gt_i32_e32 vcc, s93, v220
	s_and_b64 s[14:15], s[14:15], vcc
	v_add_u32_e32 v220, 32, v251
	v_cmp_le_i32_e64 s[16:17], s54, v220
	v_cmp_gt_i32_e32 vcc, s55, v220
	s_and_b64 s[16:17], s[16:17], vcc
	v_add_u32_e32 v220, s48, v220
	v_cmp_gt_i32_e32 vcc, s93, v220
	s_and_b64 s[16:17], s[16:17], vcc
	v_add_u32_e32 v220, 48, v251
	v_cmp_le_i32_e64 s[18:19], s54, v220
	v_cmp_gt_i32_e32 vcc, s55, v220
	s_and_b64 s[18:19], s[18:19], vcc
	v_add_u32_e32 v220, s48, v220
	v_cmp_gt_i32_e32 vcc, s93, v220
	s_and_b64 s[18:19], s[18:19], vcc
	v_add_u32_e32 v220, 128, v251
	v_cmp_le_i32_e64 s[20:21], s54, v220
	v_cmp_gt_i32_e32 vcc, s55, v220
	s_and_b64 s[20:21], s[20:21], vcc
	v_add_u32_e32 v220, s48, v220
	v_cmp_gt_i32_e32 vcc, s93, v220
	s_and_b64 s[20:21], s[20:21], vcc
	v_add_u32_e32 v220, 144, v251
	v_cmp_le_i32_e64 s[22:23], s54, v220
	v_cmp_gt_i32_e32 vcc, s55, v220
	s_and_b64 s[22:23], s[22:23], vcc
	v_add_u32_e32 v220, s48, v220
	v_cmp_gt_i32_e32 vcc, s93, v220
	s_and_b64 s[22:23], s[22:23], vcc
	v_add_u32_e32 v220, 160, v251
	v_cmp_le_i32_e64 s[24:25], s54, v220
	v_cmp_gt_i32_e32 vcc, s55, v220
	s_and_b64 s[24:25], s[24:25], vcc
	v_add_u32_e32 v220, s48, v220
	v_cmp_gt_i32_e32 vcc, s93, v220
	s_and_b64 s[24:25], s[24:25], vcc
	v_add_u32_e32 v220, 176, v251
	v_cmp_le_i32_e64 s[26:27], s54, v220
	v_cmp_gt_i32_e32 vcc, s55, v220
	s_and_b64 s[26:27], s[26:27], vcc
	v_add_u32_e32 v220, s48, v220
	v_cmp_gt_i32_e32 vcc, s93, v220
	s_and_b64 s[26:27], s[26:27], vcc
	ds_write_b64 v243, v[166:167]
	ds_write_b64 v243, v[158:159] offset:256
	ds_write_b64 v243, v[150:151] offset:512
	ds_write_b64 v243, v[142:143] offset:768
	ds_read_b64 v[170:171], v244
	ds_read_b64 v[178:179], v243 offset:16
	ds_read_b64 v[198:199], v245
	ds_read_b64 v[172:173], v244 offset:256
	ds_read_b64 v[180:181], v243 offset:272
	ds_read_b64 v[174:175], v244 offset:512
	ds_read_b64 v[194:195], v243 offset:528
	ds_read_b64 v[176:177], v244 offset:768
	ds_read_b64 v[196:197], v243 offset:784
	ds_read_b64 v[200:201], v238 offset:2048
	s_waitcnt vmcnt(0)
	ds_write_b64 v243, v[168:169]
	ds_write_b64 v243, v[160:161] offset:256
	ds_write_b64 v243, v[152:153] offset:512
	ds_write_b64 v243, v[144:145] offset:768
	s_waitcnt lgkmcnt(11)
	v_cndmask_b32_e64 v170, v170, v198, s[6:7]
	v_cndmask_b32_e64 v171, v171, v199, s[6:7]
	v_add_u32_e32 v220, s48, v227
	v_cmp_lt_i32_e32 vcc, 0, v220
	s_nop 1
	v_cndmask_b32_e32 v170, 0, v170, vcc
	v_cndmask_b32_e32 v171, 0, v171, vcc
	v_cmp_gt_i32_e32 vcc, s28, v220
	s_nop 1
	v_cndmask_b32_e32 v178, 0, v178, vcc
	v_cndmask_b32_e32 v179, 0, v179, vcc
	v_pk_fma_f32 v[202:203], v[106:107], v[170:171], v[118:119]
	v_pk_fma_f32 v[166:167], v[166:167], v[110:111], v[202:203]
	v_pk_fma_f32 v[166:167], v[114:115], v[178:179], v[166:167]
	ds_read_b64 v[170:171], v244
	ds_read_b64 v[178:179], v243 offset:16
	ds_read_b64 v[198:199], v245 offset:8
	s_waitcnt lgkmcnt(12)
	v_add_u32_e32 v220, s48, v231
	v_cmp_lt_i32_e32 vcc, 0, v220
	s_nop 1
	v_cndmask_b32_e32 v172, 0, v172, vcc
	v_cndmask_b32_e32 v173, 0, v173, vcc
	v_cmp_gt_i32_e32 vcc, s28, v220
	s_nop 1
	v_cndmask_b32_e32 v180, 0, v180, vcc
	v_cndmask_b32_e32 v181, 0, v181, vcc
	v_pk_fma_f32 v[202:203], v[106:107], v[172:173], v[118:119]
	v_pk_fma_f32 v[158:159], v[158:159], v[110:111], v[202:203]
	v_pk_fma_f32 v[158:159], v[114:115], v[180:181], v[158:159]
	ds_read_b64 v[172:173], v244 offset:256
	ds_read_b64 v[180:181], v243 offset:272
	s_waitcnt lgkmcnt(12)
	v_add_u32_e32 v220, s48, v232
	v_cmp_lt_i32_e32 vcc, 0, v220
	s_nop 1
	v_cndmask_b32_e32 v174, 0, v174, vcc
	v_cndmask_b32_e32 v175, 0, v175, vcc
	v_cmp_gt_i32_e32 vcc, s28, v220
	s_nop 1
	v_cndmask_b32_e32 v194, 0, v194, vcc
	v_cndmask_b32_e32 v195, 0, v195, vcc
	v_pk_fma_f32 v[202:203], v[106:107], v[174:175], v[118:119]
	v_pk_fma_f32 v[150:151], v[150:151], v[110:111], v[202:203]
	v_pk_fma_f32 v[150:151], v[114:115], v[194:195], v[150:151]
	ds_read_b64 v[174:175], v244 offset:512
	ds_read_b64 v[194:195], v243 offset:528
	s_waitcnt lgkmcnt(11)
	v_cndmask_b32_e64 v196, v196, v200, s[4:5]
	v_cndmask_b32_e64 v197, v197, v201, s[4:5]
	v_add_u32_e32 v220, s48, v233
	v_cmp_lt_i32_e32 vcc, 0, v220
	s_nop 1
	v_cndmask_b32_e32 v176, 0, v176, vcc
	v_cndmask_b32_e32 v177, 0, v177, vcc
	v_cmp_gt_i32_e32 vcc, s28, v220
	s_nop 1
	v_cndmask_b32_e32 v196, 0, v196, vcc
	v_cndmask_b32_e32 v197, 0, v197, vcc
	v_pk_fma_f32 v[202:203], v[106:107], v[176:177], v[118:119]
	v_pk_fma_f32 v[142:143], v[142:143], v[110:111], v[202:203]
	v_pk_fma_f32 v[142:143], v[114:115], v[196:197], v[142:143]
	ds_read_b64 v[176:177], v244 offset:768
	ds_read_b64 v[196:197], v243 offset:784
	ds_read_b64 v[200:201], v238 offset:2056
	ds_write_b64 v243, v[162:163]
	ds_write_b64 v243, v[154:155] offset:256
	ds_write_b64 v243, v[146:147] offset:512
	ds_write_b64 v243, v[138:139] offset:768
	s_waitcnt lgkmcnt(11)
; #define PG8_LAS __attribute__((address_space(3)))
; __device__ __forceinline__ float dpp_ror1(float v) { return __builtin_bit_cast(float, __builtin_amdgcn_update_dpp(0, __builtin_bit_cast(int, v), 0x121, 0xf, 0xf, false)); }
; __device__ __forceinline__ float dpp_ror15(float v) { return __builtin_bit_cast(float, __builtin_amdgcn_update_dpp(0, __builtin_bit_cast(int, v), 0x12F, 0xf, 0xf, false)); }
;     __device__ __forceinline__ void operator()(const f32x4 (&acc)[2][2][4][2], const Unit& u, int wr, int wc, int fr, int fq) const {
;     ...
;             for (int ai = 0; ai < 2; ++ai) { const int blk = ai * 2 + wr;
; #pragma unroll
;                 for (int m = 0; m < 4; ++m) { const int r = 128 * ai + 64 * wr + 16 * m + fr, t = tstart + r;
;                     const bool upok = t >= 1, dnok = (t + 1) < T, store_ok = (r >= vlo) && (r < vhi) && (t < T);
;                     f32x4 res[2];
; #pragma unroll
;                     for (int bj = 0; bj < 2; ++bj) { const f32x4 cur = acc[ai][bj][m][n];
;                         f32x4 su = cur, sd = cur;
;                         if (m > 0) { if (fr == 15) su = acc[ai][bj][m > 0 ? m - 1 : 0][n]; }
;                         if (m < 3) { if (fr == 0) sd = acc[ai][bj][m < 3 ? m + 1 : 3][n]; }
;                         f32x4 up, dn;
;                         up[0] = dpp_ror1(su[0]); up[1] = dpp_ror1(su[1]); up[2] = dpp_ror1(su[2]); up[3] = dpp_ror1(su[3]);
;                         dn[0] = dpp_ror15(sd[0]); dn[1] = dpp_ror15(sd[1]); dn[2] = dpp_ror15(sd[2]); dn[3] = dpp_ror15(sd[3]);
;                         if (m == 0) { f32x4 halo = zero4; if (blk > 0) halo = *(const PG8_LAS f32x4*)(xb + (((((blk - 1) * 2 + 1) * 4 + wc) * 4 + fq) * 16 + (bj * 2 + n) * 4)); if (fr == 0) up = halo; }
;                         if (m == 3) { f32x4 halo = zero4; if (blk < 3) halo = *(const PG8_LAS f32x4*)(xb + (((((blk + 1) * 2 + 0) * 4 + wc) * 4 + fq) * 16 + (bj * 2 + n) * 4)); if (fr == 15) dn = halo; }
;                         if (edge) { if (!upok) up = zero4; if (!dnok) dn = zero4; }
;                         res[bj] = bb[bj] + w0[bj] * up + w1[bj] * cur + w2[bj] * dn; }
	v_cndmask_b32_e64 v170, v170, v198, s[6:7]
	v_cndmask_b32_e64 v171, v171, v199, s[6:7]
	v_add_u32_e32 v220, s48, v227
	v_cmp_lt_i32_e32 vcc, 0, v220
	s_nop 1
	v_cndmask_b32_e32 v170, 0, v170, vcc
	v_cndmask_b32_e32 v171, 0, v171, vcc
	v_cmp_gt_i32_e32 vcc, s28, v220
	s_nop 1
	v_cndmask_b32_e32 v178, 0, v178, vcc
	v_cndmask_b32_e32 v179, 0, v179, vcc
	v_pk_fma_f32 v[202:203], v[108:109], v[170:171], v[120:121]
	v_pk_fma_f32 v[168:169], v[168:169], v[112:113], v[202:203]
	v_pk_fma_f32 v[168:169], v[116:117], v[178:179], v[168:169]
	ds_read_b64 v[170:171], v244
	ds_read_b64 v[178:179], v243 offset:16
	ds_read_b64 v[198:199], v245 offset:32
	s_waitcnt lgkmcnt(12)
	v_add_u32_e32 v220, s48, v231
	v_cmp_lt_i32_e32 vcc, 0, v220
	s_nop 1
	v_cndmask_b32_e32 v172, 0, v172, vcc
	v_cndmask_b32_e32 v173, 0, v173, vcc
	v_cmp_gt_i32_e32 vcc, s28, v220
	s_nop 1
	v_cndmask_b32_e32 v180, 0, v180, vcc
	v_cndmask_b32_e32 v181, 0, v181, vcc
	v_pk_fma_f32 v[202:203], v[108:109], v[172:173], v[120:121]
	v_pk_fma_f32 v[160:161], v[160:161], v[112:113], v[202:203]
	v_pk_fma_f32 v[160:161], v[116:117], v[180:181], v[160:161]
	ds_read_b64 v[172:173], v244 offset:256
	ds_read_b64 v[180:181], v243 offset:272
	s_waitcnt lgkmcnt(12)
	v_add_u32_e32 v220, s48, v232
	v_cmp_lt_i32_e32 vcc, 0, v220
	s_nop 1
	v_cndmask_b32_e32 v174, 0, v174, vcc
	v_cndmask_b32_e32 v175, 0, v175, vcc
	v_cmp_gt_i32_e32 vcc, s28, v220
	s_nop 1
	v_cndmask_b32_e32 v194, 0, v194, vcc
	v_cndmask_b32_e32 v195, 0, v195, vcc
	v_pk_fma_f32 v[202:203], v[108:109], v[174:175], v[120:121]
	v_pk_fma_f32 v[152:153], v[152:153], v[112:113], v[202:203]
	v_pk_fma_f32 v[152:153], v[116:117], v[194:195], v[152:153]
	ds_read_b64 v[174:175], v244 offset:512
	ds_read_b64 v[194:195], v243 offset:528
	s_waitcnt lgkmcnt(11)
	v_cndmask_b32_e64 v196, v196, v200, s[4:5]
	v_cndmask_b32_e64 v197, v197, v201, s[4:5]
	v_add_u32_e32 v220, s48, v233
	v_cmp_lt_i32_e32 vcc, 0, v220
	s_nop 1
	v_cndmask_b32_e32 v176, 0, v176, vcc
	v_cndmask_b32_e32 v177, 0, v177, vcc
	v_cmp_gt_i32_e32 vcc, s28, v220
	s_nop 1
	v_cndmask_b32_e32 v196, 0, v196, vcc
	v_cndmask_b32_e32 v197, 0, v197, vcc
	v_pk_fma_f32 v[202:203], v[108:109], v[176:177], v[120:121]
	v_pk_fma_f32 v[144:145], v[144:145], v[112:113], v[202:203]
	v_pk_fma_f32 v[144:145], v[116:117], v[196:197], v[144:145]
	ds_read_b64 v[176:177], v244 offset:768
	ds_read_b64 v[196:197], v243 offset:784
	ds_read_b64 v[200:201], v238 offset:2080
	ds_write_b64 v243, v[164:165]
	ds_write_b64 v243, v[156:157] offset:256
	ds_write_b64 v243, v[148:149] offset:512
	ds_write_b64 v243, v[140:141] offset:768
	s_waitcnt lgkmcnt(11)
	v_cndmask_b32_e64 v170, v170, v198, s[6:7]
	v_cndmask_b32_e64 v171, v171, v199, s[6:7]
	v_add_u32_e32 v220, s48, v227
	v_cmp_lt_i32_e32 vcc, 0, v220
	s_nop 1
	v_cndmask_b32_e32 v170, 0, v170, vcc
	v_cndmask_b32_e32 v171, 0, v171, vcc
	v_cmp_gt_i32_e32 vcc, s28, v220
	s_nop 1
	v_cndmask_b32_e32 v178, 0, v178, vcc
	v_cndmask_b32_e32 v179, 0, v179, vcc
	v_pk_fma_f32 v[202:203], v[122:123], v[170:171], v[134:135]
	v_pk_fma_f32 v[162:163], v[162:163], v[126:127], v[202:203]
	v_pk_fma_f32 v[162:163], v[130:131], v[178:179], v[162:163]
	ds_read_b64 v[170:171], v244
	ds_read_b64 v[178:179], v243 offset:16
	ds_read_b64 v[198:199], v245 offset:40
	s_waitcnt lgkmcnt(12)
	v_add_u32_e32 v220, s48, v231
	v_cmp_lt_i32_e32 vcc, 0, v220
	s_nop 1
	v_cndmask_b32_e32 v172, 0, v172, vcc
	v_cndmask_b32_e32 v173, 0, v173, vcc
	v_cmp_gt_i32_e32 vcc, s28, v220
	s_nop 1
	v_cndmask_b32_e32 v180, 0, v180, vcc
	v_cndmask_b32_e32 v181, 0, v181, vcc
	v_pk_fma_f32 v[202:203], v[122:123], v[172:173], v[134:135]
	v_pk_fma_f32 v[154:155], v[154:155], v[126:127], v[202:203]
	v_pk_fma_f32 v[154:155], v[130:131], v[180:181], v[154:155]
	ds_read_b64 v[172:173], v244 offset:256
	ds_read_b64 v[180:181], v243 offset:272
	s_waitcnt lgkmcnt(12)
	v_add_u32_e32 v220, s48, v232
	v_cmp_lt_i32_e32 vcc, 0, v220
	s_nop 1
	v_cndmask_b32_e32 v174, 0, v174, vcc
	v_cndmask_b32_e32 v175, 0, v175, vcc
	v_cmp_gt_i32_e32 vcc, s28, v220
	s_nop 1
	v_cndmask_b32_e32 v194, 0, v194, vcc
	v_cndmask_b32_e32 v195, 0, v195, vcc
	v_pk_fma_f32 v[202:203], v[122:123], v[174:175], v[134:135]
	v_pk_fma_f32 v[146:147], v[146:147], v[126:127], v[202:203]
	v_pk_fma_f32 v[146:147], v[130:131], v[194:195], v[146:147]
	ds_read_b64 v[174:175], v244 offset:512
	ds_read_b64 v[194:195], v243 offset:528
	s_waitcnt lgkmcnt(11)
	v_cndmask_b32_e64 v196, v196, v200, s[4:5]
	v_cndmask_b32_e64 v197, v197, v201, s[4:5]
	v_add_u32_e32 v220, s48, v233
	v_cmp_lt_i32_e32 vcc, 0, v220
	s_nop 1
	v_cndmask_b32_e32 v176, 0, v176, vcc
	v_cndmask_b32_e32 v177, 0, v177, vcc
	v_cmp_gt_i32_e32 vcc, s28, v220
	s_nop 1
	v_cndmask_b32_e32 v196, 0, v196, vcc
	v_cndmask_b32_e32 v197, 0, v197, vcc
	v_pk_fma_f32 v[202:203], v[122:123], v[176:177], v[134:135]
	v_pk_fma_f32 v[138:139], v[138:139], v[126:127], v[202:203]
	v_pk_fma_f32 v[138:139], v[130:131], v[196:197], v[138:139]
	ds_read_b64 v[176:177], v244 offset:768
	ds_read_b64 v[196:197], v243 offset:784
	ds_read_b64 v[200:201], v238 offset:2088
	ds_write_b64 v243, v[102:103]
	ds_write_b64 v243, v[94:95] offset:256
	ds_write_b64 v243, v[86:87] offset:512
	ds_write_b64 v243, v[78:79] offset:768
	s_waitcnt lgkmcnt(11)
	v_cndmask_b32_e64 v170, v170, v198, s[6:7]
	v_cndmask_b32_e64 v171, v171, v199, s[6:7]
	v_add_u32_e32 v220, s48, v227
	v_cmp_lt_i32_e32 vcc, 0, v220
	s_nop 1
	v_cndmask_b32_e32 v170, 0, v170, vcc
	v_cndmask_b32_e32 v171, 0, v171, vcc
	v_cmp_gt_i32_e32 vcc, s28, v220
	s_nop 1
	v_cndmask_b32_e32 v178, 0, v178, vcc
	v_cndmask_b32_e32 v179, 0, v179, vcc
	v_pk_fma_f32 v[202:203], v[124:125], v[170:171], v[136:137]
	v_pk_fma_f32 v[164:165], v[164:165], v[128:129], v[202:203]
	v_pk_fma_f32 v[164:165], v[132:133], v[178:179], v[164:165]
	ds_read_b64 v[170:171], v244
	ds_read_b64 v[178:179], v243 offset:16
	ds_read_b64 v[198:199], v238 offset:3072
	s_waitcnt lgkmcnt(12)
; #define PG8_LAS __attribute__((address_space(3)))
; __device__ __forceinline__ unsigned cvt_pk_bf16(float lo, float hi) { unsigned r; asm volatile("v_cvt_pk_bf16_f32 %0, %1, %2" : "=v"(r) : "v"(lo), "v"(hi)); return r; }
;     __device__ __forceinline__ void operator()(const f32x4 (&acc)[2][2][4][2], const Unit& u, int wr, int wc, int fr, int fq) const {
;     ...
;                 for (int m = 0; m < 4; ++m) { const int r = 128 * ai + 64 * wr + 16 * m + fr, t = tstart + r;
;                     const bool upok = t >= 1, dnok = (t + 1) < T, store_ok = (r >= vlo) && (r < vhi) && (t < T);
;                     f32x4 res[2];
; #pragma unroll
;                     for (int bj = 0; bj < 2; ++bj) { const f32x4 cur = acc[ai][bj][m][n];
;                         f32x4 su = cur, sd = cur;
;                         if (m > 0) { if (fr == 15) su = acc[ai][bj][m > 0 ? m - 1 : 0][n]; }
;                         if (m < 3) { if (fr == 0) sd = acc[ai][bj][m < 3 ? m + 1 : 3][n]; }
;                         f32x4 up, dn;
;                         up[0] = dpp_ror1(su[0]); up[1] = dpp_ror1(su[1]); up[2] = dpp_ror1(su[2]); up[3] = dpp_ror1(su[3]);
;                         dn[0] = dpp_ror15(sd[0]); dn[1] = dpp_ror15(sd[1]); dn[2] = dpp_ror15(sd[2]); dn[3] = dpp_ror15(sd[3]);
;                         if (m == 0) { f32x4 halo = zero4; if (blk > 0) halo = *(const PG8_LAS f32x4*)(xb + (((((blk - 1) * 2 + 1) * 4 + wc) * 4 + fq) * 16 + (bj * 2 + n) * 4)); if (fr == 0) up = halo; }
;                         if (m == 3) { f32x4 halo = zero4; if (blk < 3) halo = *(const PG8_LAS f32x4*)(xb + (((((blk + 1) * 2 + 0) * 4 + wc) * 4 + fq) * 16 + (bj * 2 + n) * 4)); if (fr == 15) dn = halo; }
;                         if (edge) { if (!upok) up = zero4; if (!dnok) dn = zero4; }
;                         res[bj] = bb[bj] + w0[bj] * up + w1[bj] * cur + w2[bj] * dn; }
;                     if (store_ok) {
;                         float o[4];
; #pragma unroll
;                         for (int j = 0; j < 4; ++j) { const float gg = res[1][j]; o[j] = gg * __builtin_amdgcn_rcpf(1.f + __expf(-gg)) * res[0][j]; }
;                         u32x2 w; w.x = cvt_pk_bf16(o[0], o[1]); w.y = cvt_pk_bf16(o[2], o[3]);
;                         *(u32x2*)(ACT + (size_t)(seqrow + t) * 2816 + ch0 + 4 * n) = w; } } }
	v_add_u32_e32 v220, s48, v231
	v_cmp_lt_i32_e32 vcc, 0, v220
	s_nop 1
	v_cndmask_b32_e32 v172, 0, v172, vcc
	v_cndmask_b32_e32 v173, 0, v173, vcc
	v_cmp_gt_i32_e32 vcc, s28, v220
	s_nop 1
	v_cndmask_b32_e32 v180, 0, v180, vcc
	v_cndmask_b32_e32 v181, 0, v181, vcc
	v_pk_fma_f32 v[202:203], v[124:125], v[172:173], v[136:137]
	v_pk_fma_f32 v[156:157], v[156:157], v[128:129], v[202:203]
	v_pk_fma_f32 v[156:157], v[132:133], v[180:181], v[156:157]
	ds_read_b64 v[172:173], v244 offset:256
	ds_read_b64 v[180:181], v243 offset:272
	s_waitcnt lgkmcnt(12)
	v_add_u32_e32 v220, s48, v232
	v_cmp_lt_i32_e32 vcc, 0, v220
	s_nop 1
	v_cndmask_b32_e32 v174, 0, v174, vcc
	v_cndmask_b32_e32 v175, 0, v175, vcc
	v_cmp_gt_i32_e32 vcc, s28, v220
	s_nop 1
	v_cndmask_b32_e32 v194, 0, v194, vcc
	v_cndmask_b32_e32 v195, 0, v195, vcc
	v_pk_fma_f32 v[202:203], v[124:125], v[174:175], v[136:137]
	v_pk_fma_f32 v[148:149], v[148:149], v[128:129], v[202:203]
	v_pk_fma_f32 v[148:149], v[132:133], v[194:195], v[148:149]
	ds_read_b64 v[174:175], v244 offset:512
	ds_read_b64 v[194:195], v243 offset:528
	s_waitcnt lgkmcnt(11)
	v_cndmask_b32_e64 v196, v196, v200, s[4:5]
	v_cndmask_b32_e64 v197, v197, v201, s[4:5]
	v_add_u32_e32 v220, s48, v233
	v_cmp_lt_i32_e32 vcc, 0, v220
	s_nop 1
	v_cndmask_b32_e32 v176, 0, v176, vcc
	v_cndmask_b32_e32 v177, 0, v177, vcc
	v_cmp_gt_i32_e32 vcc, s28, v220
	s_nop 1
	v_cndmask_b32_e32 v196, 0, v196, vcc
	v_cndmask_b32_e32 v197, 0, v197, vcc
	v_pk_fma_f32 v[202:203], v[124:125], v[176:177], v[136:137]
	v_pk_fma_f32 v[140:141], v[140:141], v[128:129], v[202:203]
	v_pk_fma_f32 v[140:141], v[132:133], v[196:197], v[140:141]
	ds_read_b64 v[176:177], v244 offset:768
	ds_read_b64 v[196:197], v243 offset:784
	ds_read_b64 v[200:201], v246
	v_mul_f32_e32 v208, 0xbfb8aa3b, v162
	v_mul_f32_e32 v209, 0xbfb8aa3b, v163
	v_mul_f32_e32 v210, 0xbfb8aa3b, v164
	v_mul_f32_e32 v211, 0xbfb8aa3b, v165
	v_exp_f32_e32 v208, v208
	v_exp_f32_e32 v209, v209
	v_exp_f32_e32 v210, v210
	v_exp_f32_e32 v211, v211
	v_add_f32_e32 v208, 1.0, v208
	v_add_f32_e32 v209, 1.0, v209
	v_add_f32_e32 v210, 1.0, v210
	v_add_f32_e32 v211, 1.0, v211
	v_rcp_f32_e32 v208, v208
	v_rcp_f32_e32 v209, v209
	v_rcp_f32_e32 v210, v210
	v_rcp_f32_e32 v211, v211
	v_mul_f32_e32 v162, v162, v208
	v_mul_f32_e32 v163, v163, v209
	v_mul_f32_e32 v164, v164, v210
	v_mul_f32_e32 v165, v165, v211
	v_mul_f32_e32 v162, v166, v162
	v_mul_f32_e32 v163, v167, v163
	v_mul_f32_e32 v164, v168, v164
	v_mul_f32_e32 v165, v169, v165
	v_cvt_pk_bf16_f32 v212, v162, v163
	v_cvt_pk_bf16_f32 v213, v164, v165
	ds_bpermute_b32 v212, v250, v212
	ds_bpermute_b32 v213, v250, v213
	v_mul_f32_e32 v208, 0xbfb8aa3b, v154
	v_mul_f32_e32 v209, 0xbfb8aa3b, v155
	v_mul_f32_e32 v210, 0xbfb8aa3b, v156
	v_mul_f32_e32 v211, 0xbfb8aa3b, v157
	v_exp_f32_e32 v208, v208
	v_exp_f32_e32 v209, v209
	v_exp_f32_e32 v210, v210
	v_exp_f32_e32 v211, v211
	v_add_f32_e32 v208, 1.0, v208
	v_add_f32_e32 v209, 1.0, v209
	v_add_f32_e32 v210, 1.0, v210
	v_add_f32_e32 v211, 1.0, v211
	v_rcp_f32_e32 v208, v208
	v_rcp_f32_e32 v209, v209
	v_rcp_f32_e32 v210, v210
	v_rcp_f32_e32 v211, v211
	v_mul_f32_e32 v154, v154, v208
	v_mul_f32_e32 v155, v155, v209
	v_mul_f32_e32 v156, v156, v210
	v_mul_f32_e32 v157, v157, v211
	v_mul_f32_e32 v154, v158, v154
	v_mul_f32_e32 v155, v159, v155
	v_mul_f32_e32 v156, v160, v156
	v_mul_f32_e32 v157, v161, v157
	v_cvt_pk_bf16_f32 v218, v154, v155
	v_cvt_pk_bf16_f32 v219, v156, v157
	ds_bpermute_b32 v218, v250, v218
	ds_bpermute_b32 v219, v250, v219
	s_waitcnt lgkmcnt(2)
	v_add_u32_e32 v221, 0x0, v247
	s_and_saveexec_b64 s[30:31], s[12:13]
	global_store_dwordx2 v221, v[212:213], s[10:11]
	s_mov_b64 exec, s[30:31]
	v_mul_f32_e32 v208, 0xbfb8aa3b, v146
	v_mul_f32_e32 v209, 0xbfb8aa3b, v147
	v_mul_f32_e32 v210, 0xbfb8aa3b, v148
	v_mul_f32_e32 v211, 0xbfb8aa3b, v149
	v_exp_f32_e32 v208, v208
	v_exp_f32_e32 v209, v209
	v_exp_f32_e32 v210, v210
	v_exp_f32_e32 v211, v211
	v_add_f32_e32 v208, 1.0, v208
	v_add_f32_e32 v209, 1.0, v209
	v_add_f32_e32 v210, 1.0, v210
	v_add_f32_e32 v211, 1.0, v211
	v_rcp_f32_e32 v208, v208
	v_rcp_f32_e32 v209, v209
	v_rcp_f32_e32 v210, v210
	v_rcp_f32_e32 v211, v211
	v_mul_f32_e32 v146, v146, v208
	v_mul_f32_e32 v147, v147, v209
	v_mul_f32_e32 v148, v148, v210
	v_mul_f32_e32 v149, v149, v211
	v_mul_f32_e32 v146, v150, v146
	v_mul_f32_e32 v147, v151, v147
	v_mul_f32_e32 v148, v152, v148
	v_mul_f32_e32 v149, v153, v149
	v_cvt_pk_bf16_f32 v212, v146, v147
	v_cvt_pk_bf16_f32 v213, v148, v149
	ds_bpermute_b32 v212, v250, v212
	ds_bpermute_b32 v213, v250, v213
	s_waitcnt lgkmcnt(2)
	v_add_u32_e32 v251, 0x16000, v247
	s_and_saveexec_b64 s[30:31], s[14:15]
	global_store_dwordx2 v251, v[218:219], s[10:11]
	s_mov_b64 exec, s[30:31]
	v_mul_f32_e32 v208, 0xbfb8aa3b, v138
	v_mul_f32_e32 v209, 0xbfb8aa3b, v139
	v_mul_f32_e32 v210, 0xbfb8aa3b, v140
	v_mul_f32_e32 v211, 0xbfb8aa3b, v141
	v_exp_f32_e32 v208, v208
	v_exp_f32_e32 v209, v209
	v_exp_f32_e32 v210, v210
	v_exp_f32_e32 v211, v211
	v_add_f32_e32 v208, 1.0, v208
	v_add_f32_e32 v209, 1.0, v209
	v_add_f32_e32 v210, 1.0, v210
	v_add_f32_e32 v211, 1.0, v211
	v_rcp_f32_e32 v208, v208
	v_rcp_f32_e32 v209, v209
	v_rcp_f32_e32 v210, v210
	v_rcp_f32_e32 v211, v211
	v_mul_f32_e32 v138, v138, v208
	v_mul_f32_e32 v139, v139, v209
	v_mul_f32_e32 v140, v140, v210
	v_mul_f32_e32 v141, v141, v211
	v_mul_f32_e32 v138, v142, v138
	v_mul_f32_e32 v139, v143, v139
	v_mul_f32_e32 v140, v144, v140
	v_mul_f32_e32 v141, v145, v141
	v_cvt_pk_bf16_f32 v218, v138, v139
	v_cvt_pk_bf16_f32 v219, v140, v141
	ds_bpermute_b32 v218, v250, v218
	ds_bpermute_b32 v219, v250, v219
	s_waitcnt lgkmcnt(2)
;     __device__ __forceinline__ void operator()(const f32x4 (&acc)[2][2][4][2], const Unit& u, int wr, int wc, int fr, int fq) const {
;     ...
;         for (int n = 0; n < 2; ++n) {
;             if (n == 1) {
; #pragma unroll
;                 for (int bj = 0; bj < 2; ++bj) { const int col = bj * 2816 + ch0 + 4;
;                     w0[bj] = *(const f32x4*)(cw + col); w1[bj] = *(const f32x4*)(cw + 5632 + col); w2[bj] = *(const f32x4*)(cw + 11264 + col); bb[bj] = *(const f32x4*)(cb + col); } }
; #pragma unroll
;             for (int ai = 0; ai < 2; ++ai) { const int blk = ai * 2 + wr;
; #pragma unroll
;                 for (int m = 0; m < 4; ++m) { const int r = 128 * ai + 64 * wr + 16 * m + fr, t = tstart + r;
;                     const bool upok = t >= 1, dnok = (t + 1) < T, store_ok = (r >= vlo) && (r < vhi) && (t < T);
;                     f32x4 res[2];
; #pragma unroll
;                     for (int bj = 0; bj < 2; ++bj) { const f32x4 cur = acc[ai][bj][m][n];
;                         f32x4 su = cur, sd = cur;
;                         if (m > 0) { if (fr == 15) su = acc[ai][bj][m > 0 ? m - 1 : 0][n]; }
;                         if (m < 3) { if (fr == 0) sd = acc[ai][bj][m < 3 ? m + 1 : 3][n]; }
;                         f32x4 up, dn;
;                         up[0] = dpp_ror1(su[0]); up[1] = dpp_ror1(su[1]); up[2] = dpp_ror1(su[2]); up[3] = dpp_ror1(su[3]);
;                         dn[0] = dpp_ror15(sd[0]); dn[1] = dpp_ror15(sd[1]); dn[2] = dpp_ror15(sd[2]); dn[3] = dpp_ror15(sd[3]);
;                         if (m == 0) { f32x4 halo = zero4; if (blk > 0) halo = *(const PG8_LAS f32x4*)(xb + (((((blk - 1) * 2 + 1) * 4 + wc) * 4 + fq) * 16 + (bj * 2 + n) * 4)); if (fr == 0) up = halo; }
;                         if (m == 3) { f32x4 halo = zero4; if (blk < 3) halo = *(const PG8_LAS f32x4*)(xb + (((((blk + 1) * 2 + 0) * 4 + wc) * 4 + fq) * 16 + (bj * 2 + n) * 4)); if (fr == 15) dn = halo; }
;     ...
;                     if (store_ok) {
;                         float o[4];
; #pragma unroll
;                         for (int j = 0; j < 4; ++j) { const float gg = res[1][j]; o[j] = gg * __builtin_amdgcn_rcpf(1.f + __expf(-gg)) * res[0][j]; }
;                         u32x2 w; w.x = cvt_pk_bf16(o[0], o[1]); w.y = cvt_pk_bf16(o[2], o[3]);
;                         *(u32x2*)(ACT + (size_t)(seqrow + t) * 2816 + ch0 + 4 * n) = w; } } }
	v_add_u32_e32 v221, 0x2c000, v247
	s_and_saveexec_b64 s[30:31], s[16:17]
	global_store_dwordx2 v221, v[212:213], s[10:11]
	s_mov_b64 exec, s[30:31]
	s_waitcnt lgkmcnt(0)
	v_add_u32_e32 v251, 0x42000, v247
	s_and_saveexec_b64 s[30:31], s[18:19]
	global_store_dwordx2 v251, v[218:219], s[10:11]
	s_mov_b64 exec, s[30:31]
	global_load_dwordx4 v[138:141], v248, s[62:63] offset:16
	global_load_dwordx4 v[142:145], v248, s[66:67] offset:16
	global_load_dwordx4 v[146:149], v248, s[68:69] offset:16
	global_load_dwordx4 v[150:153], v248, s[64:65] offset:16
	global_load_dwordx4 v[154:157], v249, s[62:63] offset:16
	global_load_dwordx4 v[158:161], v249, s[66:67] offset:16
	global_load_dwordx4 v[162:165], v249, s[68:69] offset:16
	global_load_dwordx4 v[166:169], v249, s[64:65] offset:16
	ds_write_b64 v243, v[104:105]
	ds_write_b64 v243, v[96:97] offset:256
	ds_write_b64 v243, v[88:89] offset:512
	ds_write_b64 v243, v[80:81] offset:768
	v_cndmask_b32_e64 v170, v170, v198, s[6:7]
	v_cndmask_b32_e64 v171, v171, v199, s[6:7]
	v_add_u32_e32 v220, s48, v234
	v_cmp_lt_i32_e32 vcc, 0, v220
	s_nop 1
	v_cndmask_b32_e32 v170, 0, v170, vcc
	v_cndmask_b32_e32 v171, 0, v171, vcc
	v_cmp_gt_i32_e32 vcc, s28, v220
	s_nop 1
	v_cndmask_b32_e32 v178, 0, v178, vcc
	v_cndmask_b32_e32 v179, 0, v179, vcc
	v_pk_fma_f32 v[202:203], v[106:107], v[170:171], v[118:119]
	v_pk_fma_f32 v[102:103], v[102:103], v[110:111], v[202:203]
	v_pk_fma_f32 v[102:103], v[114:115], v[178:179], v[102:103]
	ds_read_b64 v[170:171], v244
	ds_read_b64 v[178:179], v243 offset:16
	ds_read_b64 v[198:199], v238 offset:3080
	v_add_u32_e32 v220, s48, v235
	v_cmp_lt_i32_e32 vcc, 0, v220
	s_nop 1
	v_cndmask_b32_e32 v172, 0, v172, vcc
	v_cndmask_b32_e32 v173, 0, v173, vcc
	v_cmp_gt_i32_e32 vcc, s28, v220
	s_nop 1
	v_cndmask_b32_e32 v180, 0, v180, vcc
	v_cndmask_b32_e32 v181, 0, v181, vcc
	v_pk_fma_f32 v[202:203], v[106:107], v[172:173], v[118:119]
	v_pk_fma_f32 v[94:95], v[94:95], v[110:111], v[202:203]
	v_pk_fma_f32 v[94:95], v[114:115], v[180:181], v[94:95]
	ds_read_b64 v[172:173], v244 offset:256
	ds_read_b64 v[180:181], v243 offset:272
	v_add_u32_e32 v220, s48, v236
	v_cmp_lt_i32_e32 vcc, 0, v220
	s_nop 1
	v_cndmask_b32_e32 v174, 0, v174, vcc
	v_cndmask_b32_e32 v175, 0, v175, vcc
	v_cmp_gt_i32_e32 vcc, s28, v220
	s_nop 1
	v_cndmask_b32_e32 v194, 0, v194, vcc
	v_cndmask_b32_e32 v195, 0, v195, vcc
	v_pk_fma_f32 v[202:203], v[106:107], v[174:175], v[118:119]
	v_pk_fma_f32 v[86:87], v[86:87], v[110:111], v[202:203]
	v_pk_fma_f32 v[86:87], v[114:115], v[194:195], v[86:87]
	ds_read_b64 v[174:175], v244 offset:512
	ds_read_b64 v[194:195], v243 offset:528
	v_cndmask_b32_e64 v196, v196, v200, s[4:5]
	v_cndmask_b32_e64 v197, v197, v201, s[4:5]
	v_add_u32_e32 v220, s48, v237
	v_cmp_lt_i32_e32 vcc, 0, v220
	s_nop 1
	v_cndmask_b32_e32 v176, 0, v176, vcc
	v_cndmask_b32_e32 v177, 0, v177, vcc
	v_cmp_gt_i32_e32 vcc, s28, v220
	s_nop 1
	v_cndmask_b32_e32 v196, 0, v196, vcc
	v_cndmask_b32_e32 v197, 0, v197, vcc
	v_pk_fma_f32 v[202:203], v[106:107], v[176:177], v[118:119]
	v_pk_fma_f32 v[78:79], v[78:79], v[110:111], v[202:203]
	v_pk_fma_f32 v[78:79], v[114:115], v[196:197], v[78:79]
	ds_read_b64 v[176:177], v244 offset:768
	ds_read_b64 v[196:197], v243 offset:784
	ds_read_b64 v[200:201], v246 offset:8
	ds_write_b64 v243, v[98:99]
	ds_write_b64 v243, v[90:91] offset:256
	ds_write_b64 v243, v[82:83] offset:512
	ds_write_b64 v243, v[74:75] offset:768
	s_waitcnt lgkmcnt(11)
	v_cndmask_b32_e64 v170, v170, v198, s[6:7]
	v_cndmask_b32_e64 v171, v171, v199, s[6:7]
	v_add_u32_e32 v220, s48, v234
	v_cmp_lt_i32_e32 vcc, 0, v220
	s_nop 1
	v_cndmask_b32_e32 v170, 0, v170, vcc
	v_cndmask_b32_e32 v171, 0, v171, vcc
	v_cmp_gt_i32_e32 vcc, s28, v220
	s_nop 1
	v_cndmask_b32_e32 v178, 0, v178, vcc
	v_cndmask_b32_e32 v179, 0, v179, vcc
	v_pk_fma_f32 v[202:203], v[108:109], v[170:171], v[120:121]
	v_pk_fma_f32 v[104:105], v[104:105], v[112:113], v[202:203]
	v_pk_fma_f32 v[104:105], v[116:117], v[178:179], v[104:105]
	ds_read_b64 v[170:171], v244
	ds_read_b64 v[178:179], v243 offset:16
	ds_read_b64 v[198:199], v238 offset:3104
	s_waitcnt lgkmcnt(12)
	v_add_u32_e32 v220, s48, v235
	v_cmp_lt_i32_e32 vcc, 0, v220
	s_nop 1
	v_cndmask_b32_e32 v172, 0, v172, vcc
	v_cndmask_b32_e32 v173, 0, v173, vcc
	v_cmp_gt_i32_e32 vcc, s28, v220
	s_nop 1
	v_cndmask_b32_e32 v180, 0, v180, vcc
	v_cndmask_b32_e32 v181, 0, v181, vcc
	v_pk_fma_f32 v[202:203], v[108:109], v[172:173], v[120:121]
	v_pk_fma_f32 v[96:97], v[96:97], v[112:113], v[202:203]
	v_pk_fma_f32 v[96:97], v[116:117], v[180:181], v[96:97]
	ds_read_b64 v[172:173], v244 offset:256
	ds_read_b64 v[180:181], v243 offset:272
	s_waitcnt lgkmcnt(12)
	v_add_u32_e32 v220, s48, v236
	v_cmp_lt_i32_e32 vcc, 0, v220
	s_nop 1
	v_cndmask_b32_e32 v174, 0, v174, vcc
	v_cndmask_b32_e32 v175, 0, v175, vcc
	v_cmp_gt_i32_e32 vcc, s28, v220
	s_nop 1
	v_cndmask_b32_e32 v194, 0, v194, vcc
	v_cndmask_b32_e32 v195, 0, v195, vcc
	v_pk_fma_f32 v[202:203], v[108:109], v[174:175], v[120:121]
	v_pk_fma_f32 v[88:89], v[88:89], v[112:113], v[202:203]
	v_pk_fma_f32 v[88:89], v[116:117], v[194:195], v[88:89]
	ds_read_b64 v[174:175], v244 offset:512
	ds_read_b64 v[194:195], v243 offset:528
	s_waitcnt lgkmcnt(11)
	v_cndmask_b32_e64 v196, v196, v200, s[4:5]
	v_cndmask_b32_e64 v197, v197, v201, s[4:5]
	v_add_u32_e32 v220, s48, v237
	v_cmp_lt_i32_e32 vcc, 0, v220
	s_nop 1
	v_cndmask_b32_e32 v176, 0, v176, vcc
	v_cndmask_b32_e32 v177, 0, v177, vcc
	v_cmp_gt_i32_e32 vcc, s28, v220
	s_nop 1
	v_cndmask_b32_e32 v196, 0, v196, vcc
	v_cndmask_b32_e32 v197, 0, v197, vcc
	v_pk_fma_f32 v[202:203], v[108:109], v[176:177], v[120:121]
	v_pk_fma_f32 v[80:81], v[80:81], v[112:113], v[202:203]
	v_pk_fma_f32 v[80:81], v[116:117], v[196:197], v[80:81]
	ds_read_b64 v[176:177], v244 offset:768
	ds_read_b64 v[196:197], v243 offset:784
	ds_read_b64 v[200:201], v246 offset:32
	ds_write_b64 v243, v[100:101]
	ds_write_b64 v243, v[92:93] offset:256
	ds_write_b64 v243, v[84:85] offset:512
	ds_write_b64 v243, v[76:77] offset:768
	s_waitcnt lgkmcnt(11)
; #define PG8_LAS __attribute__((address_space(3)))
; __device__ __forceinline__ unsigned cvt_pk_bf16(float lo, float hi) { unsigned r; asm volatile("v_cvt_pk_bf16_f32 %0, %1, %2" : "=v"(r) : "v"(lo), "v"(hi)); return r; }
;     __device__ __forceinline__ void operator()(const f32x4 (&acc)[2][2][4][2], const Unit& u, int wr, int wc, int fr, int fq) const {
;     ...
;                 for (int m = 0; m < 4; ++m) { const int r = 128 * ai + 64 * wr + 16 * m + fr, t = tstart + r;
;                     const bool upok = t >= 1, dnok = (t + 1) < T, store_ok = (r >= vlo) && (r < vhi) && (t < T);
;                     f32x4 res[2];
; #pragma unroll
;                     for (int bj = 0; bj < 2; ++bj) { const f32x4 cur = acc[ai][bj][m][n];
;                         f32x4 su = cur, sd = cur;
;                         if (m > 0) { if (fr == 15) su = acc[ai][bj][m > 0 ? m - 1 : 0][n]; }
;                         if (m < 3) { if (fr == 0) sd = acc[ai][bj][m < 3 ? m + 1 : 3][n]; }
;                         f32x4 up, dn;
;                         up[0] = dpp_ror1(su[0]); up[1] = dpp_ror1(su[1]); up[2] = dpp_ror1(su[2]); up[3] = dpp_ror1(su[3]);
;                         dn[0] = dpp_ror15(sd[0]); dn[1] = dpp_ror15(sd[1]); dn[2] = dpp_ror15(sd[2]); dn[3] = dpp_ror15(sd[3]);
;                         if (m == 0) { f32x4 halo = zero4; if (blk > 0) halo = *(const PG8_LAS f32x4*)(xb + (((((blk - 1) * 2 + 1) * 4 + wc) * 4 + fq) * 16 + (bj * 2 + n) * 4)); if (fr == 0) up = halo; }
;                         if (m == 3) { f32x4 halo = zero4; if (blk < 3) halo = *(const PG8_LAS f32x4*)(xb + (((((blk + 1) * 2 + 0) * 4 + wc) * 4 + fq) * 16 + (bj * 2 + n) * 4)); if (fr == 15) dn = halo; }
;                         if (edge) { if (!upok) up = zero4; if (!dnok) dn = zero4; }
;                         res[bj] = bb[bj] + w0[bj] * up + w1[bj] * cur + w2[bj] * dn; }
;                     if (store_ok) {
;                         float o[4];
; #pragma unroll
;                         for (int j = 0; j < 4; ++j) { const float gg = res[1][j]; o[j] = gg * __builtin_amdgcn_rcpf(1.f + __expf(-gg)) * res[0][j]; }
;                         u32x2 w; w.x = cvt_pk_bf16(o[0], o[1]); w.y = cvt_pk_bf16(o[2], o[3]);
;                         *(u32x2*)(ACT + (size_t)(seqrow + t) * 2816 + ch0 + 4 * n) = w; } } }
	v_cndmask_b32_e64 v170, v170, v198, s[6:7]
	v_cndmask_b32_e64 v171, v171, v199, s[6:7]
	v_add_u32_e32 v220, s48, v234
	v_cmp_lt_i32_e32 vcc, 0, v220
	s_nop 1
	v_cndmask_b32_e32 v170, 0, v170, vcc
	v_cndmask_b32_e32 v171, 0, v171, vcc
	v_cmp_gt_i32_e32 vcc, s28, v220
	s_nop 1
	v_cndmask_b32_e32 v178, 0, v178, vcc
	v_cndmask_b32_e32 v179, 0, v179, vcc
	v_pk_fma_f32 v[202:203], v[122:123], v[170:171], v[134:135]
	v_pk_fma_f32 v[98:99], v[98:99], v[126:127], v[202:203]
	v_pk_fma_f32 v[98:99], v[130:131], v[178:179], v[98:99]
	ds_read_b64 v[170:171], v244
	ds_read_b64 v[178:179], v243 offset:16
	ds_read_b64 v[198:199], v238 offset:3112
	s_waitcnt lgkmcnt(12)
	v_add_u32_e32 v220, s48, v235
	v_cmp_lt_i32_e32 vcc, 0, v220
	s_nop 1
	v_cndmask_b32_e32 v172, 0, v172, vcc
	v_cndmask_b32_e32 v173, 0, v173, vcc
	v_cmp_gt_i32_e32 vcc, s28, v220
	s_nop 1
	v_cndmask_b32_e32 v180, 0, v180, vcc
	v_cndmask_b32_e32 v181, 0, v181, vcc
	v_pk_fma_f32 v[202:203], v[122:123], v[172:173], v[134:135]
	v_pk_fma_f32 v[90:91], v[90:91], v[126:127], v[202:203]
	v_pk_fma_f32 v[90:91], v[130:131], v[180:181], v[90:91]
	ds_read_b64 v[172:173], v244 offset:256
	ds_read_b64 v[180:181], v243 offset:272
	s_waitcnt lgkmcnt(12)
	v_add_u32_e32 v220, s48, v236
	v_cmp_lt_i32_e32 vcc, 0, v220
	s_nop 1
	v_cndmask_b32_e32 v174, 0, v174, vcc
	v_cndmask_b32_e32 v175, 0, v175, vcc
	v_cmp_gt_i32_e32 vcc, s28, v220
	s_nop 1
	v_cndmask_b32_e32 v194, 0, v194, vcc
	v_cndmask_b32_e32 v195, 0, v195, vcc
	v_pk_fma_f32 v[202:203], v[122:123], v[174:175], v[134:135]
	v_pk_fma_f32 v[82:83], v[82:83], v[126:127], v[202:203]
	v_pk_fma_f32 v[82:83], v[130:131], v[194:195], v[82:83]
	ds_read_b64 v[174:175], v244 offset:512
	ds_read_b64 v[194:195], v243 offset:528
	s_waitcnt lgkmcnt(11)
	v_cndmask_b32_e64 v196, v196, v200, s[4:5]
	v_cndmask_b32_e64 v197, v197, v201, s[4:5]
	v_add_u32_e32 v220, s48, v237
	v_cmp_lt_i32_e32 vcc, 0, v220
	s_nop 1
	v_cndmask_b32_e32 v176, 0, v176, vcc
	v_cndmask_b32_e32 v177, 0, v177, vcc
	v_cmp_gt_i32_e32 vcc, s28, v220
	s_nop 1
	v_cndmask_b32_e32 v196, 0, v196, vcc
	v_cndmask_b32_e32 v197, 0, v197, vcc
	v_pk_fma_f32 v[202:203], v[122:123], v[176:177], v[134:135]
	v_pk_fma_f32 v[74:75], v[74:75], v[126:127], v[202:203]
	v_pk_fma_f32 v[74:75], v[130:131], v[196:197], v[74:75]
	ds_read_b64 v[176:177], v244 offset:768
	ds_read_b64 v[196:197], v243 offset:784
	ds_read_b64 v[200:201], v246 offset:40
	ds_write_b64 v243, v[70:71]
	ds_write_b64 v243, v[62:63] offset:256
	ds_write_b64 v243, v[54:55] offset:512
	ds_write_b64 v243, v[46:47] offset:768
	s_waitcnt lgkmcnt(11)
	v_cndmask_b32_e64 v170, v170, v198, s[6:7]
	v_cndmask_b32_e64 v171, v171, v199, s[6:7]
	v_add_u32_e32 v220, s48, v234
	v_cmp_lt_i32_e32 vcc, 0, v220
	s_nop 1
	v_cndmask_b32_e32 v170, 0, v170, vcc
	v_cndmask_b32_e32 v171, 0, v171, vcc
	v_cmp_gt_i32_e32 vcc, s28, v220
	s_nop 1
	v_cndmask_b32_e32 v178, 0, v178, vcc
	v_cndmask_b32_e32 v179, 0, v179, vcc
	v_pk_fma_f32 v[202:203], v[124:125], v[170:171], v[136:137]
	v_pk_fma_f32 v[100:101], v[100:101], v[128:129], v[202:203]
	v_pk_fma_f32 v[100:101], v[132:133], v[178:179], v[100:101]
	ds_read_b64 v[170:171], v244
	ds_read_b64 v[178:179], v243 offset:16
	ds_read_b64 v[198:199], v245 offset:16
	s_waitcnt lgkmcnt(12)
	v_add_u32_e32 v220, s48, v235
	v_cmp_lt_i32_e32 vcc, 0, v220
	s_nop 1
	v_cndmask_b32_e32 v172, 0, v172, vcc
	v_cndmask_b32_e32 v173, 0, v173, vcc
	v_cmp_gt_i32_e32 vcc, s28, v220
	s_nop 1
	v_cndmask_b32_e32 v180, 0, v180, vcc
	v_cndmask_b32_e32 v181, 0, v181, vcc
	v_pk_fma_f32 v[202:203], v[124:125], v[172:173], v[136:137]
	v_pk_fma_f32 v[92:93], v[92:93], v[128:129], v[202:203]
	v_pk_fma_f32 v[92:93], v[132:133], v[180:181], v[92:93]
	ds_read_b64 v[172:173], v244 offset:256
	ds_read_b64 v[180:181], v243 offset:272
	s_waitcnt lgkmcnt(12)
	v_add_u32_e32 v220, s48, v236
	v_cmp_lt_i32_e32 vcc, 0, v220
	s_nop 1
	v_cndmask_b32_e32 v174, 0, v174, vcc
	v_cndmask_b32_e32 v175, 0, v175, vcc
	v_cmp_gt_i32_e32 vcc, s28, v220
	s_nop 1
	v_cndmask_b32_e32 v194, 0, v194, vcc
	v_cndmask_b32_e32 v195, 0, v195, vcc
	v_pk_fma_f32 v[202:203], v[124:125], v[174:175], v[136:137]
	v_pk_fma_f32 v[84:85], v[84:85], v[128:129], v[202:203]
	v_pk_fma_f32 v[84:85], v[132:133], v[194:195], v[84:85]
	ds_read_b64 v[174:175], v244 offset:512
	ds_read_b64 v[194:195], v243 offset:528
	s_waitcnt lgkmcnt(11)
	v_cndmask_b32_e64 v196, v196, v200, s[4:5]
	v_cndmask_b32_e64 v197, v197, v201, s[4:5]
	v_add_u32_e32 v220, s48, v237
	v_cmp_lt_i32_e32 vcc, 0, v220
	s_nop 1
	v_cndmask_b32_e32 v176, 0, v176, vcc
	v_cndmask_b32_e32 v177, 0, v177, vcc
	v_cmp_gt_i32_e32 vcc, s28, v220
	s_nop 1
	v_cndmask_b32_e32 v196, 0, v196, vcc
	v_cndmask_b32_e32 v197, 0, v197, vcc
	v_pk_fma_f32 v[202:203], v[124:125], v[176:177], v[136:137]
	v_pk_fma_f32 v[76:77], v[76:77], v[128:129], v[202:203]
	v_pk_fma_f32 v[76:77], v[132:133], v[196:197], v[76:77]
	ds_read_b64 v[176:177], v244 offset:768
	ds_read_b64 v[196:197], v243 offset:784
	ds_read_b64 v[200:201], v238 offset:2064
	v_mul_f32_e32 v208, 0xbfb8aa3b, v98
	v_mul_f32_e32 v209, 0xbfb8aa3b, v99
	v_mul_f32_e32 v210, 0xbfb8aa3b, v100
	v_mul_f32_e32 v211, 0xbfb8aa3b, v101
	v_exp_f32_e32 v208, v208
	v_exp_f32_e32 v209, v209
	v_exp_f32_e32 v210, v210
	v_exp_f32_e32 v211, v211
	v_add_f32_e32 v208, 1.0, v208
	v_add_f32_e32 v209, 1.0, v209
	v_add_f32_e32 v210, 1.0, v210
	v_add_f32_e32 v211, 1.0, v211
	v_rcp_f32_e32 v208, v208
	v_rcp_f32_e32 v209, v209
	v_rcp_f32_e32 v210, v210
	v_rcp_f32_e32 v211, v211
	v_mul_f32_e32 v98, v98, v208
	v_mul_f32_e32 v99, v99, v209
	v_mul_f32_e32 v100, v100, v210
	v_mul_f32_e32 v101, v101, v211
	v_mul_f32_e32 v98, v102, v98
	v_mul_f32_e32 v99, v103, v99
	v_mul_f32_e32 v100, v104, v100
	v_mul_f32_e32 v101, v105, v101
	v_cvt_pk_bf16_f32 v212, v98, v99
	v_cvt_pk_bf16_f32 v213, v100, v101
	ds_bpermute_b32 v212, v250, v212
	ds_bpermute_b32 v213, v250, v213
	v_mul_f32_e32 v208, 0xbfb8aa3b, v90
	v_mul_f32_e32 v209, 0xbfb8aa3b, v91
	v_mul_f32_e32 v210, 0xbfb8aa3b, v92
	v_mul_f32_e32 v211, 0xbfb8aa3b, v93
	v_exp_f32_e32 v208, v208
	v_exp_f32_e32 v209, v209
	v_exp_f32_e32 v210, v210
	v_exp_f32_e32 v211, v211
	v_add_f32_e32 v208, 1.0, v208
	v_add_f32_e32 v209, 1.0, v209
	v_add_f32_e32 v210, 1.0, v210
	v_add_f32_e32 v211, 1.0, v211
	v_rcp_f32_e32 v208, v208
	v_rcp_f32_e32 v209, v209
	v_rcp_f32_e32 v210, v210
	v_rcp_f32_e32 v211, v211
	v_mul_f32_e32 v90, v90, v208
	v_mul_f32_e32 v91, v91, v209
	v_mul_f32_e32 v92, v92, v210
	v_mul_f32_e32 v93, v93, v211
	v_mul_f32_e32 v90, v94, v90
	v_mul_f32_e32 v91, v95, v91
	v_mul_f32_e32 v92, v96, v92
	v_mul_f32_e32 v93, v97, v93
	v_cvt_pk_bf16_f32 v218, v90, v91
	v_cvt_pk_bf16_f32 v219, v92, v93
	ds_bpermute_b32 v218, v250, v218
	ds_bpermute_b32 v219, v250, v219
	s_waitcnt lgkmcnt(2)
;     __device__ __forceinline__ void operator()(const f32x4 (&acc)[2][2][4][2], const Unit& u, int wr, int wc, int fr, int fq) const {
;     ...
;         for (int n = 0; n < 2; ++n) {
;             if (n == 1) {
; #pragma unroll
;                 for (int bj = 0; bj < 2; ++bj) { const int col = bj * 2816 + ch0 + 4;
;                     w0[bj] = *(const f32x4*)(cw + col); w1[bj] = *(const f32x4*)(cw + 5632 + col); w2[bj] = *(const f32x4*)(cw + 11264 + col); bb[bj] = *(const f32x4*)(cb + col); } }
; #pragma unroll
;             for (int ai = 0; ai < 2; ++ai) { const int blk = ai * 2 + wr;
; #pragma unroll
;                 for (int m = 0; m < 4; ++m) { const int r = 128 * ai + 64 * wr + 16 * m + fr, t = tstart + r;
;                     const bool upok = t >= 1, dnok = (t + 1) < T, store_ok = (r >= vlo) && (r < vhi) && (t < T);
;                     f32x4 res[2];
; #pragma unroll
;                     for (int bj = 0; bj < 2; ++bj) { const f32x4 cur = acc[ai][bj][m][n];
;                         f32x4 su = cur, sd = cur;
;                         if (m > 0) { if (fr == 15) su = acc[ai][bj][m > 0 ? m - 1 : 0][n]; }
;                         if (m < 3) { if (fr == 0) sd = acc[ai][bj][m < 3 ? m + 1 : 3][n]; }
;                         f32x4 up, dn;
;                         up[0] = dpp_ror1(su[0]); up[1] = dpp_ror1(su[1]); up[2] = dpp_ror1(su[2]); up[3] = dpp_ror1(su[3]);
;                         dn[0] = dpp_ror15(sd[0]); dn[1] = dpp_ror15(sd[1]); dn[2] = dpp_ror15(sd[2]); dn[3] = dpp_ror15(sd[3]);
;                         if (m == 0) { f32x4 halo = zero4; if (blk > 0) halo = *(const PG8_LAS f32x4*)(xb + (((((blk - 1) * 2 + 1) * 4 + wc) * 4 + fq) * 16 + (bj * 2 + n) * 4)); if (fr == 0) up = halo; }
;                         if (m == 3) { f32x4 halo = zero4; if (blk < 3) halo = *(const PG8_LAS f32x4*)(xb + (((((blk + 1) * 2 + 0) * 4 + wc) * 4 + fq) * 16 + (bj * 2 + n) * 4)); if (fr == 15) dn = halo; }
;     ...
;                     if (store_ok) {
;                         float o[4];
; #pragma unroll
;                         for (int j = 0; j < 4; ++j) { const float gg = res[1][j]; o[j] = gg * __builtin_amdgcn_rcpf(1.f + __expf(-gg)) * res[0][j]; }
;                         u32x2 w; w.x = cvt_pk_bf16(o[0], o[1]); w.y = cvt_pk_bf16(o[2], o[3]);
;                         *(u32x2*)(ACT + (size_t)(seqrow + t) * 2816 + ch0 + 4 * n) = w; } } }
	v_add_u32_e32 v221, 0xb0000, v247
	s_and_saveexec_b64 s[30:31], s[20:21]
	global_store_dwordx2 v221, v[212:213], s[10:11]
	s_mov_b64 exec, s[30:31]
	v_mul_f32_e32 v208, 0xbfb8aa3b, v82
	v_mul_f32_e32 v209, 0xbfb8aa3b, v83
	v_mul_f32_e32 v210, 0xbfb8aa3b, v84
	v_mul_f32_e32 v211, 0xbfb8aa3b, v85
	v_exp_f32_e32 v208, v208
	v_exp_f32_e32 v209, v209
	v_exp_f32_e32 v210, v210
	v_exp_f32_e32 v211, v211
	v_add_f32_e32 v208, 1.0, v208
	v_add_f32_e32 v209, 1.0, v209
	v_add_f32_e32 v210, 1.0, v210
	v_add_f32_e32 v211, 1.0, v211
	v_rcp_f32_e32 v208, v208
	v_rcp_f32_e32 v209, v209
	v_rcp_f32_e32 v210, v210
	v_rcp_f32_e32 v211, v211
	v_mul_f32_e32 v82, v82, v208
	v_mul_f32_e32 v83, v83, v209
	v_mul_f32_e32 v84, v84, v210
	v_mul_f32_e32 v85, v85, v211
	v_mul_f32_e32 v82, v86, v82
	v_mul_f32_e32 v83, v87, v83
	v_mul_f32_e32 v84, v88, v84
	v_mul_f32_e32 v85, v89, v85
	v_cvt_pk_bf16_f32 v212, v82, v83
	v_cvt_pk_bf16_f32 v213, v84, v85
	ds_bpermute_b32 v212, v250, v212
	ds_bpermute_b32 v213, v250, v213
	s_waitcnt lgkmcnt(2)
	v_add_u32_e32 v251, 0xc6000, v247
	s_and_saveexec_b64 s[30:31], s[22:23]
	global_store_dwordx2 v251, v[218:219], s[10:11]
	s_mov_b64 exec, s[30:31]
	v_mul_f32_e32 v208, 0xbfb8aa3b, v74
	v_mul_f32_e32 v209, 0xbfb8aa3b, v75
	v_mul_f32_e32 v210, 0xbfb8aa3b, v76
	v_mul_f32_e32 v211, 0xbfb8aa3b, v77
	v_exp_f32_e32 v208, v208
	v_exp_f32_e32 v209, v209
	v_exp_f32_e32 v210, v210
	v_exp_f32_e32 v211, v211
	v_add_f32_e32 v208, 1.0, v208
	v_add_f32_e32 v209, 1.0, v209
	v_add_f32_e32 v210, 1.0, v210
	v_add_f32_e32 v211, 1.0, v211
	v_rcp_f32_e32 v208, v208
	v_rcp_f32_e32 v209, v209
	v_rcp_f32_e32 v210, v210
	v_rcp_f32_e32 v211, v211
	v_mul_f32_e32 v74, v74, v208
	v_mul_f32_e32 v75, v75, v209
	v_mul_f32_e32 v76, v76, v210
	v_mul_f32_e32 v77, v77, v211
	v_mul_f32_e32 v74, v78, v74
	v_mul_f32_e32 v75, v79, v75
	v_mul_f32_e32 v76, v80, v76
	v_mul_f32_e32 v77, v81, v77
	v_cvt_pk_bf16_f32 v218, v74, v75
	v_cvt_pk_bf16_f32 v219, v76, v77
	ds_bpermute_b32 v218, v250, v218
	ds_bpermute_b32 v219, v250, v219
	s_waitcnt lgkmcnt(2)
	v_add_u32_e32 v221, 0xdc000, v247
	s_and_saveexec_b64 s[30:31], s[24:25]
	global_store_dwordx2 v221, v[212:213], s[10:11]
	s_mov_b64 exec, s[30:31]
	s_waitcnt lgkmcnt(0)
	v_add_u32_e32 v251, 0xf2000, v247
	s_and_saveexec_b64 s[30:31], s[26:27]
	global_store_dwordx2 v251, v[218:219], s[10:11]
	s_mov_b64 exec, s[30:31]
	s_waitcnt vmcnt(4)
	ds_write_b64 v243, v[72:73]
	ds_write_b64 v243, v[64:65] offset:256
	ds_write_b64 v243, v[56:57] offset:512
	ds_write_b64 v243, v[48:49] offset:768
	v_cndmask_b32_e64 v170, v170, v198, s[6:7]
	v_cndmask_b32_e64 v171, v171, v199, s[6:7]
	v_add_u32_e32 v220, s48, v227
	v_cmp_lt_i32_e32 vcc, 0, v220
	s_nop 1
	v_cndmask_b32_e32 v170, 0, v170, vcc
	v_cndmask_b32_e32 v171, 0, v171, vcc
	v_cmp_gt_i32_e32 vcc, s28, v220
	s_nop 1
	v_cndmask_b32_e32 v178, 0, v178, vcc
	v_cndmask_b32_e32 v179, 0, v179, vcc
	v_pk_fma_f32 v[202:203], v[138:139], v[170:171], v[150:151]
	v_pk_fma_f32 v[70:71], v[70:71], v[142:143], v[202:203]
	v_pk_fma_f32 v[70:71], v[146:147], v[178:179], v[70:71]
	ds_read_b64 v[170:171], v244
	ds_read_b64 v[178:179], v243 offset:16
	ds_read_b64 v[198:199], v245 offset:24
	v_add_u32_e32 v220, s48, v231
	v_cmp_lt_i32_e32 vcc, 0, v220
	s_nop 1
	v_cndmask_b32_e32 v172, 0, v172, vcc
	v_cndmask_b32_e32 v173, 0, v173, vcc
	v_cmp_gt_i32_e32 vcc, s28, v220
	s_nop 1
	v_cndmask_b32_e32 v180, 0, v180, vcc
	v_cndmask_b32_e32 v181, 0, v181, vcc
	v_pk_fma_f32 v[202:203], v[138:139], v[172:173], v[150:151]
	v_pk_fma_f32 v[62:63], v[62:63], v[142:143], v[202:203]
	v_pk_fma_f32 v[62:63], v[146:147], v[180:181], v[62:63]
	ds_read_b64 v[172:173], v244 offset:256
	ds_read_b64 v[180:181], v243 offset:272
	v_add_u32_e32 v220, s48, v232
	v_cmp_lt_i32_e32 vcc, 0, v220
	s_nop 1
	v_cndmask_b32_e32 v174, 0, v174, vcc
	v_cndmask_b32_e32 v175, 0, v175, vcc
	v_cmp_gt_i32_e32 vcc, s28, v220
	s_nop 1
	v_cndmask_b32_e32 v194, 0, v194, vcc
	v_cndmask_b32_e32 v195, 0, v195, vcc
	v_pk_fma_f32 v[202:203], v[138:139], v[174:175], v[150:151]
	v_pk_fma_f32 v[54:55], v[54:55], v[142:143], v[202:203]
	v_pk_fma_f32 v[54:55], v[146:147], v[194:195], v[54:55]
	ds_read_b64 v[174:175], v244 offset:512
	ds_read_b64 v[194:195], v243 offset:528
	v_cndmask_b32_e64 v196, v196, v200, s[4:5]
	v_cndmask_b32_e64 v197, v197, v201, s[4:5]
	v_add_u32_e32 v220, s48, v233
	v_cmp_lt_i32_e32 vcc, 0, v220
	s_nop 1
	v_cndmask_b32_e32 v176, 0, v176, vcc
	v_cndmask_b32_e32 v177, 0, v177, vcc
	v_cmp_gt_i32_e32 vcc, s28, v220
	s_nop 1
	v_cndmask_b32_e32 v196, 0, v196, vcc
	v_cndmask_b32_e32 v197, 0, v197, vcc
	v_pk_fma_f32 v[202:203], v[138:139], v[176:177], v[150:151]
	v_pk_fma_f32 v[46:47], v[46:47], v[142:143], v[202:203]
	v_pk_fma_f32 v[46:47], v[146:147], v[196:197], v[46:47]
	ds_read_b64 v[176:177], v244 offset:768
	ds_read_b64 v[196:197], v243 offset:784
	ds_read_b64 v[200:201], v238 offset:2072
	ds_write_b64 v243, v[66:67]
	ds_write_b64 v243, v[58:59] offset:256
	ds_write_b64 v243, v[50:51] offset:512
	ds_write_b64 v243, v[42:43] offset:768
	s_waitcnt lgkmcnt(11)
	v_cndmask_b32_e64 v170, v170, v198, s[6:7]
	v_cndmask_b32_e64 v171, v171, v199, s[6:7]
	v_add_u32_e32 v220, s48, v227
	v_cmp_lt_i32_e32 vcc, 0, v220
	s_nop 1
	v_cndmask_b32_e32 v170, 0, v170, vcc
	v_cndmask_b32_e32 v171, 0, v171, vcc
	v_cmp_gt_i32_e32 vcc, s28, v220
	s_nop 1
	v_cndmask_b32_e32 v178, 0, v178, vcc
	v_cndmask_b32_e32 v179, 0, v179, vcc
	v_pk_fma_f32 v[202:203], v[140:141], v[170:171], v[152:153]
	v_pk_fma_f32 v[72:73], v[72:73], v[144:145], v[202:203]
	v_pk_fma_f32 v[72:73], v[148:149], v[178:179], v[72:73]
	ds_read_b64 v[170:171], v244
	ds_read_b64 v[178:179], v243 offset:16
	ds_read_b64 v[198:199], v245 offset:48
	s_waitcnt lgkmcnt(12)
; #define PG8_LAS __attribute__((address_space(3)))
; __device__ __forceinline__ float dpp_ror1(float v) { return __builtin_bit_cast(float, __builtin_amdgcn_update_dpp(0, __builtin_bit_cast(int, v), 0x121, 0xf, 0xf, false)); }
; __device__ __forceinline__ float dpp_ror15(float v) { return __builtin_bit_cast(float, __builtin_amdgcn_update_dpp(0, __builtin_bit_cast(int, v), 0x12F, 0xf, 0xf, false)); }
;     __device__ __forceinline__ void operator()(const f32x4 (&acc)[2][2][4][2], const Unit& u, int wr, int wc, int fr, int fq) const {
;     ...
;             for (int ai = 0; ai < 2; ++ai) { const int blk = ai * 2 + wr;
; #pragma unroll
;                 for (int m = 0; m < 4; ++m) { const int r = 128 * ai + 64 * wr + 16 * m + fr, t = tstart + r;
;                     const bool upok = t >= 1, dnok = (t + 1) < T, store_ok = (r >= vlo) && (r < vhi) && (t < T);
;                     f32x4 res[2];
; #pragma unroll
;                     for (int bj = 0; bj < 2; ++bj) { const f32x4 cur = acc[ai][bj][m][n];
;                         f32x4 su = cur, sd = cur;
;                         if (m > 0) { if (fr == 15) su = acc[ai][bj][m > 0 ? m - 1 : 0][n]; }
;                         if (m < 3) { if (fr == 0) sd = acc[ai][bj][m < 3 ? m + 1 : 3][n]; }
;                         f32x4 up, dn;
;                         up[0] = dpp_ror1(su[0]); up[1] = dpp_ror1(su[1]); up[2] = dpp_ror1(su[2]); up[3] = dpp_ror1(su[3]);
;                         dn[0] = dpp_ror15(sd[0]); dn[1] = dpp_ror15(sd[1]); dn[2] = dpp_ror15(sd[2]); dn[3] = dpp_ror15(sd[3]);
;                         if (m == 0) { f32x4 halo = zero4; if (blk > 0) halo = *(const PG8_LAS f32x4*)(xb + (((((blk - 1) * 2 + 1) * 4 + wc) * 4 + fq) * 16 + (bj * 2 + n) * 4)); if (fr == 0) up = halo; }
;                         if (m == 3) { f32x4 halo = zero4; if (blk < 3) halo = *(const PG8_LAS f32x4*)(xb + (((((blk + 1) * 2 + 0) * 4 + wc) * 4 + fq) * 16 + (bj * 2 + n) * 4)); if (fr == 15) dn = halo; }
;                         if (edge) { if (!upok) up = zero4; if (!dnok) dn = zero4; }
;                         res[bj] = bb[bj] + w0[bj] * up + w1[bj] * cur + w2[bj] * dn; }
	v_add_u32_e32 v220, s48, v231
	v_cmp_lt_i32_e32 vcc, 0, v220
	s_nop 1
	v_cndmask_b32_e32 v172, 0, v172, vcc
	v_cndmask_b32_e32 v173, 0, v173, vcc
	v_cmp_gt_i32_e32 vcc, s28, v220
	s_nop 1
	v_cndmask_b32_e32 v180, 0, v180, vcc
	v_cndmask_b32_e32 v181, 0, v181, vcc
	v_pk_fma_f32 v[202:203], v[140:141], v[172:173], v[152:153]
	v_pk_fma_f32 v[64:65], v[64:65], v[144:145], v[202:203]
	v_pk_fma_f32 v[64:65], v[148:149], v[180:181], v[64:65]
	ds_read_b64 v[172:173], v244 offset:256
	ds_read_b64 v[180:181], v243 offset:272
	s_waitcnt lgkmcnt(12)
	v_add_u32_e32 v220, s48, v232
	v_cmp_lt_i32_e32 vcc, 0, v220
	s_nop 1
	v_cndmask_b32_e32 v174, 0, v174, vcc
	v_cndmask_b32_e32 v175, 0, v175, vcc
	v_cmp_gt_i32_e32 vcc, s28, v220
	s_nop 1
	v_cndmask_b32_e32 v194, 0, v194, vcc
	v_cndmask_b32_e32 v195, 0, v195, vcc
	v_pk_fma_f32 v[202:203], v[140:141], v[174:175], v[152:153]
	v_pk_fma_f32 v[56:57], v[56:57], v[144:145], v[202:203]
	v_pk_fma_f32 v[56:57], v[148:149], v[194:195], v[56:57]
	ds_read_b64 v[174:175], v244 offset:512
	ds_read_b64 v[194:195], v243 offset:528
	s_waitcnt lgkmcnt(11)
	v_cndmask_b32_e64 v196, v196, v200, s[4:5]
	v_cndmask_b32_e64 v197, v197, v201, s[4:5]
	v_add_u32_e32 v220, s48, v233
	v_cmp_lt_i32_e32 vcc, 0, v220
	s_nop 1
	v_cndmask_b32_e32 v176, 0, v176, vcc
	v_cndmask_b32_e32 v177, 0, v177, vcc
	v_cmp_gt_i32_e32 vcc, s28, v220
	s_nop 1
	v_cndmask_b32_e32 v196, 0, v196, vcc
	v_cndmask_b32_e32 v197, 0, v197, vcc
	v_pk_fma_f32 v[202:203], v[140:141], v[176:177], v[152:153]
	v_pk_fma_f32 v[48:49], v[48:49], v[144:145], v[202:203]
	v_pk_fma_f32 v[48:49], v[148:149], v[196:197], v[48:49]
	ds_read_b64 v[176:177], v244 offset:768
	ds_read_b64 v[196:197], v243 offset:784
	ds_read_b64 v[200:201], v238 offset:2096
	ds_write_b64 v243, v[68:69]
	ds_write_b64 v243, v[60:61] offset:256
	ds_write_b64 v243, v[52:53] offset:512
	ds_write_b64 v243, v[44:45] offset:768
	s_waitcnt lgkmcnt(11)
	v_cndmask_b32_e64 v170, v170, v198, s[6:7]
	v_cndmask_b32_e64 v171, v171, v199, s[6:7]
	v_add_u32_e32 v220, s48, v227
	v_cmp_lt_i32_e32 vcc, 0, v220
	s_nop 1
	v_cndmask_b32_e32 v170, 0, v170, vcc
	v_cndmask_b32_e32 v171, 0, v171, vcc
	v_cmp_gt_i32_e32 vcc, s28, v220
	s_nop 1
	v_cndmask_b32_e32 v178, 0, v178, vcc
	v_cndmask_b32_e32 v179, 0, v179, vcc
	v_pk_fma_f32 v[202:203], v[154:155], v[170:171], v[166:167]
	v_pk_fma_f32 v[66:67], v[66:67], v[158:159], v[202:203]
	v_pk_fma_f32 v[66:67], v[162:163], v[178:179], v[66:67]
	ds_read_b64 v[170:171], v244
	ds_read_b64 v[178:179], v243 offset:16
	ds_read_b64 v[198:199], v245 offset:56
	s_waitcnt lgkmcnt(12)
	v_add_u32_e32 v220, s48, v231
	v_cmp_lt_i32_e32 vcc, 0, v220
	s_nop 1
	v_cndmask_b32_e32 v172, 0, v172, vcc
	v_cndmask_b32_e32 v173, 0, v173, vcc
	v_cmp_gt_i32_e32 vcc, s28, v220
	s_nop 1
	v_cndmask_b32_e32 v180, 0, v180, vcc
	v_cndmask_b32_e32 v181, 0, v181, vcc
	v_pk_fma_f32 v[202:203], v[154:155], v[172:173], v[166:167]
	v_pk_fma_f32 v[58:59], v[58:59], v[158:159], v[202:203]
	v_pk_fma_f32 v[58:59], v[162:163], v[180:181], v[58:59]
	ds_read_b64 v[172:173], v244 offset:256
	ds_read_b64 v[180:181], v243 offset:272
	s_waitcnt lgkmcnt(12)
	v_add_u32_e32 v220, s48, v232
	v_cmp_lt_i32_e32 vcc, 0, v220
	s_nop 1
	v_cndmask_b32_e32 v174, 0, v174, vcc
	v_cndmask_b32_e32 v175, 0, v175, vcc
	v_cmp_gt_i32_e32 vcc, s28, v220
	s_nop 1
	v_cndmask_b32_e32 v194, 0, v194, vcc
	v_cndmask_b32_e32 v195, 0, v195, vcc
	v_pk_fma_f32 v[202:203], v[154:155], v[174:175], v[166:167]
	v_pk_fma_f32 v[50:51], v[50:51], v[158:159], v[202:203]
	v_pk_fma_f32 v[50:51], v[162:163], v[194:195], v[50:51]
	ds_read_b64 v[174:175], v244 offset:512
	ds_read_b64 v[194:195], v243 offset:528
	s_waitcnt lgkmcnt(11)
	v_cndmask_b32_e64 v196, v196, v200, s[4:5]
	v_cndmask_b32_e64 v197, v197, v201, s[4:5]
	v_add_u32_e32 v220, s48, v233
	v_cmp_lt_i32_e32 vcc, 0, v220
	s_nop 1
	v_cndmask_b32_e32 v176, 0, v176, vcc
	v_cndmask_b32_e32 v177, 0, v177, vcc
	v_cmp_gt_i32_e32 vcc, s28, v220
	s_nop 1
	v_cndmask_b32_e32 v196, 0, v196, vcc
	v_cndmask_b32_e32 v197, 0, v197, vcc
	v_pk_fma_f32 v[202:203], v[154:155], v[176:177], v[166:167]
	v_pk_fma_f32 v[42:43], v[42:43], v[158:159], v[202:203]
	v_pk_fma_f32 v[42:43], v[162:163], v[196:197], v[42:43]
	ds_read_b64 v[176:177], v244 offset:768
	ds_read_b64 v[196:197], v243 offset:784
	ds_read_b64 v[200:201], v238 offset:2104
	ds_write_b64 v243, v[30:31]
	ds_write_b64 v243, v[22:23] offset:256
	ds_write_b64 v243, v[14:15] offset:512
	ds_write_b64 v243, v[6:7] offset:768
	s_waitcnt lgkmcnt(11)
	v_cndmask_b32_e64 v170, v170, v198, s[6:7]
	v_cndmask_b32_e64 v171, v171, v199, s[6:7]
	v_add_u32_e32 v220, s48, v227
	v_cmp_lt_i32_e32 vcc, 0, v220
	s_nop 1
	v_cndmask_b32_e32 v170, 0, v170, vcc
	v_cndmask_b32_e32 v171, 0, v171, vcc
	v_cmp_gt_i32_e32 vcc, s28, v220
	s_nop 1
	v_cndmask_b32_e32 v178, 0, v178, vcc
	v_cndmask_b32_e32 v179, 0, v179, vcc
	v_pk_fma_f32 v[202:203], v[156:157], v[170:171], v[168:169]
	v_pk_fma_f32 v[68:69], v[68:69], v[160:161], v[202:203]
	v_pk_fma_f32 v[68:69], v[164:165], v[178:179], v[68:69]
	ds_read_b64 v[170:171], v244
	ds_read_b64 v[178:179], v243 offset:16
	ds_read_b64 v[198:199], v238 offset:3088
	s_waitcnt lgkmcnt(12)
	v_add_u32_e32 v220, s48, v231
	v_cmp_lt_i32_e32 vcc, 0, v220
	s_nop 1
	v_cndmask_b32_e32 v172, 0, v172, vcc
	v_cndmask_b32_e32 v173, 0, v173, vcc
	v_cmp_gt_i32_e32 vcc, s28, v220
	s_nop 1
	v_cndmask_b32_e32 v180, 0, v180, vcc
	v_cndmask_b32_e32 v181, 0, v181, vcc
	v_pk_fma_f32 v[202:203], v[156:157], v[172:173], v[168:169]
	v_pk_fma_f32 v[60:61], v[60:61], v[160:161], v[202:203]
	v_pk_fma_f32 v[60:61], v[164:165], v[180:181], v[60:61]
	ds_read_b64 v[172:173], v244 offset:256
	ds_read_b64 v[180:181], v243 offset:272
	s_waitcnt lgkmcnt(12)
; #define PG8_LAS __attribute__((address_space(3)))
;     __device__ __forceinline__ void operator()(const f32x4 (&acc)[2][2][4][2], const Unit& u, int wr, int wc, int fr, int fq) const {
;     ...
;         for (int n = 0; n < 2; ++n) {
;             if (n == 1) {
; #pragma unroll
;                 for (int bj = 0; bj < 2; ++bj) { const int col = bj * 2816 + ch0 + 4;
;                     w0[bj] = *(const f32x4*)(cw + col); w1[bj] = *(const f32x4*)(cw + 5632 + col); w2[bj] = *(const f32x4*)(cw + 11264 + col); bb[bj] = *(const f32x4*)(cb + col); } }
; #pragma unroll
;             for (int ai = 0; ai < 2; ++ai) { const int blk = ai * 2 + wr;
; #pragma unroll
;                 for (int m = 0; m < 4; ++m) { const int r = 128 * ai + 64 * wr + 16 * m + fr, t = tstart + r;
;                     const bool upok = t >= 1, dnok = (t + 1) < T, store_ok = (r >= vlo) && (r < vhi) && (t < T);
;                     f32x4 res[2];
; #pragma unroll
;                     for (int bj = 0; bj < 2; ++bj) { const f32x4 cur = acc[ai][bj][m][n];
;                         f32x4 su = cur, sd = cur;
;                         if (m > 0) { if (fr == 15) su = acc[ai][bj][m > 0 ? m - 1 : 0][n]; }
;                         if (m < 3) { if (fr == 0) sd = acc[ai][bj][m < 3 ? m + 1 : 3][n]; }
;                         f32x4 up, dn;
;                         up[0] = dpp_ror1(su[0]); up[1] = dpp_ror1(su[1]); up[2] = dpp_ror1(su[2]); up[3] = dpp_ror1(su[3]);
;                         dn[0] = dpp_ror15(sd[0]); dn[1] = dpp_ror15(sd[1]); dn[2] = dpp_ror15(sd[2]); dn[3] = dpp_ror15(sd[3]);
;                         if (m == 0) { f32x4 halo = zero4; if (blk > 0) halo = *(const PG8_LAS f32x4*)(xb + (((((blk - 1) * 2 + 1) * 4 + wc) * 4 + fq) * 16 + (bj * 2 + n) * 4)); if (fr == 0) up = halo; }
;                         if (m == 3) { f32x4 halo = zero4; if (blk < 3) halo = *(const PG8_LAS f32x4*)(xb + (((((blk + 1) * 2 + 0) * 4 + wc) * 4 + fq) * 16 + (bj * 2 + n) * 4)); if (fr == 15) dn = halo; }
;                         if (edge) { if (!upok) up = zero4; if (!dnok) dn = zero4; }
;                         res[bj] = bb[bj] + w0[bj] * up + w1[bj] * cur + w2[bj] * dn; }
;                     if (store_ok) {
;                         float o[4];
; #pragma unroll
;                         for (int j = 0; j < 4; ++j) { const float gg = res[1][j]; o[j] = gg * __builtin_amdgcn_rcpf(1.f + __expf(-gg)) * res[0][j]; }
	v_add_u32_e32 v220, s48, v232
	v_cmp_lt_i32_e32 vcc, 0, v220
	s_nop 1
	v_cndmask_b32_e32 v174, 0, v174, vcc
	v_cndmask_b32_e32 v175, 0, v175, vcc
	v_cmp_gt_i32_e32 vcc, s28, v220
	s_nop 1
	v_cndmask_b32_e32 v194, 0, v194, vcc
	v_cndmask_b32_e32 v195, 0, v195, vcc
	v_pk_fma_f32 v[202:203], v[156:157], v[174:175], v[168:169]
	v_pk_fma_f32 v[52:53], v[52:53], v[160:161], v[202:203]
	v_pk_fma_f32 v[52:53], v[164:165], v[194:195], v[52:53]
	ds_read_b64 v[174:175], v244 offset:512
	ds_read_b64 v[194:195], v243 offset:528
	s_waitcnt lgkmcnt(11)
	v_cndmask_b32_e64 v196, v196, v200, s[4:5]
	v_cndmask_b32_e64 v197, v197, v201, s[4:5]
	v_add_u32_e32 v220, s48, v233
	v_cmp_lt_i32_e32 vcc, 0, v220
	s_nop 1
	v_cndmask_b32_e32 v176, 0, v176, vcc
	v_cndmask_b32_e32 v177, 0, v177, vcc
	v_cmp_gt_i32_e32 vcc, s28, v220
	s_nop 1
	v_cndmask_b32_e32 v196, 0, v196, vcc
	v_cndmask_b32_e32 v197, 0, v197, vcc
	v_pk_fma_f32 v[202:203], v[156:157], v[176:177], v[168:169]
	v_pk_fma_f32 v[44:45], v[44:45], v[160:161], v[202:203]
	v_pk_fma_f32 v[44:45], v[164:165], v[196:197], v[44:45]
	ds_read_b64 v[176:177], v244 offset:768
	ds_read_b64 v[196:197], v243 offset:784
	ds_read_b64 v[200:201], v246 offset:16
	v_mul_f32_e32 v208, 0xbfb8aa3b, v66
	v_mul_f32_e32 v209, 0xbfb8aa3b, v67
	v_mul_f32_e32 v210, 0xbfb8aa3b, v68
	v_mul_f32_e32 v211, 0xbfb8aa3b, v69
	v_exp_f32_e32 v208, v208
	v_exp_f32_e32 v209, v209
	v_exp_f32_e32 v210, v210
	v_exp_f32_e32 v211, v211
	v_add_f32_e32 v208, 1.0, v208
	v_add_f32_e32 v209, 1.0, v209
	v_add_f32_e32 v210, 1.0, v210
	v_add_f32_e32 v211, 1.0, v211
	v_rcp_f32_e32 v208, v208
	v_rcp_f32_e32 v209, v209
	v_rcp_f32_e32 v210, v210
	v_rcp_f32_e32 v211, v211
	v_mul_f32_e32 v66, v66, v208
	v_mul_f32_e32 v67, v67, v209
	v_mul_f32_e32 v68, v68, v210
	v_mul_f32_e32 v69, v69, v211
	v_mul_f32_e32 v66, v70, v66
	v_mul_f32_e32 v67, v71, v67
	v_mul_f32_e32 v68, v72, v68
	v_mul_f32_e32 v69, v73, v69
	v_cvt_pk_bf16_f32 v212, v66, v67
	v_cvt_pk_bf16_f32 v213, v68, v69
	ds_bpermute_b32 v212, v250, v212
	ds_bpermute_b32 v213, v250, v213
	v_mul_f32_e32 v208, 0xbfb8aa3b, v58
	v_mul_f32_e32 v209, 0xbfb8aa3b, v59
	v_mul_f32_e32 v210, 0xbfb8aa3b, v60
	v_mul_f32_e32 v211, 0xbfb8aa3b, v61
	v_exp_f32_e32 v208, v208
	v_exp_f32_e32 v209, v209
	v_exp_f32_e32 v210, v210
	v_exp_f32_e32 v211, v211
	v_add_f32_e32 v208, 1.0, v208
	v_add_f32_e32 v209, 1.0, v209
	v_add_f32_e32 v210, 1.0, v210
	v_add_f32_e32 v211, 1.0, v211
	v_rcp_f32_e32 v208, v208
	v_rcp_f32_e32 v209, v209
	v_rcp_f32_e32 v210, v210
	v_rcp_f32_e32 v211, v211
	v_mul_f32_e32 v58, v58, v208
	v_mul_f32_e32 v59, v59, v209
	v_mul_f32_e32 v60, v60, v210
	v_mul_f32_e32 v61, v61, v211
	v_mul_f32_e32 v58, v62, v58
	v_mul_f32_e32 v59, v63, v59
	v_mul_f32_e32 v60, v64, v60
	v_mul_f32_e32 v61, v65, v61
	v_cvt_pk_bf16_f32 v218, v58, v59
	v_cvt_pk_bf16_f32 v219, v60, v61
	ds_bpermute_b32 v218, v250, v218
	ds_bpermute_b32 v219, v250, v219
	s_waitcnt lgkmcnt(2)
	v_add_u32_e32 v221, 0x0, v247
	s_and_saveexec_b64 s[30:31], s[12:13]
	global_store_dwordx2 v221, v[212:213], s[10:11] offset:8
	s_mov_b64 exec, s[30:31]
	v_mul_f32_e32 v208, 0xbfb8aa3b, v50
	v_mul_f32_e32 v209, 0xbfb8aa3b, v51
	v_mul_f32_e32 v210, 0xbfb8aa3b, v52
	v_mul_f32_e32 v211, 0xbfb8aa3b, v53
	v_exp_f32_e32 v208, v208
	v_exp_f32_e32 v209, v209
	v_exp_f32_e32 v210, v210
	v_exp_f32_e32 v211, v211
	v_add_f32_e32 v208, 1.0, v208
	v_add_f32_e32 v209, 1.0, v209
	v_add_f32_e32 v210, 1.0, v210
	v_add_f32_e32 v211, 1.0, v211
	v_rcp_f32_e32 v208, v208
	v_rcp_f32_e32 v209, v209
	v_rcp_f32_e32 v210, v210
	v_rcp_f32_e32 v211, v211
	v_mul_f32_e32 v50, v50, v208
	v_mul_f32_e32 v51, v51, v209
	v_mul_f32_e32 v52, v52, v210
	v_mul_f32_e32 v53, v53, v211
	v_mul_f32_e32 v50, v54, v50
	v_mul_f32_e32 v51, v55, v51
	v_mul_f32_e32 v52, v56, v52
	v_mul_f32_e32 v53, v57, v53
	v_cvt_pk_bf16_f32 v212, v50, v51
	v_cvt_pk_bf16_f32 v213, v52, v53
	ds_bpermute_b32 v212, v250, v212
	ds_bpermute_b32 v213, v250, v213
	s_waitcnt lgkmcnt(2)
	v_add_u32_e32 v251, 0x16000, v247
	s_and_saveexec_b64 s[30:31], s[14:15]
	global_store_dwordx2 v251, v[218:219], s[10:11] offset:8
	s_mov_b64 exec, s[30:31]
	v_mul_f32_e32 v208, 0xbfb8aa3b, v42
	v_mul_f32_e32 v209, 0xbfb8aa3b, v43
	v_mul_f32_e32 v210, 0xbfb8aa3b, v44
	v_mul_f32_e32 v211, 0xbfb8aa3b, v45
	v_exp_f32_e32 v208, v208
	v_exp_f32_e32 v209, v209
	v_exp_f32_e32 v210, v210
	v_exp_f32_e32 v211, v211
	v_add_f32_e32 v208, 1.0, v208
	v_add_f32_e32 v209, 1.0, v209
	v_add_f32_e32 v210, 1.0, v210
	v_add_f32_e32 v211, 1.0, v211
	v_rcp_f32_e32 v208, v208
	v_rcp_f32_e32 v209, v209
	v_rcp_f32_e32 v210, v210
	v_rcp_f32_e32 v211, v211
	v_mul_f32_e32 v42, v42, v208
	v_mul_f32_e32 v43, v43, v209
	v_mul_f32_e32 v44, v44, v210
	v_mul_f32_e32 v45, v45, v211
	v_mul_f32_e32 v42, v46, v42
	v_mul_f32_e32 v43, v47, v43
	v_mul_f32_e32 v44, v48, v44
	v_mul_f32_e32 v45, v49, v45
	v_cvt_pk_bf16_f32 v218, v42, v43
	v_cvt_pk_bf16_f32 v219, v44, v45
	ds_bpermute_b32 v218, v250, v218
	ds_bpermute_b32 v219, v250, v219
	s_waitcnt lgkmcnt(2)
	v_add_u32_e32 v221, 0x2c000, v247
	s_and_saveexec_b64 s[30:31], s[16:17]
	global_store_dwordx2 v221, v[212:213], s[10:11] offset:8
	s_mov_b64 exec, s[30:31]
	s_waitcnt lgkmcnt(0)
;     __device__ __forceinline__ void operator()(const f32x4 (&acc)[2][2][4][2], const Unit& u, int wr, int wc, int fr, int fq) const {
;     ...
;         for (int n = 0; n < 2; ++n) {
;             if (n == 1) {
; #pragma unroll
;                 for (int bj = 0; bj < 2; ++bj) { const int col = bj * 2816 + ch0 + 4;
;                     w0[bj] = *(const f32x4*)(cw + col); w1[bj] = *(const f32x4*)(cw + 5632 + col); w2[bj] = *(const f32x4*)(cw + 11264 + col); bb[bj] = *(const f32x4*)(cb + col); } }
; #pragma unroll
;             for (int ai = 0; ai < 2; ++ai) { const int blk = ai * 2 + wr;
; #pragma unroll
;                 for (int m = 0; m < 4; ++m) { const int r = 128 * ai + 64 * wr + 16 * m + fr, t = tstart + r;
;                     const bool upok = t >= 1, dnok = (t + 1) < T, store_ok = (r >= vlo) && (r < vhi) && (t < T);
;                     f32x4 res[2];
; #pragma unroll
;                     for (int bj = 0; bj < 2; ++bj) { const f32x4 cur = acc[ai][bj][m][n];
;                         f32x4 su = cur, sd = cur;
;                         if (m > 0) { if (fr == 15) su = acc[ai][bj][m > 0 ? m - 1 : 0][n]; }
;                         if (m < 3) { if (fr == 0) sd = acc[ai][bj][m < 3 ? m + 1 : 3][n]; }
;                         f32x4 up, dn;
;                         up[0] = dpp_ror1(su[0]); up[1] = dpp_ror1(su[1]); up[2] = dpp_ror1(su[2]); up[3] = dpp_ror1(su[3]);
;                         dn[0] = dpp_ror15(sd[0]); dn[1] = dpp_ror15(sd[1]); dn[2] = dpp_ror15(sd[2]); dn[3] = dpp_ror15(sd[3]);
;                         if (m == 0) { f32x4 halo = zero4; if (blk > 0) halo = *(const PG8_LAS f32x4*)(xb + (((((blk - 1) * 2 + 1) * 4 + wc) * 4 + fq) * 16 + (bj * 2 + n) * 4)); if (fr == 0) up = halo; }
;                         if (m == 3) { f32x4 halo = zero4; if (blk < 3) halo = *(const PG8_LAS f32x4*)(xb + (((((blk + 1) * 2 + 0) * 4 + wc) * 4 + fq) * 16 + (bj * 2 + n) * 4)); if (fr == 15) dn = halo; }
;     ...
;                     if (store_ok) {
;                         float o[4];
; #pragma unroll
;                         for (int j = 0; j < 4; ++j) { const float gg = res[1][j]; o[j] = gg * __builtin_amdgcn_rcpf(1.f + __expf(-gg)) * res[0][j]; }
;                         u32x2 w; w.x = cvt_pk_bf16(o[0], o[1]); w.y = cvt_pk_bf16(o[2], o[3]);
;                         *(u32x2*)(ACT + (size_t)(seqrow + t) * 2816 + ch0 + 4 * n) = w; } } }
	v_add_u32_e32 v251, 0x42000, v247
	s_and_saveexec_b64 s[30:31], s[18:19]
	global_store_dwordx2 v251, v[218:219], s[10:11] offset:8
	s_mov_b64 exec, s[30:31]
	ds_write_b64 v243, v[32:33]
	ds_write_b64 v243, v[24:25] offset:256
	ds_write_b64 v243, v[16:17] offset:512
	ds_write_b64 v243, v[8:9] offset:768
	v_cndmask_b32_e64 v170, v170, v198, s[6:7]
	v_cndmask_b32_e64 v171, v171, v199, s[6:7]
	v_add_u32_e32 v220, s48, v234
	v_cmp_lt_i32_e32 vcc, 0, v220
	s_nop 1
	v_cndmask_b32_e32 v170, 0, v170, vcc
	v_cndmask_b32_e32 v171, 0, v171, vcc
	v_cmp_gt_i32_e32 vcc, s28, v220
	s_nop 1
	v_cndmask_b32_e32 v178, 0, v178, vcc
	v_cndmask_b32_e32 v179, 0, v179, vcc
	v_pk_fma_f32 v[202:203], v[138:139], v[170:171], v[150:151]
	v_pk_fma_f32 v[30:31], v[30:31], v[142:143], v[202:203]
	v_pk_fma_f32 v[30:31], v[146:147], v[178:179], v[30:31]
	ds_read_b64 v[170:171], v244
	ds_read_b64 v[178:179], v243 offset:16
	ds_read_b64 v[198:199], v238 offset:3096
	v_add_u32_e32 v220, s48, v235
	v_cmp_lt_i32_e32 vcc, 0, v220
	s_nop 1
	v_cndmask_b32_e32 v172, 0, v172, vcc
	v_cndmask_b32_e32 v173, 0, v173, vcc
	v_cmp_gt_i32_e32 vcc, s28, v220
	s_nop 1
	v_cndmask_b32_e32 v180, 0, v180, vcc
	v_cndmask_b32_e32 v181, 0, v181, vcc
	v_pk_fma_f32 v[202:203], v[138:139], v[172:173], v[150:151]
	v_pk_fma_f32 v[22:23], v[22:23], v[142:143], v[202:203]
	v_pk_fma_f32 v[22:23], v[146:147], v[180:181], v[22:23]
	ds_read_b64 v[172:173], v244 offset:256
	ds_read_b64 v[180:181], v243 offset:272
	v_add_u32_e32 v220, s48, v236
	v_cmp_lt_i32_e32 vcc, 0, v220
	s_nop 1
	v_cndmask_b32_e32 v174, 0, v174, vcc
	v_cndmask_b32_e32 v175, 0, v175, vcc
	v_cmp_gt_i32_e32 vcc, s28, v220
	s_nop 1
	v_cndmask_b32_e32 v194, 0, v194, vcc
	v_cndmask_b32_e32 v195, 0, v195, vcc
	v_pk_fma_f32 v[202:203], v[138:139], v[174:175], v[150:151]
	v_pk_fma_f32 v[14:15], v[14:15], v[142:143], v[202:203]
	v_pk_fma_f32 v[14:15], v[146:147], v[194:195], v[14:15]
	ds_read_b64 v[174:175], v244 offset:512
	ds_read_b64 v[194:195], v243 offset:528
	v_cndmask_b32_e64 v196, v196, v200, s[4:5]
	v_cndmask_b32_e64 v197, v197, v201, s[4:5]
	v_add_u32_e32 v220, s48, v237
	v_cmp_lt_i32_e32 vcc, 0, v220
	s_nop 1
	v_cndmask_b32_e32 v176, 0, v176, vcc
	v_cndmask_b32_e32 v177, 0, v177, vcc
	v_cmp_gt_i32_e32 vcc, s28, v220
	s_nop 1
	v_cndmask_b32_e32 v196, 0, v196, vcc
	v_cndmask_b32_e32 v197, 0, v197, vcc
	v_pk_fma_f32 v[202:203], v[138:139], v[176:177], v[150:151]
	v_pk_fma_f32 v[6:7], v[6:7], v[142:143], v[202:203]
	v_pk_fma_f32 v[6:7], v[146:147], v[196:197], v[6:7]
	ds_read_b64 v[176:177], v244 offset:768
	ds_read_b64 v[196:197], v243 offset:784
	ds_read_b64 v[200:201], v246 offset:24
	ds_write_b64 v243, v[26:27]
	ds_write_b64 v243, v[18:19] offset:256
	ds_write_b64 v243, v[10:11] offset:512
	ds_write_b64 v243, v[2:3] offset:768
	s_waitcnt lgkmcnt(11)
	v_cndmask_b32_e64 v170, v170, v198, s[6:7]
	v_cndmask_b32_e64 v171, v171, v199, s[6:7]
	v_add_u32_e32 v220, s48, v234
	v_cmp_lt_i32_e32 vcc, 0, v220
	s_nop 1
	v_cndmask_b32_e32 v170, 0, v170, vcc
	v_cndmask_b32_e32 v171, 0, v171, vcc
	v_cmp_gt_i32_e32 vcc, s28, v220
	s_nop 1
	v_cndmask_b32_e32 v178, 0, v178, vcc
	v_cndmask_b32_e32 v179, 0, v179, vcc
	v_pk_fma_f32 v[202:203], v[140:141], v[170:171], v[152:153]
	v_pk_fma_f32 v[32:33], v[32:33], v[144:145], v[202:203]
	v_pk_fma_f32 v[32:33], v[148:149], v[178:179], v[32:33]
	ds_read_b64 v[170:171], v244
	ds_read_b64 v[178:179], v243 offset:16
	ds_read_b64 v[198:199], v238 offset:3120
	s_waitcnt lgkmcnt(12)
	v_add_u32_e32 v220, s48, v235
	v_cmp_lt_i32_e32 vcc, 0, v220
	s_nop 1
	v_cndmask_b32_e32 v172, 0, v172, vcc
	v_cndmask_b32_e32 v173, 0, v173, vcc
	v_cmp_gt_i32_e32 vcc, s28, v220
	s_nop 1
	v_cndmask_b32_e32 v180, 0, v180, vcc
	v_cndmask_b32_e32 v181, 0, v181, vcc
	v_pk_fma_f32 v[202:203], v[140:141], v[172:173], v[152:153]
	v_pk_fma_f32 v[24:25], v[24:25], v[144:145], v[202:203]
	v_pk_fma_f32 v[24:25], v[148:149], v[180:181], v[24:25]
	ds_read_b64 v[172:173], v244 offset:256
	ds_read_b64 v[180:181], v243 offset:272
	s_waitcnt lgkmcnt(12)
	v_add_u32_e32 v220, s48, v236
	v_cmp_lt_i32_e32 vcc, 0, v220
	s_nop 1
	v_cndmask_b32_e32 v174, 0, v174, vcc
	v_cndmask_b32_e32 v175, 0, v175, vcc
	v_cmp_gt_i32_e32 vcc, s28, v220
	s_nop 1
	v_cndmask_b32_e32 v194, 0, v194, vcc
	v_cndmask_b32_e32 v195, 0, v195, vcc
	v_pk_fma_f32 v[202:203], v[140:141], v[174:175], v[152:153]
	v_pk_fma_f32 v[16:17], v[16:17], v[144:145], v[202:203]
	v_pk_fma_f32 v[16:17], v[148:149], v[194:195], v[16:17]
	ds_read_b64 v[174:175], v244 offset:512
	ds_read_b64 v[194:195], v243 offset:528
	s_waitcnt lgkmcnt(11)
	v_cndmask_b32_e64 v196, v196, v200, s[4:5]
	v_cndmask_b32_e64 v197, v197, v201, s[4:5]
	v_add_u32_e32 v220, s48, v237
	v_cmp_lt_i32_e32 vcc, 0, v220
	s_nop 1
	v_cndmask_b32_e32 v176, 0, v176, vcc
	v_cndmask_b32_e32 v177, 0, v177, vcc
	v_cmp_gt_i32_e32 vcc, s28, v220
	s_nop 1
	v_cndmask_b32_e32 v196, 0, v196, vcc
	v_cndmask_b32_e32 v197, 0, v197, vcc
	v_pk_fma_f32 v[202:203], v[140:141], v[176:177], v[152:153]
	v_pk_fma_f32 v[8:9], v[8:9], v[144:145], v[202:203]
	v_pk_fma_f32 v[8:9], v[148:149], v[196:197], v[8:9]
	ds_read_b64 v[176:177], v244 offset:768
	ds_read_b64 v[196:197], v243 offset:784
	ds_read_b64 v[200:201], v246 offset:48
	ds_write_b64 v243, v[28:29]
	ds_write_b64 v243, v[20:21] offset:256
	ds_write_b64 v243, v[12:13] offset:512
	ds_write_b64 v243, v[4:5] offset:768
	s_waitcnt lgkmcnt(11)
; #define PG8_LAS __attribute__((address_space(3)))
; __device__ __forceinline__ float dpp_ror1(float v) { return __builtin_bit_cast(float, __builtin_amdgcn_update_dpp(0, __builtin_bit_cast(int, v), 0x121, 0xf, 0xf, false)); }
; __device__ __forceinline__ float dpp_ror15(float v) { return __builtin_bit_cast(float, __builtin_amdgcn_update_dpp(0, __builtin_bit_cast(int, v), 0x12F, 0xf, 0xf, false)); }
;     __device__ __forceinline__ void operator()(const f32x4 (&acc)[2][2][4][2], const Unit& u, int wr, int wc, int fr, int fq) const {
;     ...
;             for (int ai = 0; ai < 2; ++ai) { const int blk = ai * 2 + wr;
; #pragma unroll
;                 for (int m = 0; m < 4; ++m) { const int r = 128 * ai + 64 * wr + 16 * m + fr, t = tstart + r;
;                     const bool upok = t >= 1, dnok = (t + 1) < T, store_ok = (r >= vlo) && (r < vhi) && (t < T);
;                     f32x4 res[2];
; #pragma unroll
;                     for (int bj = 0; bj < 2; ++bj) { const f32x4 cur = acc[ai][bj][m][n];
;                         f32x4 su = cur, sd = cur;
;                         if (m > 0) { if (fr == 15) su = acc[ai][bj][m > 0 ? m - 1 : 0][n]; }
;                         if (m < 3) { if (fr == 0) sd = acc[ai][bj][m < 3 ? m + 1 : 3][n]; }
;                         f32x4 up, dn;
;                         up[0] = dpp_ror1(su[0]); up[1] = dpp_ror1(su[1]); up[2] = dpp_ror1(su[2]); up[3] = dpp_ror1(su[3]);
;                         dn[0] = dpp_ror15(sd[0]); dn[1] = dpp_ror15(sd[1]); dn[2] = dpp_ror15(sd[2]); dn[3] = dpp_ror15(sd[3]);
;                         if (m == 0) { f32x4 halo = zero4; if (blk > 0) halo = *(const PG8_LAS f32x4*)(xb + (((((blk - 1) * 2 + 1) * 4 + wc) * 4 + fq) * 16 + (bj * 2 + n) * 4)); if (fr == 0) up = halo; }
;                         if (m == 3) { f32x4 halo = zero4; if (blk < 3) halo = *(const PG8_LAS f32x4*)(xb + (((((blk + 1) * 2 + 0) * 4 + wc) * 4 + fq) * 16 + (bj * 2 + n) * 4)); if (fr == 15) dn = halo; }
;                         if (edge) { if (!upok) up = zero4; if (!dnok) dn = zero4; }
;                         res[bj] = bb[bj] + w0[bj] * up + w1[bj] * cur + w2[bj] * dn; }
	v_cndmask_b32_e64 v170, v170, v198, s[6:7]
	v_cndmask_b32_e64 v171, v171, v199, s[6:7]
	v_add_u32_e32 v220, s48, v234
	v_cmp_lt_i32_e32 vcc, 0, v220
	s_nop 1
	v_cndmask_b32_e32 v170, 0, v170, vcc
	v_cndmask_b32_e32 v171, 0, v171, vcc
	v_cmp_gt_i32_e32 vcc, s28, v220
	s_nop 1
	v_cndmask_b32_e32 v178, 0, v178, vcc
	v_cndmask_b32_e32 v179, 0, v179, vcc
	v_pk_fma_f32 v[202:203], v[154:155], v[170:171], v[166:167]
	v_pk_fma_f32 v[26:27], v[26:27], v[158:159], v[202:203]
	v_pk_fma_f32 v[26:27], v[162:163], v[178:179], v[26:27]
	ds_read_b64 v[170:171], v244
	ds_read_b64 v[178:179], v243 offset:16
	ds_read_b64 v[198:199], v238 offset:3128
	s_waitcnt lgkmcnt(12)
	v_add_u32_e32 v220, s48, v235
	v_cmp_lt_i32_e32 vcc, 0, v220
	s_nop 1
	v_cndmask_b32_e32 v172, 0, v172, vcc
	v_cndmask_b32_e32 v173, 0, v173, vcc
	v_cmp_gt_i32_e32 vcc, s28, v220
	s_nop 1
	v_cndmask_b32_e32 v180, 0, v180, vcc
	v_cndmask_b32_e32 v181, 0, v181, vcc
	v_pk_fma_f32 v[202:203], v[154:155], v[172:173], v[166:167]
	v_pk_fma_f32 v[18:19], v[18:19], v[158:159], v[202:203]
	v_pk_fma_f32 v[18:19], v[162:163], v[180:181], v[18:19]
	ds_read_b64 v[172:173], v244 offset:256
	ds_read_b64 v[180:181], v243 offset:272
	s_waitcnt lgkmcnt(12)
	v_add_u32_e32 v220, s48, v236
	v_cmp_lt_i32_e32 vcc, 0, v220
	s_nop 1
	v_cndmask_b32_e32 v174, 0, v174, vcc
	v_cndmask_b32_e32 v175, 0, v175, vcc
	v_cmp_gt_i32_e32 vcc, s28, v220
	s_nop 1
	v_cndmask_b32_e32 v194, 0, v194, vcc
	v_cndmask_b32_e32 v195, 0, v195, vcc
	v_pk_fma_f32 v[202:203], v[154:155], v[174:175], v[166:167]
	v_pk_fma_f32 v[10:11], v[10:11], v[158:159], v[202:203]
	v_pk_fma_f32 v[10:11], v[162:163], v[194:195], v[10:11]
	ds_read_b64 v[174:175], v244 offset:512
	ds_read_b64 v[194:195], v243 offset:528
	s_waitcnt lgkmcnt(11)
	v_cndmask_b32_e64 v196, v196, v200, s[4:5]
	v_cndmask_b32_e64 v197, v197, v201, s[4:5]
	v_add_u32_e32 v220, s48, v237
	v_cmp_lt_i32_e32 vcc, 0, v220
	s_nop 1
	v_cndmask_b32_e32 v176, 0, v176, vcc
	v_cndmask_b32_e32 v177, 0, v177, vcc
	v_cmp_gt_i32_e32 vcc, s28, v220
	s_nop 1
	v_cndmask_b32_e32 v196, 0, v196, vcc
	v_cndmask_b32_e32 v197, 0, v197, vcc
	v_pk_fma_f32 v[202:203], v[154:155], v[176:177], v[166:167]
	v_pk_fma_f32 v[2:3], v[2:3], v[158:159], v[202:203]
	v_pk_fma_f32 v[2:3], v[162:163], v[196:197], v[2:3]
	ds_read_b64 v[176:177], v244 offset:768
	ds_read_b64 v[196:197], v243 offset:784
	ds_read_b64 v[200:201], v246 offset:56
	s_waitcnt lgkmcnt(7)
	v_cndmask_b32_e64 v170, v170, v198, s[6:7]
	v_cndmask_b32_e64 v171, v171, v199, s[6:7]
	v_add_u32_e32 v220, s48, v234
	v_cmp_lt_i32_e32 vcc, 0, v220
	s_nop 1
	v_cndmask_b32_e32 v170, 0, v170, vcc
	v_cndmask_b32_e32 v171, 0, v171, vcc
	v_cmp_gt_i32_e32 vcc, s28, v220
	s_nop 1
	v_cndmask_b32_e32 v178, 0, v178, vcc
	v_cndmask_b32_e32 v179, 0, v179, vcc
	v_pk_fma_f32 v[202:203], v[156:157], v[170:171], v[168:169]
	v_pk_fma_f32 v[28:29], v[28:29], v[160:161], v[202:203]
	v_pk_fma_f32 v[28:29], v[164:165], v[178:179], v[28:29]
	s_waitcnt lgkmcnt(5)
	v_add_u32_e32 v220, s48, v235
	v_cmp_lt_i32_e32 vcc, 0, v220
	s_nop 1
	v_cndmask_b32_e32 v172, 0, v172, vcc
	v_cndmask_b32_e32 v173, 0, v173, vcc
	v_cmp_gt_i32_e32 vcc, s28, v220
	s_nop 1
	v_cndmask_b32_e32 v180, 0, v180, vcc
	v_cndmask_b32_e32 v181, 0, v181, vcc
	v_pk_fma_f32 v[202:203], v[156:157], v[172:173], v[168:169]
	v_pk_fma_f32 v[20:21], v[20:21], v[160:161], v[202:203]
	v_pk_fma_f32 v[20:21], v[164:165], v[180:181], v[20:21]
	s_waitcnt lgkmcnt(3)
	v_add_u32_e32 v220, s48, v236
	v_cmp_lt_i32_e32 vcc, 0, v220
	s_nop 1
	v_cndmask_b32_e32 v174, 0, v174, vcc
	v_cndmask_b32_e32 v175, 0, v175, vcc
	v_cmp_gt_i32_e32 vcc, s28, v220
	s_nop 1
	v_cndmask_b32_e32 v194, 0, v194, vcc
	v_cndmask_b32_e32 v195, 0, v195, vcc
	v_pk_fma_f32 v[202:203], v[156:157], v[174:175], v[168:169]
	v_pk_fma_f32 v[12:13], v[12:13], v[160:161], v[202:203]
	v_pk_fma_f32 v[12:13], v[164:165], v[194:195], v[12:13]
	s_waitcnt lgkmcnt(0)
; #define PG8_LAS __attribute__((address_space(3)))
; __device__ __forceinline__ unsigned cvt_pk_bf16(float lo, float hi) { unsigned r; asm volatile("v_cvt_pk_bf16_f32 %0, %1, %2" : "=v"(r) : "v"(lo), "v"(hi)); return r; }
;     __device__ __forceinline__ void operator()(const f32x4 (&acc)[2][2][4][2], const Unit& u, int wr, int wc, int fr, int fq) const {
;     ...
;                 for (int m = 0; m < 4; ++m) { const int r = 128 * ai + 64 * wr + 16 * m + fr, t = tstart + r;
;                     const bool upok = t >= 1, dnok = (t + 1) < T, store_ok = (r >= vlo) && (r < vhi) && (t < T);
;                     f32x4 res[2];
; #pragma unroll
;                     for (int bj = 0; bj < 2; ++bj) { const f32x4 cur = acc[ai][bj][m][n];
;                         f32x4 su = cur, sd = cur;
;                         if (m > 0) { if (fr == 15) su = acc[ai][bj][m > 0 ? m - 1 : 0][n]; }
;                         if (m < 3) { if (fr == 0) sd = acc[ai][bj][m < 3 ? m + 1 : 3][n]; }
;                         f32x4 up, dn;
;                         up[0] = dpp_ror1(su[0]); up[1] = dpp_ror1(su[1]); up[2] = dpp_ror1(su[2]); up[3] = dpp_ror1(su[3]);
;                         dn[0] = dpp_ror15(sd[0]); dn[1] = dpp_ror15(sd[1]); dn[2] = dpp_ror15(sd[2]); dn[3] = dpp_ror15(sd[3]);
;                         if (m == 0) { f32x4 halo = zero4; if (blk > 0) halo = *(const PG8_LAS f32x4*)(xb + (((((blk - 1) * 2 + 1) * 4 + wc) * 4 + fq) * 16 + (bj * 2 + n) * 4)); if (fr == 0) up = halo; }
;                         if (m == 3) { f32x4 halo = zero4; if (blk < 3) halo = *(const PG8_LAS f32x4*)(xb + (((((blk + 1) * 2 + 0) * 4 + wc) * 4 + fq) * 16 + (bj * 2 + n) * 4)); if (fr == 15) dn = halo; }
;                         if (edge) { if (!upok) up = zero4; if (!dnok) dn = zero4; }
;                         res[bj] = bb[bj] + w0[bj] * up + w1[bj] * cur + w2[bj] * dn; }
;                     if (store_ok) {
;                         float o[4];
; #pragma unroll
;                         for (int j = 0; j < 4; ++j) { const float gg = res[1][j]; o[j] = gg * __builtin_amdgcn_rcpf(1.f + __expf(-gg)) * res[0][j]; }
;                         u32x2 w; w.x = cvt_pk_bf16(o[0], o[1]); w.y = cvt_pk_bf16(o[2], o[3]);
;                         *(u32x2*)(ACT + (size_t)(seqrow + t) * 2816 + ch0 + 4 * n) = w; } } }
	v_cndmask_b32_e64 v196, v196, v200, s[4:5]
	v_cndmask_b32_e64 v197, v197, v201, s[4:5]
	v_add_u32_e32 v220, s48, v237
	v_cmp_lt_i32_e32 vcc, 0, v220
	s_nop 1
	v_cndmask_b32_e32 v176, 0, v176, vcc
	v_cndmask_b32_e32 v177, 0, v177, vcc
	v_cmp_gt_i32_e32 vcc, s28, v220
	s_nop 1
	v_cndmask_b32_e32 v196, 0, v196, vcc
	v_cndmask_b32_e32 v197, 0, v197, vcc
	v_pk_fma_f32 v[202:203], v[156:157], v[176:177], v[168:169]
	v_pk_fma_f32 v[4:5], v[4:5], v[160:161], v[202:203]
	v_pk_fma_f32 v[4:5], v[164:165], v[196:197], v[4:5]
	v_mul_f32_e32 v208, 0xbfb8aa3b, v26
	v_mul_f32_e32 v209, 0xbfb8aa3b, v27
	v_mul_f32_e32 v210, 0xbfb8aa3b, v28
	v_mul_f32_e32 v211, 0xbfb8aa3b, v29
	v_exp_f32_e32 v208, v208
	v_exp_f32_e32 v209, v209
	v_exp_f32_e32 v210, v210
	v_exp_f32_e32 v211, v211
	v_add_f32_e32 v208, 1.0, v208
	v_add_f32_e32 v209, 1.0, v209
	v_add_f32_e32 v210, 1.0, v210
	v_add_f32_e32 v211, 1.0, v211
	v_rcp_f32_e32 v208, v208
	v_rcp_f32_e32 v209, v209
	v_rcp_f32_e32 v210, v210
	v_rcp_f32_e32 v211, v211
	v_mul_f32_e32 v26, v26, v208
	v_mul_f32_e32 v27, v27, v209
	v_mul_f32_e32 v28, v28, v210
	v_mul_f32_e32 v29, v29, v211
	v_mul_f32_e32 v26, v30, v26
	v_mul_f32_e32 v27, v31, v27
	v_mul_f32_e32 v28, v32, v28
	v_mul_f32_e32 v29, v33, v29
	v_cvt_pk_bf16_f32 v212, v26, v27
	v_cvt_pk_bf16_f32 v213, v28, v29
	ds_bpermute_b32 v212, v250, v212
	ds_bpermute_b32 v213, v250, v213
	v_mul_f32_e32 v208, 0xbfb8aa3b, v18
	v_mul_f32_e32 v209, 0xbfb8aa3b, v19
	v_mul_f32_e32 v210, 0xbfb8aa3b, v20
	v_mul_f32_e32 v211, 0xbfb8aa3b, v21
	v_exp_f32_e32 v208, v208
	v_exp_f32_e32 v209, v209
	v_exp_f32_e32 v210, v210
	v_exp_f32_e32 v211, v211
	v_add_f32_e32 v208, 1.0, v208
	v_add_f32_e32 v209, 1.0, v209
	v_add_f32_e32 v210, 1.0, v210
	v_add_f32_e32 v211, 1.0, v211
	v_rcp_f32_e32 v208, v208
	v_rcp_f32_e32 v209, v209
	v_rcp_f32_e32 v210, v210
	v_rcp_f32_e32 v211, v211
	v_mul_f32_e32 v18, v18, v208
	v_mul_f32_e32 v19, v19, v209
	v_mul_f32_e32 v20, v20, v210
	v_mul_f32_e32 v21, v21, v211
	v_mul_f32_e32 v18, v22, v18
	v_mul_f32_e32 v19, v23, v19
	v_mul_f32_e32 v20, v24, v20
	v_mul_f32_e32 v21, v25, v21
	v_cvt_pk_bf16_f32 v218, v18, v19
	v_cvt_pk_bf16_f32 v219, v20, v21
	ds_bpermute_b32 v218, v250, v218
	ds_bpermute_b32 v219, v250, v219
	s_waitcnt lgkmcnt(2)
	v_add_u32_e32 v221, 0xb0000, v247
	s_and_saveexec_b64 s[30:31], s[20:21]
	global_store_dwordx2 v221, v[212:213], s[10:11] offset:8
	s_mov_b64 exec, s[30:31]
	v_mul_f32_e32 v208, 0xbfb8aa3b, v10
	v_mul_f32_e32 v209, 0xbfb8aa3b, v11
	v_mul_f32_e32 v210, 0xbfb8aa3b, v12
	v_mul_f32_e32 v211, 0xbfb8aa3b, v13
	v_exp_f32_e32 v208, v208
	v_exp_f32_e32 v209, v209
	v_exp_f32_e32 v210, v210
	v_exp_f32_e32 v211, v211
	v_add_f32_e32 v208, 1.0, v208
	v_add_f32_e32 v209, 1.0, v209
	v_add_f32_e32 v210, 1.0, v210
	v_add_f32_e32 v211, 1.0, v211
	v_rcp_f32_e32 v208, v208
	v_rcp_f32_e32 v209, v209
	v_rcp_f32_e32 v210, v210
	v_rcp_f32_e32 v211, v211
	v_mul_f32_e32 v10, v10, v208
	v_mul_f32_e32 v11, v11, v209
	v_mul_f32_e32 v12, v12, v210
	v_mul_f32_e32 v13, v13, v211
	v_mul_f32_e32 v10, v14, v10
	v_mul_f32_e32 v11, v15, v11
	v_mul_f32_e32 v12, v16, v12
	v_mul_f32_e32 v13, v17, v13
	v_cvt_pk_bf16_f32 v212, v10, v11
	v_cvt_pk_bf16_f32 v213, v12, v13
	ds_bpermute_b32 v212, v250, v212
	ds_bpermute_b32 v213, v250, v213
	s_waitcnt lgkmcnt(2)
	v_add_u32_e32 v251, 0xc6000, v247
	s_and_saveexec_b64 s[30:31], s[22:23]
	global_store_dwordx2 v251, v[218:219], s[10:11] offset:8
	s_mov_b64 exec, s[30:31]
	v_mul_f32_e32 v208, 0xbfb8aa3b, v2
	v_mul_f32_e32 v209, 0xbfb8aa3b, v3
	v_mul_f32_e32 v210, 0xbfb8aa3b, v4
	v_mul_f32_e32 v211, 0xbfb8aa3b, v5
	v_exp_f32_e32 v208, v208
	v_exp_f32_e32 v209, v209
	v_exp_f32_e32 v210, v210
	v_exp_f32_e32 v211, v211
	v_add_f32_e32 v208, 1.0, v208
	v_add_f32_e32 v209, 1.0, v209
	v_add_f32_e32 v210, 1.0, v210
	v_add_f32_e32 v211, 1.0, v211
	v_rcp_f32_e32 v208, v208
	v_rcp_f32_e32 v209, v209
	v_rcp_f32_e32 v210, v210
	v_rcp_f32_e32 v211, v211
	v_mul_f32_e32 v2, v2, v208
	v_mul_f32_e32 v3, v3, v209
	v_mul_f32_e32 v4, v4, v210
	v_mul_f32_e32 v5, v5, v211
	v_mul_f32_e32 v2, v6, v2
	v_mul_f32_e32 v3, v7, v3
	v_mul_f32_e32 v4, v8, v4
	v_mul_f32_e32 v5, v9, v5
	v_cvt_pk_bf16_f32 v218, v2, v3
	v_cvt_pk_bf16_f32 v219, v4, v5
	ds_bpermute_b32 v218, v250, v218
	ds_bpermute_b32 v219, v250, v219
	s_waitcnt lgkmcnt(2)
	v_add_u32_e32 v221, 0xdc000, v247
	s_and_saveexec_b64 s[30:31], s[24:25]
	global_store_dwordx2 v221, v[212:213], s[10:11] offset:8
	s_mov_b64 exec, s[30:31]
	s_waitcnt lgkmcnt(0)
	v_add_u32_e32 v251, 0xf2000, v247
	s_and_saveexec_b64 s[30:31], s[26:27]
	global_store_dwordx2 v251, v[218:219], s[10:11] offset:8
	s_mov_b64 exec, s[30:31]
